# v28 + GEMM first-trip-after-epilogue peel: first MFMA per accumulator takes C=0 (no zeroing), DMA waits re-derived (vmcnt 24 at phase 4, vmcnt 10 before phase 7) so epilogue stores need not drain befo
# speedup vs baseline: 1.0062x; 1.0009x over previous
; #define PG8_STAGE(bufoff, gbase, voff) do { _Pragma("unroll") for (int _i = 0; _i < 2; ++_i) \
;     __builtin_amdgcn_global_load_lds((const unsigned*)((const char*)(gbase) + (voff)[_i]), (LAS unsigned*)(lds + (bufoff) + ldsw + _i * 8192), 16, 0, 0); } while (0)
; #define PG8_WAIT_V(n) asm volatile("s_waitcnt vmcnt(" #n ")" ::: "memory")
; template <class Epi>
; __device__ __forceinline__ void gemm_phase(LAS unsigned char* lds, const Gemm g, const Epi& E) {
;   int tid_ = threadIdx.x; asm volatile("" : "+v"(tid_));
;   const int tid = tid_, wid = __builtin_amdgcn_readfirstlane(tid >> 6), lane = tid & 63, wr = wid >> 2, wc = wid & 3, fr = lane & 15, fq = lane >> 4;
;   const int K = g.K, nt = K / BK;
;   StaticOrder S; S.init(g.M, g.N, gridDim.x, g.rev ? (int)gridDim.x - 1 - (int)blockIdx.x : (int)blockIdx.x, g.A2 != nullptr);
;   unsigned voffA[2], voffB[2];
; #pragma unroll
;   for (int i = 0; i < 2; ++i) { int R, C; stage_rc(tid * 16 + i * 8192, R, C); const int Rb = (R & ~31) + perm32(R & 31);
;     voffA[i] = (unsigned)(R * g.lda + C) * 2u; voffB[i] = (unsigned)(Rb * g.ldb + C) * 2u; }
;   const size_t kstep = (size_t)(BK * 2);
;   const size_t hstepA = (size_t)HALF * g.lda * 2, hstepB = (size_t)HALF * g.ldb * 2;
;   const size_t tstepA = 2 * hstepA, tstepB = 2 * hstepB;
;   const unsigned ldsw = (unsigned)wid * 1024u;
;   const int aoff = lds_byte(wr * 64 + fr, fq * 8), boff = lds_byte(wc * 32 + fr, fq * 8);
;     ...
;   Unit cur, nxt; int ui = 0;
;   if (!S.next(0, cur)) return;
;   f32x4 acc[2][2][4][2];
; #pragma unroll
;   for (int a = 0; a < 2; ++a)
; #pragma unroll
;     for (int b = 0; b < 2; ++b)
; #pragma unroll
;       for (int m = 0; m < 4; ++m)
; #pragma unroll
;         for (int n = 0; n < 2; ++n) acc[a][b][m][n] = (f32x4){0.f, 0.f, 0.f, 0.f};
;   bf16x8 At[4][2], B0[2][2], B1[2][2];
;   const char* cA = (const char*)(cur.w ? g.A2 : g.A) + (size_t)cur.pm * tstepA; const char* cB = (const char*)(cur.w ? g.Bt2 : g.Bt) + (size_t)cur.pn * tstepB;
;   PG8_STAGE(PG8_SB(0, 0), cB, voffB); PG8_STAGE(PG8_SA(0, 0), cA, voffA); PG8_STAGE(PG8_SB(0, 1), cB + hstepB, voffB); PG8_STAGE(PG8_SA(0, 1), cA + hstepA, voffA);
;   if (wr == 1) PG8_BAR;
;   PG8_WAIT_V(4); PG8_BAR;
;   PG8_STAGE(PG8_SB(1, 0), cB + kstep, voffB); PG8_STAGE(PG8_SA(1, 0), cA + kstep, voffA); PG8_STAGE(PG8_SB(1, 1), cB + hstepB + kstep, voffB);
;   PG8_WAIT_V(6); PG8_BAR;
.LBB0_566:
	s_add_i32 m0, s84, 0x18000
	v_lshl_add_u64 v[0:1], v[0:1], 0, s[22:23]
	s_waitcnt vmcnt(4)
	s_barrier
	global_load_lds_dwordx4 v[0:1], off
	v_lshl_add_u64 v[0:1], v[2:3], 0, s[22:23]
	s_add_i32 m0, s84, 0x1a000
	s_add_i32 s74, s84, 0x8000
	global_load_lds_dwordx4 v[0:1], off
	v_lshl_add_u64 v[0:1], v[4:5], 0, s[22:23]
	s_mov_b32 m0, s74
	s_add_i32 s78, s84, 0xa000
	global_load_lds_dwordx4 v[0:1], off
	v_lshl_add_u64 v[0:1], v[6:7], 0, s[22:23]
	s_mov_b32 m0, s78
	s_lshl_b32 s88, s28, 3
	global_load_lds_dwordx4 v[0:1], off
	s_add_i32 m0, s84, 0x1c000
	v_lshl_add_u64 v[0:1], v[8:9], 0, s[22:23]
	global_load_lds_dwordx4 v[0:1], off
	v_lshl_add_u64 v[0:1], v[10:11], 0, s[22:23]
	s_add_i32 m0, s84, 0x1e000
	v_lshrrev_b32_e32 v20, 1, v18
	global_load_lds_dwordx4 v[0:1], off
	v_cvt_f32_u32_e32 v0, s88
	v_and_b32_e32 v20, 24, v20
	v_and_b32_e32 v19, 15, v18
	v_lshlrev_b32_e32 v21, 1, v20
	v_rcp_iflag_f32_e32 v0, v0
	v_lshlrev_b32_e32 v18, 2, v18
	s_lshl_b32 s0, s0, 5
	v_lshl_or_b32 v172, s1, 6, v19
	v_mul_f32_e32 v0, 0x4f7ffffe, v0
	v_cvt_u32_f32_e32 v0, v0
	v_lshl_or_b32 v19, v19, 6, v21
	s_lshl_b32 s1, s1, 13
	v_and_b32_e32 v18, 32, v18
	s_and_b32 s0, s0, 0x60
	v_bitop3_b32 v21, v19, s1, v18 bitop3:0xde
	s_lshl_b32 s1, s0, 7
	v_bitop3_b32 v173, v19, s1, v18 bitop3:0xde
	s_lshr_b32 s1, s34, 3
	v_writelane_b32 v255, s1, 23
	s_add_i32 s77, s1, 1
	v_readfirstlane_b32 s1, v0
	v_add_u32_e32 v0, v14, v12
	v_or_b32_e32 v174, s0, v20
	s_sub_i32 s0, 0, s88
	v_add_lshl_u32 v0, v0, v13, 1
	v_mov_b32_e32 v1, v133
	s_waitcnt vmcnt(6)
	s_mul_i32 s0, s0, s1
	v_lshl_add_u64 v[144:145], s[56:57], 0, v[0:1]
	v_add_u32_e32 v0, v17, v15
	s_lshr_b32 s72, s29, 6
	s_mul_hi_u32 s0, s1, s0
	v_add_lshl_u32 v0, v0, v16, 1
	s_ashr_i32 s73, s90, 31
	v_mov_b32_e32 v137, v133
	s_mov_b32 s35, s57
	s_and_b32 s79, s34, 7
	s_add_i32 s89, s72, -2
	s_mov_b32 s48, 0
	s_add_i32 s49, s1, s0
	v_lshl_add_u64 v[146:147], s[56:57], 0, v[0:1]
	v_add_u32_e32 v175, 0, v21
	s_barrier
	s_mov_b32 s32, 0
	s_branch .LBB0_568

; template <class Epi>
; __device__ __forceinline__ void gemm_phase(LAS unsigned char* lds, const Gemm g, const Epi& E) {
;     ...
;     if (!has_next) break;
; #pragma unroll
;     for (int a = 0; a < 2; ++a)
; #pragma unroll
;       for (int b = 0; b < 2; ++b)
; #pragma unroll
;         for (int m = 0; m < 4; ++m)
; #pragma unroll
;           for (int n = 0; n < 2; ++n) acc[a][b][m][n] = (f32x4){0.f, 0.f, 0.f, 0.f};
;     cur = nxt; cA = nA; cB = nB; ++ui;
.LBB0_578:
	s_add_u32 s2, s2, 0x80
	s_addc_u32 s3, s3, 0
	s_add_u32 s38, s26, 0x100
	s_addc_u32 s39, s27, 0
	s_mov_b32 s26, 0
	s_cmp_eq_u32 s32, 1
	s_cbranch_scc1 .Lpeel
	v_mov_b64_e32 v[0:1], 0
	v_mov_b64_e32 v[2:3], 0
	v_mov_b64_e32 v[4:5], 0
	v_mov_b64_e32 v[6:7], 0
	v_mov_b64_e32 v[8:9], 0
	v_mov_b64_e32 v[10:11], 0
	v_mov_b64_e32 v[12:13], 0
	v_mov_b64_e32 v[14:15], 0
	v_mov_b64_e32 v[16:17], 0
	v_mov_b64_e32 v[18:19], 0
	v_mov_b64_e32 v[20:21], 0
	v_mov_b64_e32 v[22:23], 0
	v_mov_b64_e32 v[24:25], 0
	v_mov_b64_e32 v[26:27], 0
	v_mov_b64_e32 v[28:29], 0
	v_mov_b64_e32 v[30:31], 0
	v_mov_b64_e32 v[32:33], 0
	v_mov_b64_e32 v[34:35], 0
	v_mov_b64_e32 v[36:37], 0
	v_mov_b64_e32 v[38:39], 0
	v_mov_b64_e32 v[40:41], 0
	v_mov_b64_e32 v[42:43], 0
	v_mov_b64_e32 v[44:45], 0
	v_mov_b64_e32 v[46:47], 0
	v_mov_b64_e32 v[48:49], 0
	v_mov_b64_e32 v[50:51], 0
	v_mov_b64_e32 v[52:53], 0
	v_mov_b64_e32 v[54:55], 0
	v_mov_b64_e32 v[56:57], 0
	v_mov_b64_e32 v[58:59], 0
	v_mov_b64_e32 v[60:61], 0
	v_mov_b64_e32 v[62:63], 0
	v_mov_b64_e32 v[64:65], 0
	v_mov_b64_e32 v[66:67], 0
	v_mov_b64_e32 v[68:69], 0
	v_mov_b64_e32 v[70:71], 0
	v_mov_b64_e32 v[72:73], 0
	v_mov_b64_e32 v[74:75], 0
	v_mov_b64_e32 v[76:77], 0
	v_mov_b64_e32 v[78:79], 0
	v_mov_b64_e32 v[80:81], 0
	v_mov_b64_e32 v[82:83], 0
	v_mov_b64_e32 v[84:85], 0
	v_mov_b64_e32 v[86:87], 0
	v_mov_b64_e32 v[88:89], 0
	v_mov_b64_e32 v[90:91], 0
	v_mov_b64_e32 v[92:93], 0
	v_mov_b64_e32 v[94:95], 0
	v_mov_b64_e32 v[96:97], 0
	v_mov_b64_e32 v[98:99], 0
	v_mov_b64_e32 v[100:101], 0
	v_mov_b64_e32 v[102:103], 0
	v_mov_b64_e32 v[104:105], 0
	v_mov_b64_e32 v[106:107], 0
	v_mov_b64_e32 v[108:109], 0
	v_mov_b64_e32 v[110:111], 0
	v_mov_b64_e32 v[112:113], 0
	v_mov_b64_e32 v[114:115], 0
	v_mov_b64_e32 v[116:117], 0
	v_mov_b64_e32 v[118:119], 0
	v_mov_b64_e32 v[120:121], 0
	v_mov_b64_e32 v[122:123], 0
	v_mov_b64_e32 v[124:125], 0
	v_mov_b64_e32 v[126:127], 0

.Lgemm_exit:
	s_lshl_b32 s28, s53, 8
	v_lshl_add_u32 v150, s75, 8, v172
	s_cmp_eq_u32 s12, 0
	v_ashrrev_i32_e32 v151, 31, v150
	v_mad_i64_i32 v[164:165], s[2:3], v150, s54, 0
	v_mad_i64_i32 v[154:155], s[2:3], v150, s33, 0
	s_cselect_b32 s29, s40, s41
	v_lshlrev_b64 v[162:163], 10, v[150:151]
	v_cmp_gt_i32_e64 s[38:39], s92, v150
	v_lshlrev_b64 v[152:153], 12, v[150:151]
	v_or_b32_e32 v148, s28, v174
	s_cmp_eq_u32 s29, 6
	s_cbranch_scc1 .Lepi6
	s_cmp_eq_u32 s29, 0
	s_cbranch_scc1 .Lepi0
	s_cmp_eq_u32 s29, 3
	s_cbranch_scc1 .Lepi3
	s_cmp_eq_u32 s29, 4
	s_cbranch_scc1 .Lepi4
	s_cmp_eq_u32 s29, 1
	s_cbranch_scc1 .Lepi1
	s_cmp_eq_u32 s29, 2
	s_cbranch_scc1 .Lepi2
	s_cmp_eq_u32 s29, 5
	s_cbranch_scc1 .Lepi5
	s_branch .Lepi7
.Lepi6:
	v_mul_u32_u24_e32 v176, 0x1600, v150
	v_ashrrev_i32_e32 v177, 1, v148
	v_lshl_add_u32 v176, v177, 1, v176
	v_add_u32_e32 v177, 0x16000, v176
	v_add_u32_e32 v178, 0x2c000, v176
	v_add_u32_e32 v179, 0x42000, v176
	v_add_u32_e32 v180, 0xb0000, v176
	v_add_u32_e32 v181, 0xc6000, v176
	v_add_u32_e32 v182, 0xdc000, v176
	v_add_u32_e32 v183, 0xf2000, v176
	v_mul_f32_e32 v152, 0xbfb8aa3b, v124
	v_mul_f32_e32 v153, 0xbfb8aa3b, v125
	v_mul_f32_e32 v154, 0xbfb8aa3b, v126
	v_mul_f32_e32 v155, 0xbfb8aa3b, v127
	v_exp_f32_e32 v152, v152
	v_exp_f32_e32 v153, v153
	v_exp_f32_e32 v154, v154
	v_exp_f32_e32 v155, v155
	v_pk_add_f32 v[152:153], v[152:153], 1.0 op_sel_hi:[1,0]
	v_pk_add_f32 v[154:155], v[154:155], 1.0 op_sel_hi:[1,0]
	v_div_scale_f32 v156, s[38:39], v152, v152, 1.0
	v_div_scale_f32 v157, s[38:39], v153, v153, 1.0
	v_div_scale_f32 v158, s[38:39], v154, v154, 1.0
	v_div_scale_f32 v159, s[38:39], v155, v155, 1.0
	v_rcp_f32_e32 v160, v156
	v_rcp_f32_e32 v161, v157
	v_rcp_f32_e32 v162, v158
	v_rcp_f32_e32 v163, v159
	v_pk_fma_f32 v[164:165], v[156:157], v[160:161], 1.0 op_sel_hi:[1,1,0] neg_lo:[1,0,0] neg_hi:[1,0,0]
	v_pk_fma_f32 v[166:167], v[158:159], v[162:163], 1.0 op_sel_hi:[1,1,0] neg_lo:[1,0,0] neg_hi:[1,0,0]
	v_pk_fma_f32 v[160:161], v[164:165], v[160:161], v[160:161]
	v_pk_fma_f32 v[162:163], v[166:167], v[162:163], v[162:163]
	v_div_scale_f32 v168, s[2:3], 1.0, v152, 1.0
	v_div_scale_f32 v169, s[26:27], 1.0, v153, 1.0
	v_div_scale_f32 v170, s[28:29], 1.0, v154, 1.0
	v_div_scale_f32 v171, vcc, 1.0, v155, 1.0
	v_pk_mul_f32 v[128:129], v[168:169], v[160:161]
	v_pk_mul_f32 v[130:131], v[170:171], v[162:163]
	v_pk_fma_f32 v[164:165], v[156:157], v[128:129], v[168:169] neg_lo:[1,0,0] neg_hi:[1,0,0]
	v_pk_fma_f32 v[166:167], v[158:159], v[130:131], v[170:171] neg_lo:[1,0,0] neg_hi:[1,0,0]
	v_pk_fma_f32 v[128:129], v[164:165], v[160:161], v[128:129]
	v_pk_fma_f32 v[130:131], v[166:167], v[162:163], v[130:131]
	v_pk_fma_f32 v[156:157], v[156:157], v[128:129], v[168:169] neg_lo:[1,0,0] neg_hi:[1,0,0]
	v_pk_fma_f32 v[158:159], v[158:159], v[130:131], v[170:171] neg_lo:[1,0,0] neg_hi:[1,0,0]
	v_div_fmas_f32 v159, v159, v163, v131
	s_mov_b64 vcc, s[28:29]
	v_div_fmas_f32 v158, v158, v162, v130
	s_mov_b64 vcc, s[26:27]
	v_div_fmas_f32 v157, v157, v161, v129
	s_mov_b64 vcc, s[2:3]
	v_div_fmas_f32 v156, v156, v160, v128
	v_div_fixup_f32 v152, v156, v152, 1.0
	v_div_fixup_f32 v153, v157, v153, 1.0
	v_div_fixup_f32 v154, v158, v154, 1.0
	v_div_fixup_f32 v155, v159, v155, 1.0
	v_pk_mul_f32 v[152:153], v[124:125], v[152:153]
	v_pk_mul_f32 v[154:155], v[126:127], v[154:155]
	v_pk_mul_f32 v[152:153], v[120:121], v[152:153]
	v_pk_mul_f32 v[154:155], v[122:123], v[154:155]
	v_cvt_pk_bf16_f32 v184, v152, v153
	v_cvt_pk_bf16_f32 v185, v154, v155
	global_store_dwordx2 v176, v[184:185], s[64:65]
	v_mul_f32_e32 v152, 0xbfb8aa3b, v116
	v_mul_f32_e32 v153, 0xbfb8aa3b, v117
	v_mul_f32_e32 v154, 0xbfb8aa3b, v118
	v_mul_f32_e32 v155, 0xbfb8aa3b, v119
	v_exp_f32_e32 v152, v152
	v_exp_f32_e32 v153, v153
	v_exp_f32_e32 v154, v154
	v_exp_f32_e32 v155, v155
	v_pk_add_f32 v[152:153], v[152:153], 1.0 op_sel_hi:[1,0]
	v_pk_add_f32 v[154:155], v[154:155], 1.0 op_sel_hi:[1,0]
	v_div_scale_f32 v156, s[38:39], v152, v152, 1.0
	v_div_scale_f32 v157, s[38:39], v153, v153, 1.0
	v_div_scale_f32 v158, s[38:39], v154, v154, 1.0
	v_div_scale_f32 v159, s[38:39], v155, v155, 1.0
	v_rcp_f32_e32 v160, v156
	v_rcp_f32_e32 v161, v157
	v_rcp_f32_e32 v162, v158
	v_rcp_f32_e32 v163, v159
	v_pk_fma_f32 v[164:165], v[156:157], v[160:161], 1.0 op_sel_hi:[1,1,0] neg_lo:[1,0,0] neg_hi:[1,0,0]
	v_pk_fma_f32 v[166:167], v[158:159], v[162:163], 1.0 op_sel_hi:[1,1,0] neg_lo:[1,0,0] neg_hi:[1,0,0]
	v_pk_fma_f32 v[160:161], v[164:165], v[160:161], v[160:161]
	v_pk_fma_f32 v[162:163], v[166:167], v[162:163], v[162:163]
	v_div_scale_f32 v168, s[2:3], 1.0, v152, 1.0
	v_div_scale_f32 v169, s[26:27], 1.0, v153, 1.0
	v_div_scale_f32 v170, s[28:29], 1.0, v154, 1.0
	v_div_scale_f32 v171, vcc, 1.0, v155, 1.0
	v_pk_mul_f32 v[128:129], v[168:169], v[160:161]
	v_pk_mul_f32 v[130:131], v[170:171], v[162:163]
	v_pk_fma_f32 v[164:165], v[156:157], v[128:129], v[168:169] neg_lo:[1,0,0] neg_hi:[1,0,0]
	v_pk_fma_f32 v[166:167], v[158:159], v[130:131], v[170:171] neg_lo:[1,0,0] neg_hi:[1,0,0]
	v_pk_fma_f32 v[128:129], v[164:165], v[160:161], v[128:129]
	v_pk_fma_f32 v[130:131], v[166:167], v[162:163], v[130:131]
	v_pk_fma_f32 v[156:157], v[156:157], v[128:129], v[168:169] neg_lo:[1,0,0] neg_hi:[1,0,0]
	v_pk_fma_f32 v[158:159], v[158:159], v[130:131], v[170:171] neg_lo:[1,0,0] neg_hi:[1,0,0]
	v_div_fmas_f32 v159, v159, v163, v131
	s_mov_b64 vcc, s[28:29]
	v_div_fmas_f32 v158, v158, v162, v130
	s_mov_b64 vcc, s[26:27]
	v_div_fmas_f32 v157, v157, v161, v129
	s_mov_b64 vcc, s[2:3]
	v_div_fmas_f32 v156, v156, v160, v128
	v_div_fixup_f32 v152, v156, v152, 1.0
	v_div_fixup_f32 v153, v157, v153, 1.0
; __device__ __forceinline__ float sigmoidf_(float x) { return 1.f / (1.f + __expf(-x)); }
	v_div_fixup_f32 v154, v158, v154, 1.0
	v_div_fixup_f32 v155, v159, v155, 1.0
	v_pk_mul_f32 v[152:153], v[116:117], v[152:153]
	v_pk_mul_f32 v[154:155], v[118:119], v[154:155]
	v_pk_mul_f32 v[152:153], v[112:113], v[152:153]
	v_pk_mul_f32 v[154:155], v[114:115], v[154:155]
	v_cvt_pk_bf16_f32 v186, v152, v153
	v_cvt_pk_bf16_f32 v187, v154, v155
	global_store_dwordx2 v176, v[186:187], s[64:65] offset:128
	v_mul_f32_e32 v152, 0xbfb8aa3b, v108
	v_mul_f32_e32 v153, 0xbfb8aa3b, v109
	v_mul_f32_e32 v154, 0xbfb8aa3b, v110
	v_mul_f32_e32 v155, 0xbfb8aa3b, v111
	v_exp_f32_e32 v152, v152
	v_exp_f32_e32 v153, v153
	v_exp_f32_e32 v154, v154
	v_exp_f32_e32 v155, v155
	v_pk_add_f32 v[152:153], v[152:153], 1.0 op_sel_hi:[1,0]
	v_pk_add_f32 v[154:155], v[154:155], 1.0 op_sel_hi:[1,0]
	v_div_scale_f32 v156, s[38:39], v152, v152, 1.0
	v_div_scale_f32 v157, s[38:39], v153, v153, 1.0
	v_div_scale_f32 v158, s[38:39], v154, v154, 1.0
	v_div_scale_f32 v159, s[38:39], v155, v155, 1.0
	v_rcp_f32_e32 v160, v156
	v_rcp_f32_e32 v161, v157
	v_rcp_f32_e32 v162, v158
	v_rcp_f32_e32 v163, v159
	v_pk_fma_f32 v[164:165], v[156:157], v[160:161], 1.0 op_sel_hi:[1,1,0] neg_lo:[1,0,0] neg_hi:[1,0,0]
	v_pk_fma_f32 v[166:167], v[158:159], v[162:163], 1.0 op_sel_hi:[1,1,0] neg_lo:[1,0,0] neg_hi:[1,0,0]
	v_pk_fma_f32 v[160:161], v[164:165], v[160:161], v[160:161]
	v_pk_fma_f32 v[162:163], v[166:167], v[162:163], v[162:163]
	v_div_scale_f32 v168, s[2:3], 1.0, v152, 1.0
	v_div_scale_f32 v169, s[26:27], 1.0, v153, 1.0
	v_div_scale_f32 v170, s[28:29], 1.0, v154, 1.0
	v_div_scale_f32 v171, vcc, 1.0, v155, 1.0
	v_pk_mul_f32 v[128:129], v[168:169], v[160:161]
	v_pk_mul_f32 v[130:131], v[170:171], v[162:163]
	v_pk_fma_f32 v[164:165], v[156:157], v[128:129], v[168:169] neg_lo:[1,0,0] neg_hi:[1,0,0]
	v_pk_fma_f32 v[166:167], v[158:159], v[130:131], v[170:171] neg_lo:[1,0,0] neg_hi:[1,0,0]
	v_pk_fma_f32 v[128:129], v[164:165], v[160:161], v[128:129]
	v_pk_fma_f32 v[130:131], v[166:167], v[162:163], v[130:131]
	v_pk_fma_f32 v[156:157], v[156:157], v[128:129], v[168:169] neg_lo:[1,0,0] neg_hi:[1,0,0]
	v_pk_fma_f32 v[158:159], v[158:159], v[130:131], v[170:171] neg_lo:[1,0,0] neg_hi:[1,0,0]
	v_div_fmas_f32 v159, v159, v163, v131
	s_mov_b64 vcc, s[28:29]
	v_div_fmas_f32 v158, v158, v162, v130
	s_mov_b64 vcc, s[26:27]
	v_div_fmas_f32 v157, v157, v161, v129
	s_mov_b64 vcc, s[2:3]
	v_div_fmas_f32 v156, v156, v160, v128
	v_div_fixup_f32 v152, v156, v152, 1.0
	v_div_fixup_f32 v153, v157, v153, 1.0
	v_div_fixup_f32 v154, v158, v154, 1.0
	v_div_fixup_f32 v155, v159, v155, 1.0
	v_pk_mul_f32 v[152:153], v[108:109], v[152:153]
	v_pk_mul_f32 v[154:155], v[110:111], v[154:155]
	v_pk_mul_f32 v[152:153], v[104:105], v[152:153]
	v_pk_mul_f32 v[154:155], v[106:107], v[154:155]
	v_cvt_pk_bf16_f32 v184, v152, v153
	v_cvt_pk_bf16_f32 v185, v154, v155
	global_store_dwordx2 v177, v[184:185], s[64:65]
	v_mul_f32_e32 v152, 0xbfb8aa3b, v100
	v_mul_f32_e32 v153, 0xbfb8aa3b, v101
	v_mul_f32_e32 v154, 0xbfb8aa3b, v102
	v_mul_f32_e32 v155, 0xbfb8aa3b, v103
	v_exp_f32_e32 v152, v152
	v_exp_f32_e32 v153, v153
	v_exp_f32_e32 v154, v154
	v_exp_f32_e32 v155, v155
	v_pk_add_f32 v[152:153], v[152:153], 1.0 op_sel_hi:[1,0]
	v_pk_add_f32 v[154:155], v[154:155], 1.0 op_sel_hi:[1,0]
	v_div_scale_f32 v156, s[38:39], v152, v152, 1.0
	v_div_scale_f32 v157, s[38:39], v153, v153, 1.0
	v_div_scale_f32 v158, s[38:39], v154, v154, 1.0
	v_div_scale_f32 v159, s[38:39], v155, v155, 1.0
	v_rcp_f32_e32 v160, v156
	v_rcp_f32_e32 v161, v157
	v_rcp_f32_e32 v162, v158
	v_rcp_f32_e32 v163, v159
	v_pk_fma_f32 v[164:165], v[156:157], v[160:161], 1.0 op_sel_hi:[1,1,0] neg_lo:[1,0,0] neg_hi:[1,0,0]
	v_pk_fma_f32 v[166:167], v[158:159], v[162:163], 1.0 op_sel_hi:[1,1,0] neg_lo:[1,0,0] neg_hi:[1,0,0]
	v_pk_fma_f32 v[160:161], v[164:165], v[160:161], v[160:161]
	v_pk_fma_f32 v[162:163], v[166:167], v[162:163], v[162:163]
	v_div_scale_f32 v168, s[2:3], 1.0, v152, 1.0
	v_div_scale_f32 v169, s[26:27], 1.0, v153, 1.0
	v_div_scale_f32 v170, s[28:29], 1.0, v154, 1.0
	v_div_scale_f32 v171, vcc, 1.0, v155, 1.0
	v_pk_mul_f32 v[128:129], v[168:169], v[160:161]
	v_pk_mul_f32 v[130:131], v[170:171], v[162:163]
	v_pk_fma_f32 v[164:165], v[156:157], v[128:129], v[168:169] neg_lo:[1,0,0] neg_hi:[1,0,0]
	v_pk_fma_f32 v[166:167], v[158:159], v[130:131], v[170:171] neg_lo:[1,0,0] neg_hi:[1,0,0]
	v_pk_fma_f32 v[128:129], v[164:165], v[160:161], v[128:129]
	v_pk_fma_f32 v[130:131], v[166:167], v[162:163], v[130:131]
	v_pk_fma_f32 v[156:157], v[156:157], v[128:129], v[168:169] neg_lo:[1,0,0] neg_hi:[1,0,0]
	v_pk_fma_f32 v[158:159], v[158:159], v[130:131], v[170:171] neg_lo:[1,0,0] neg_hi:[1,0,0]
	v_div_fmas_f32 v159, v159, v163, v131
	s_mov_b64 vcc, s[28:29]
	v_div_fmas_f32 v158, v158, v162, v130
	s_mov_b64 vcc, s[26:27]
	v_div_fmas_f32 v157, v157, v161, v129
	s_mov_b64 vcc, s[2:3]
	v_div_fmas_f32 v156, v156, v160, v128
	v_div_fixup_f32 v152, v156, v152, 1.0
	v_div_fixup_f32 v153, v157, v153, 1.0
	v_div_fixup_f32 v154, v158, v154, 1.0
	v_div_fixup_f32 v155, v159, v155, 1.0
	v_pk_mul_f32 v[152:153], v[100:101], v[152:153]
	v_pk_mul_f32 v[154:155], v[102:103], v[154:155]
	v_pk_mul_f32 v[152:153], v[96:97], v[152:153]
	v_pk_mul_f32 v[154:155], v[98:99], v[154:155]
	v_cvt_pk_bf16_f32 v186, v152, v153
	v_cvt_pk_bf16_f32 v187, v154, v155
	global_store_dwordx2 v177, v[186:187], s[64:65] offset:128
	v_mul_f32_e32 v152, 0xbfb8aa3b, v92
	v_mul_f32_e32 v153, 0xbfb8aa3b, v93
	v_mul_f32_e32 v154, 0xbfb8aa3b, v94
	v_mul_f32_e32 v155, 0xbfb8aa3b, v95
	v_exp_f32_e32 v152, v152
	v_exp_f32_e32 v153, v153
	v_exp_f32_e32 v154, v154
	v_exp_f32_e32 v155, v155
	v_pk_add_f32 v[152:153], v[152:153], 1.0 op_sel_hi:[1,0]
; __device__ __forceinline__ float sigmoidf_(float x) { return 1.f / (1.f + __expf(-x)); }
	v_pk_add_f32 v[154:155], v[154:155], 1.0 op_sel_hi:[1,0]
	v_div_scale_f32 v156, s[38:39], v152, v152, 1.0
	v_div_scale_f32 v157, s[38:39], v153, v153, 1.0
	v_div_scale_f32 v158, s[38:39], v154, v154, 1.0
	v_div_scale_f32 v159, s[38:39], v155, v155, 1.0
	v_rcp_f32_e32 v160, v156
	v_rcp_f32_e32 v161, v157
	v_rcp_f32_e32 v162, v158
	v_rcp_f32_e32 v163, v159
	v_pk_fma_f32 v[164:165], v[156:157], v[160:161], 1.0 op_sel_hi:[1,1,0] neg_lo:[1,0,0] neg_hi:[1,0,0]
	v_pk_fma_f32 v[166:167], v[158:159], v[162:163], 1.0 op_sel_hi:[1,1,0] neg_lo:[1,0,0] neg_hi:[1,0,0]
	v_pk_fma_f32 v[160:161], v[164:165], v[160:161], v[160:161]
	v_pk_fma_f32 v[162:163], v[166:167], v[162:163], v[162:163]
	v_div_scale_f32 v168, s[2:3], 1.0, v152, 1.0
	v_div_scale_f32 v169, s[26:27], 1.0, v153, 1.0
	v_div_scale_f32 v170, s[28:29], 1.0, v154, 1.0
	v_div_scale_f32 v171, vcc, 1.0, v155, 1.0
	v_pk_mul_f32 v[128:129], v[168:169], v[160:161]
	v_pk_mul_f32 v[130:131], v[170:171], v[162:163]
	v_pk_fma_f32 v[164:165], v[156:157], v[128:129], v[168:169] neg_lo:[1,0,0] neg_hi:[1,0,0]
	v_pk_fma_f32 v[166:167], v[158:159], v[130:131], v[170:171] neg_lo:[1,0,0] neg_hi:[1,0,0]
	v_pk_fma_f32 v[128:129], v[164:165], v[160:161], v[128:129]
	v_pk_fma_f32 v[130:131], v[166:167], v[162:163], v[130:131]
	v_pk_fma_f32 v[156:157], v[156:157], v[128:129], v[168:169] neg_lo:[1,0,0] neg_hi:[1,0,0]
	v_pk_fma_f32 v[158:159], v[158:159], v[130:131], v[170:171] neg_lo:[1,0,0] neg_hi:[1,0,0]
	v_div_fmas_f32 v159, v159, v163, v131
	s_mov_b64 vcc, s[28:29]
	v_div_fmas_f32 v158, v158, v162, v130
	s_mov_b64 vcc, s[26:27]
	v_div_fmas_f32 v157, v157, v161, v129
	s_mov_b64 vcc, s[2:3]
	v_div_fmas_f32 v156, v156, v160, v128
	v_div_fixup_f32 v152, v156, v152, 1.0
	v_div_fixup_f32 v153, v157, v153, 1.0
	v_div_fixup_f32 v154, v158, v154, 1.0
	v_div_fixup_f32 v155, v159, v155, 1.0
	v_pk_mul_f32 v[152:153], v[92:93], v[152:153]
	v_pk_mul_f32 v[154:155], v[94:95], v[154:155]
	v_pk_mul_f32 v[152:153], v[88:89], v[152:153]
	v_pk_mul_f32 v[154:155], v[90:91], v[154:155]
	v_cvt_pk_bf16_f32 v184, v152, v153
	v_cvt_pk_bf16_f32 v185, v154, v155
	global_store_dwordx2 v178, v[184:185], s[64:65]
	v_mul_f32_e32 v152, 0xbfb8aa3b, v84
	v_mul_f32_e32 v153, 0xbfb8aa3b, v85
	v_mul_f32_e32 v154, 0xbfb8aa3b, v86
	v_mul_f32_e32 v155, 0xbfb8aa3b, v87
	v_exp_f32_e32 v152, v152
	v_exp_f32_e32 v153, v153
	v_exp_f32_e32 v154, v154
	v_exp_f32_e32 v155, v155
	v_pk_add_f32 v[152:153], v[152:153], 1.0 op_sel_hi:[1,0]
	v_pk_add_f32 v[154:155], v[154:155], 1.0 op_sel_hi:[1,0]
	v_div_scale_f32 v156, s[38:39], v152, v152, 1.0
	v_div_scale_f32 v157, s[38:39], v153, v153, 1.0
	v_div_scale_f32 v158, s[38:39], v154, v154, 1.0
	v_div_scale_f32 v159, s[38:39], v155, v155, 1.0
	v_rcp_f32_e32 v160, v156
	v_rcp_f32_e32 v161, v157
	v_rcp_f32_e32 v162, v158
	v_rcp_f32_e32 v163, v159
	v_pk_fma_f32 v[164:165], v[156:157], v[160:161], 1.0 op_sel_hi:[1,1,0] neg_lo:[1,0,0] neg_hi:[1,0,0]
	v_pk_fma_f32 v[166:167], v[158:159], v[162:163], 1.0 op_sel_hi:[1,1,0] neg_lo:[1,0,0] neg_hi:[1,0,0]
	v_pk_fma_f32 v[160:161], v[164:165], v[160:161], v[160:161]
	v_pk_fma_f32 v[162:163], v[166:167], v[162:163], v[162:163]
	v_div_scale_f32 v168, s[2:3], 1.0, v152, 1.0
	v_div_scale_f32 v169, s[26:27], 1.0, v153, 1.0
	v_div_scale_f32 v170, s[28:29], 1.0, v154, 1.0
	v_div_scale_f32 v171, vcc, 1.0, v155, 1.0
	v_pk_mul_f32 v[128:129], v[168:169], v[160:161]
	v_pk_mul_f32 v[130:131], v[170:171], v[162:163]
	v_pk_fma_f32 v[164:165], v[156:157], v[128:129], v[168:169] neg_lo:[1,0,0] neg_hi:[1,0,0]
	v_pk_fma_f32 v[166:167], v[158:159], v[130:131], v[170:171] neg_lo:[1,0,0] neg_hi:[1,0,0]
	v_pk_fma_f32 v[128:129], v[164:165], v[160:161], v[128:129]
	v_pk_fma_f32 v[130:131], v[166:167], v[162:163], v[130:131]
	v_pk_fma_f32 v[156:157], v[156:157], v[128:129], v[168:169] neg_lo:[1,0,0] neg_hi:[1,0,0]
	v_pk_fma_f32 v[158:159], v[158:159], v[130:131], v[170:171] neg_lo:[1,0,0] neg_hi:[1,0,0]
	v_div_fmas_f32 v159, v159, v163, v131
	s_mov_b64 vcc, s[28:29]
	v_div_fmas_f32 v158, v158, v162, v130
	s_mov_b64 vcc, s[26:27]
	v_div_fmas_f32 v157, v157, v161, v129
	s_mov_b64 vcc, s[2:3]
	v_div_fmas_f32 v156, v156, v160, v128
	v_div_fixup_f32 v152, v156, v152, 1.0
	v_div_fixup_f32 v153, v157, v153, 1.0
	v_div_fixup_f32 v154, v158, v154, 1.0
	v_div_fixup_f32 v155, v159, v155, 1.0
	v_pk_mul_f32 v[152:153], v[84:85], v[152:153]
	v_pk_mul_f32 v[154:155], v[86:87], v[154:155]
	v_pk_mul_f32 v[152:153], v[80:81], v[152:153]
	v_pk_mul_f32 v[154:155], v[82:83], v[154:155]
	v_cvt_pk_bf16_f32 v186, v152, v153
	v_cvt_pk_bf16_f32 v187, v154, v155
	global_store_dwordx2 v178, v[186:187], s[64:65] offset:128
	v_mul_f32_e32 v152, 0xbfb8aa3b, v76
	v_mul_f32_e32 v153, 0xbfb8aa3b, v77
	v_mul_f32_e32 v154, 0xbfb8aa3b, v78
	v_mul_f32_e32 v155, 0xbfb8aa3b, v79
	v_exp_f32_e32 v152, v152
	v_exp_f32_e32 v153, v153
	v_exp_f32_e32 v154, v154
	v_exp_f32_e32 v155, v155
	v_pk_add_f32 v[152:153], v[152:153], 1.0 op_sel_hi:[1,0]
	v_pk_add_f32 v[154:155], v[154:155], 1.0 op_sel_hi:[1,0]
	v_div_scale_f32 v156, s[38:39], v152, v152, 1.0
	v_div_scale_f32 v157, s[38:39], v153, v153, 1.0
	v_div_scale_f32 v158, s[38:39], v154, v154, 1.0
	v_div_scale_f32 v159, s[38:39], v155, v155, 1.0
	v_rcp_f32_e32 v160, v156
	v_rcp_f32_e32 v161, v157
	v_rcp_f32_e32 v162, v158
	v_rcp_f32_e32 v163, v159
	v_pk_fma_f32 v[164:165], v[156:157], v[160:161], 1.0 op_sel_hi:[1,1,0] neg_lo:[1,0,0] neg_hi:[1,0,0]
	v_pk_fma_f32 v[166:167], v[158:159], v[162:163], 1.0 op_sel_hi:[1,1,0] neg_lo:[1,0,0] neg_hi:[1,0,0]
	v_pk_fma_f32 v[160:161], v[164:165], v[160:161], v[160:161]
	v_pk_fma_f32 v[162:163], v[166:167], v[162:163], v[162:163]
	v_div_scale_f32 v168, s[2:3], 1.0, v152, 1.0
; __device__ __forceinline__ float sigmoidf_(float x) { return 1.f / (1.f + __expf(-x)); }
	v_div_scale_f32 v169, s[26:27], 1.0, v153, 1.0
	v_div_scale_f32 v170, s[28:29], 1.0, v154, 1.0
	v_div_scale_f32 v171, vcc, 1.0, v155, 1.0
	v_pk_mul_f32 v[128:129], v[168:169], v[160:161]
	v_pk_mul_f32 v[130:131], v[170:171], v[162:163]
	v_pk_fma_f32 v[164:165], v[156:157], v[128:129], v[168:169] neg_lo:[1,0,0] neg_hi:[1,0,0]
	v_pk_fma_f32 v[166:167], v[158:159], v[130:131], v[170:171] neg_lo:[1,0,0] neg_hi:[1,0,0]
	v_pk_fma_f32 v[128:129], v[164:165], v[160:161], v[128:129]
	v_pk_fma_f32 v[130:131], v[166:167], v[162:163], v[130:131]
	v_pk_fma_f32 v[156:157], v[156:157], v[128:129], v[168:169] neg_lo:[1,0,0] neg_hi:[1,0,0]
	v_pk_fma_f32 v[158:159], v[158:159], v[130:131], v[170:171] neg_lo:[1,0,0] neg_hi:[1,0,0]
	v_div_fmas_f32 v159, v159, v163, v131
	s_mov_b64 vcc, s[28:29]
	v_div_fmas_f32 v158, v158, v162, v130
	s_mov_b64 vcc, s[26:27]
	v_div_fmas_f32 v157, v157, v161, v129
	s_mov_b64 vcc, s[2:3]
	v_div_fmas_f32 v156, v156, v160, v128
	v_div_fixup_f32 v152, v156, v152, 1.0
	v_div_fixup_f32 v153, v157, v153, 1.0
	v_div_fixup_f32 v154, v158, v154, 1.0
	v_div_fixup_f32 v155, v159, v155, 1.0
	v_pk_mul_f32 v[152:153], v[76:77], v[152:153]
	v_pk_mul_f32 v[154:155], v[78:79], v[154:155]
	v_pk_mul_f32 v[152:153], v[72:73], v[152:153]
	v_pk_mul_f32 v[154:155], v[74:75], v[154:155]
	v_cvt_pk_bf16_f32 v184, v152, v153
	v_cvt_pk_bf16_f32 v185, v154, v155
	global_store_dwordx2 v179, v[184:185], s[64:65]
	v_mul_f32_e32 v152, 0xbfb8aa3b, v68
	v_mul_f32_e32 v153, 0xbfb8aa3b, v69
	v_mul_f32_e32 v154, 0xbfb8aa3b, v70
	v_mul_f32_e32 v155, 0xbfb8aa3b, v71
	v_exp_f32_e32 v152, v152
	v_exp_f32_e32 v153, v153
	v_exp_f32_e32 v154, v154
	v_exp_f32_e32 v155, v155
	v_pk_add_f32 v[152:153], v[152:153], 1.0 op_sel_hi:[1,0]
	v_pk_add_f32 v[154:155], v[154:155], 1.0 op_sel_hi:[1,0]
	v_div_scale_f32 v156, s[38:39], v152, v152, 1.0
	v_div_scale_f32 v157, s[38:39], v153, v153, 1.0
	v_div_scale_f32 v158, s[38:39], v154, v154, 1.0
	v_div_scale_f32 v159, s[38:39], v155, v155, 1.0
	v_rcp_f32_e32 v160, v156
	v_rcp_f32_e32 v161, v157
	v_rcp_f32_e32 v162, v158
	v_rcp_f32_e32 v163, v159
	v_pk_fma_f32 v[164:165], v[156:157], v[160:161], 1.0 op_sel_hi:[1,1,0] neg_lo:[1,0,0] neg_hi:[1,0,0]
	v_pk_fma_f32 v[166:167], v[158:159], v[162:163], 1.0 op_sel_hi:[1,1,0] neg_lo:[1,0,0] neg_hi:[1,0,0]
	v_pk_fma_f32 v[160:161], v[164:165], v[160:161], v[160:161]
	v_pk_fma_f32 v[162:163], v[166:167], v[162:163], v[162:163]
	v_div_scale_f32 v168, s[2:3], 1.0, v152, 1.0
	v_div_scale_f32 v169, s[26:27], 1.0, v153, 1.0
	v_div_scale_f32 v170, s[28:29], 1.0, v154, 1.0
	v_div_scale_f32 v171, vcc, 1.0, v155, 1.0
	v_pk_mul_f32 v[128:129], v[168:169], v[160:161]
	v_pk_mul_f32 v[130:131], v[170:171], v[162:163]
	v_pk_fma_f32 v[164:165], v[156:157], v[128:129], v[168:169] neg_lo:[1,0,0] neg_hi:[1,0,0]
	v_pk_fma_f32 v[166:167], v[158:159], v[130:131], v[170:171] neg_lo:[1,0,0] neg_hi:[1,0,0]
	v_pk_fma_f32 v[128:129], v[164:165], v[160:161], v[128:129]
	v_pk_fma_f32 v[130:131], v[166:167], v[162:163], v[130:131]
	v_pk_fma_f32 v[156:157], v[156:157], v[128:129], v[168:169] neg_lo:[1,0,0] neg_hi:[1,0,0]
	v_pk_fma_f32 v[158:159], v[158:159], v[130:131], v[170:171] neg_lo:[1,0,0] neg_hi:[1,0,0]
	v_div_fmas_f32 v159, v159, v163, v131
	s_mov_b64 vcc, s[28:29]
	v_div_fmas_f32 v158, v158, v162, v130
	s_mov_b64 vcc, s[26:27]
	v_div_fmas_f32 v157, v157, v161, v129
	s_mov_b64 vcc, s[2:3]
	v_div_fmas_f32 v156, v156, v160, v128
	v_div_fixup_f32 v152, v156, v152, 1.0
	v_div_fixup_f32 v153, v157, v153, 1.0
	v_div_fixup_f32 v154, v158, v154, 1.0
	v_div_fixup_f32 v155, v159, v155, 1.0
	v_pk_mul_f32 v[152:153], v[68:69], v[152:153]
	v_pk_mul_f32 v[154:155], v[70:71], v[154:155]
	v_pk_mul_f32 v[152:153], v[64:65], v[152:153]
	v_pk_mul_f32 v[154:155], v[66:67], v[154:155]
	v_cvt_pk_bf16_f32 v186, v152, v153
	v_cvt_pk_bf16_f32 v187, v154, v155
	global_store_dwordx2 v179, v[186:187], s[64:65] offset:128
	v_mul_f32_e32 v152, 0xbfb8aa3b, v60
	v_mul_f32_e32 v153, 0xbfb8aa3b, v61
	v_mul_f32_e32 v154, 0xbfb8aa3b, v62
	v_mul_f32_e32 v155, 0xbfb8aa3b, v63
	v_exp_f32_e32 v152, v152
	v_exp_f32_e32 v153, v153
	v_exp_f32_e32 v154, v154
	v_exp_f32_e32 v155, v155
	v_pk_add_f32 v[152:153], v[152:153], 1.0 op_sel_hi:[1,0]
	v_pk_add_f32 v[154:155], v[154:155], 1.0 op_sel_hi:[1,0]
	v_div_scale_f32 v156, s[38:39], v152, v152, 1.0
	v_div_scale_f32 v157, s[38:39], v153, v153, 1.0
	v_div_scale_f32 v158, s[38:39], v154, v154, 1.0
	v_div_scale_f32 v159, s[38:39], v155, v155, 1.0
	v_rcp_f32_e32 v160, v156
	v_rcp_f32_e32 v161, v157
	v_rcp_f32_e32 v162, v158
	v_rcp_f32_e32 v163, v159
	v_pk_fma_f32 v[164:165], v[156:157], v[160:161], 1.0 op_sel_hi:[1,1,0] neg_lo:[1,0,0] neg_hi:[1,0,0]
	v_pk_fma_f32 v[166:167], v[158:159], v[162:163], 1.0 op_sel_hi:[1,1,0] neg_lo:[1,0,0] neg_hi:[1,0,0]
	v_pk_fma_f32 v[160:161], v[164:165], v[160:161], v[160:161]
	v_pk_fma_f32 v[162:163], v[166:167], v[162:163], v[162:163]
	v_div_scale_f32 v168, s[2:3], 1.0, v152, 1.0
	v_div_scale_f32 v169, s[26:27], 1.0, v153, 1.0
	v_div_scale_f32 v170, s[28:29], 1.0, v154, 1.0
	v_div_scale_f32 v171, vcc, 1.0, v155, 1.0
	v_pk_mul_f32 v[128:129], v[168:169], v[160:161]
	v_pk_mul_f32 v[130:131], v[170:171], v[162:163]
	v_pk_fma_f32 v[164:165], v[156:157], v[128:129], v[168:169] neg_lo:[1,0,0] neg_hi:[1,0,0]
	v_pk_fma_f32 v[166:167], v[158:159], v[130:131], v[170:171] neg_lo:[1,0,0] neg_hi:[1,0,0]
	v_pk_fma_f32 v[128:129], v[164:165], v[160:161], v[128:129]
	v_pk_fma_f32 v[130:131], v[166:167], v[162:163], v[130:131]
	v_pk_fma_f32 v[156:157], v[156:157], v[128:129], v[168:169] neg_lo:[1,0,0] neg_hi:[1,0,0]
	v_pk_fma_f32 v[158:159], v[158:159], v[130:131], v[170:171] neg_lo:[1,0,0] neg_hi:[1,0,0]
; __device__ __forceinline__ float sigmoidf_(float x) { return 1.f / (1.f + __expf(-x)); }
	v_div_fmas_f32 v159, v159, v163, v131
	s_mov_b64 vcc, s[28:29]
	v_div_fmas_f32 v158, v158, v162, v130
	s_mov_b64 vcc, s[26:27]
	v_div_fmas_f32 v157, v157, v161, v129
	s_mov_b64 vcc, s[2:3]
	v_div_fmas_f32 v156, v156, v160, v128
	v_div_fixup_f32 v152, v156, v152, 1.0
	v_div_fixup_f32 v153, v157, v153, 1.0
	v_div_fixup_f32 v154, v158, v154, 1.0
	v_div_fixup_f32 v155, v159, v155, 1.0
	v_pk_mul_f32 v[152:153], v[60:61], v[152:153]
	v_pk_mul_f32 v[154:155], v[62:63], v[154:155]
	v_pk_mul_f32 v[152:153], v[56:57], v[152:153]
	v_pk_mul_f32 v[154:155], v[58:59], v[154:155]
	v_cvt_pk_bf16_f32 v184, v152, v153
	v_cvt_pk_bf16_f32 v185, v154, v155
	global_store_dwordx2 v180, v[184:185], s[64:65]
	v_mul_f32_e32 v152, 0xbfb8aa3b, v52
	v_mul_f32_e32 v153, 0xbfb8aa3b, v53
	v_mul_f32_e32 v154, 0xbfb8aa3b, v54
	v_mul_f32_e32 v155, 0xbfb8aa3b, v55
	v_exp_f32_e32 v152, v152
	v_exp_f32_e32 v153, v153
	v_exp_f32_e32 v154, v154
	v_exp_f32_e32 v155, v155
	v_pk_add_f32 v[152:153], v[152:153], 1.0 op_sel_hi:[1,0]
	v_pk_add_f32 v[154:155], v[154:155], 1.0 op_sel_hi:[1,0]
	v_div_scale_f32 v156, s[38:39], v152, v152, 1.0
	v_div_scale_f32 v157, s[38:39], v153, v153, 1.0
	v_div_scale_f32 v158, s[38:39], v154, v154, 1.0
	v_div_scale_f32 v159, s[38:39], v155, v155, 1.0
	v_rcp_f32_e32 v160, v156
	v_rcp_f32_e32 v161, v157
	v_rcp_f32_e32 v162, v158
	v_rcp_f32_e32 v163, v159
	v_pk_fma_f32 v[164:165], v[156:157], v[160:161], 1.0 op_sel_hi:[1,1,0] neg_lo:[1,0,0] neg_hi:[1,0,0]
	v_pk_fma_f32 v[166:167], v[158:159], v[162:163], 1.0 op_sel_hi:[1,1,0] neg_lo:[1,0,0] neg_hi:[1,0,0]
	v_pk_fma_f32 v[160:161], v[164:165], v[160:161], v[160:161]
	v_pk_fma_f32 v[162:163], v[166:167], v[162:163], v[162:163]
	v_div_scale_f32 v168, s[2:3], 1.0, v152, 1.0
	v_div_scale_f32 v169, s[26:27], 1.0, v153, 1.0
	v_div_scale_f32 v170, s[28:29], 1.0, v154, 1.0
	v_div_scale_f32 v171, vcc, 1.0, v155, 1.0
	v_pk_mul_f32 v[128:129], v[168:169], v[160:161]
	v_pk_mul_f32 v[130:131], v[170:171], v[162:163]
	v_pk_fma_f32 v[164:165], v[156:157], v[128:129], v[168:169] neg_lo:[1,0,0] neg_hi:[1,0,0]
	v_pk_fma_f32 v[166:167], v[158:159], v[130:131], v[170:171] neg_lo:[1,0,0] neg_hi:[1,0,0]
	v_pk_fma_f32 v[128:129], v[164:165], v[160:161], v[128:129]
	v_pk_fma_f32 v[130:131], v[166:167], v[162:163], v[130:131]
	v_pk_fma_f32 v[156:157], v[156:157], v[128:129], v[168:169] neg_lo:[1,0,0] neg_hi:[1,0,0]
	v_pk_fma_f32 v[158:159], v[158:159], v[130:131], v[170:171] neg_lo:[1,0,0] neg_hi:[1,0,0]
	v_div_fmas_f32 v159, v159, v163, v131
	s_mov_b64 vcc, s[28:29]
	v_div_fmas_f32 v158, v158, v162, v130
	s_mov_b64 vcc, s[26:27]
	v_div_fmas_f32 v157, v157, v161, v129
	s_mov_b64 vcc, s[2:3]
	v_div_fmas_f32 v156, v156, v160, v128
	v_div_fixup_f32 v152, v156, v152, 1.0
	v_div_fixup_f32 v153, v157, v153, 1.0
	v_div_fixup_f32 v154, v158, v154, 1.0
	v_div_fixup_f32 v155, v159, v155, 1.0
	v_pk_mul_f32 v[152:153], v[52:53], v[152:153]
	v_pk_mul_f32 v[154:155], v[54:55], v[154:155]
	v_pk_mul_f32 v[152:153], v[48:49], v[152:153]
	v_pk_mul_f32 v[154:155], v[50:51], v[154:155]
	v_cvt_pk_bf16_f32 v186, v152, v153
	v_cvt_pk_bf16_f32 v187, v154, v155
	global_store_dwordx2 v180, v[186:187], s[64:65] offset:128
	v_mul_f32_e32 v152, 0xbfb8aa3b, v44
	v_mul_f32_e32 v153, 0xbfb8aa3b, v45
	v_mul_f32_e32 v154, 0xbfb8aa3b, v46
	v_mul_f32_e32 v155, 0xbfb8aa3b, v47
	v_exp_f32_e32 v152, v152
	v_exp_f32_e32 v153, v153
	v_exp_f32_e32 v154, v154
	v_exp_f32_e32 v155, v155
	v_pk_add_f32 v[152:153], v[152:153], 1.0 op_sel_hi:[1,0]
	v_pk_add_f32 v[154:155], v[154:155], 1.0 op_sel_hi:[1,0]
	v_div_scale_f32 v156, s[38:39], v152, v152, 1.0
	v_div_scale_f32 v157, s[38:39], v153, v153, 1.0
	v_div_scale_f32 v158, s[38:39], v154, v154, 1.0
	v_div_scale_f32 v159, s[38:39], v155, v155, 1.0
	v_rcp_f32_e32 v160, v156
	v_rcp_f32_e32 v161, v157
	v_rcp_f32_e32 v162, v158
	v_rcp_f32_e32 v163, v159
	v_pk_fma_f32 v[164:165], v[156:157], v[160:161], 1.0 op_sel_hi:[1,1,0] neg_lo:[1,0,0] neg_hi:[1,0,0]
	v_pk_fma_f32 v[166:167], v[158:159], v[162:163], 1.0 op_sel_hi:[1,1,0] neg_lo:[1,0,0] neg_hi:[1,0,0]
	v_pk_fma_f32 v[160:161], v[164:165], v[160:161], v[160:161]
	v_pk_fma_f32 v[162:163], v[166:167], v[162:163], v[162:163]
	v_div_scale_f32 v168, s[2:3], 1.0, v152, 1.0
	v_div_scale_f32 v169, s[26:27], 1.0, v153, 1.0
	v_div_scale_f32 v170, s[28:29], 1.0, v154, 1.0
	v_div_scale_f32 v171, vcc, 1.0, v155, 1.0
	v_pk_mul_f32 v[128:129], v[168:169], v[160:161]
	v_pk_mul_f32 v[130:131], v[170:171], v[162:163]
	v_pk_fma_f32 v[164:165], v[156:157], v[128:129], v[168:169] neg_lo:[1,0,0] neg_hi:[1,0,0]
	v_pk_fma_f32 v[166:167], v[158:159], v[130:131], v[170:171] neg_lo:[1,0,0] neg_hi:[1,0,0]
	v_pk_fma_f32 v[128:129], v[164:165], v[160:161], v[128:129]
	v_pk_fma_f32 v[130:131], v[166:167], v[162:163], v[130:131]
	v_pk_fma_f32 v[156:157], v[156:157], v[128:129], v[168:169] neg_lo:[1,0,0] neg_hi:[1,0,0]
	v_pk_fma_f32 v[158:159], v[158:159], v[130:131], v[170:171] neg_lo:[1,0,0] neg_hi:[1,0,0]
	v_div_fmas_f32 v159, v159, v163, v131
	s_mov_b64 vcc, s[28:29]
	v_div_fmas_f32 v158, v158, v162, v130
	s_mov_b64 vcc, s[26:27]
	v_div_fmas_f32 v157, v157, v161, v129
	s_mov_b64 vcc, s[2:3]
	v_div_fmas_f32 v156, v156, v160, v128
	v_div_fixup_f32 v152, v156, v152, 1.0
	v_div_fixup_f32 v153, v157, v153, 1.0
	v_div_fixup_f32 v154, v158, v154, 1.0
	v_div_fixup_f32 v155, v159, v155, 1.0
	v_pk_mul_f32 v[152:153], v[44:45], v[152:153]
	v_pk_mul_f32 v[154:155], v[46:47], v[154:155]
	v_pk_mul_f32 v[152:153], v[40:41], v[152:153]
	v_pk_mul_f32 v[154:155], v[42:43], v[154:155]
	v_cvt_pk_bf16_f32 v184, v152, v153
	v_cvt_pk_bf16_f32 v185, v154, v155
	global_store_dwordx2 v181, v[184:185], s[64:65]
	v_mul_f32_e32 v152, 0xbfb8aa3b, v36
; __device__ __forceinline__ float sigmoidf_(float x) { return 1.f / (1.f + __expf(-x)); }
	v_mul_f32_e32 v153, 0xbfb8aa3b, v37
	v_mul_f32_e32 v154, 0xbfb8aa3b, v38
	v_mul_f32_e32 v155, 0xbfb8aa3b, v39
	v_exp_f32_e32 v152, v152
	v_exp_f32_e32 v153, v153
	v_exp_f32_e32 v154, v154
	v_exp_f32_e32 v155, v155
	v_pk_add_f32 v[152:153], v[152:153], 1.0 op_sel_hi:[1,0]
	v_pk_add_f32 v[154:155], v[154:155], 1.0 op_sel_hi:[1,0]
	v_div_scale_f32 v156, s[38:39], v152, v152, 1.0
	v_div_scale_f32 v157, s[38:39], v153, v153, 1.0
	v_div_scale_f32 v158, s[38:39], v154, v154, 1.0
	v_div_scale_f32 v159, s[38:39], v155, v155, 1.0
	v_rcp_f32_e32 v160, v156
	v_rcp_f32_e32 v161, v157
	v_rcp_f32_e32 v162, v158
	v_rcp_f32_e32 v163, v159
	v_pk_fma_f32 v[164:165], v[156:157], v[160:161], 1.0 op_sel_hi:[1,1,0] neg_lo:[1,0,0] neg_hi:[1,0,0]
	v_pk_fma_f32 v[166:167], v[158:159], v[162:163], 1.0 op_sel_hi:[1,1,0] neg_lo:[1,0,0] neg_hi:[1,0,0]
	v_pk_fma_f32 v[160:161], v[164:165], v[160:161], v[160:161]
	v_pk_fma_f32 v[162:163], v[166:167], v[162:163], v[162:163]
	v_div_scale_f32 v168, s[2:3], 1.0, v152, 1.0
	v_div_scale_f32 v169, s[26:27], 1.0, v153, 1.0
	v_div_scale_f32 v170, s[28:29], 1.0, v154, 1.0
	v_div_scale_f32 v171, vcc, 1.0, v155, 1.0
	v_pk_mul_f32 v[128:129], v[168:169], v[160:161]
	v_pk_mul_f32 v[130:131], v[170:171], v[162:163]
	v_pk_fma_f32 v[164:165], v[156:157], v[128:129], v[168:169] neg_lo:[1,0,0] neg_hi:[1,0,0]
	v_pk_fma_f32 v[166:167], v[158:159], v[130:131], v[170:171] neg_lo:[1,0,0] neg_hi:[1,0,0]
	v_pk_fma_f32 v[128:129], v[164:165], v[160:161], v[128:129]
	v_pk_fma_f32 v[130:131], v[166:167], v[162:163], v[130:131]
	v_pk_fma_f32 v[156:157], v[156:157], v[128:129], v[168:169] neg_lo:[1,0,0] neg_hi:[1,0,0]
	v_pk_fma_f32 v[158:159], v[158:159], v[130:131], v[170:171] neg_lo:[1,0,0] neg_hi:[1,0,0]
	v_div_fmas_f32 v159, v159, v163, v131
	s_mov_b64 vcc, s[28:29]
	v_div_fmas_f32 v158, v158, v162, v130
	s_mov_b64 vcc, s[26:27]
	v_div_fmas_f32 v157, v157, v161, v129
	s_mov_b64 vcc, s[2:3]
	v_div_fmas_f32 v156, v156, v160, v128
	v_div_fixup_f32 v152, v156, v152, 1.0
	v_div_fixup_f32 v153, v157, v153, 1.0
	v_div_fixup_f32 v154, v158, v154, 1.0
	v_div_fixup_f32 v155, v159, v155, 1.0
	v_pk_mul_f32 v[152:153], v[36:37], v[152:153]
	v_pk_mul_f32 v[154:155], v[38:39], v[154:155]
	v_pk_mul_f32 v[152:153], v[32:33], v[152:153]
	v_pk_mul_f32 v[154:155], v[34:35], v[154:155]
	v_cvt_pk_bf16_f32 v186, v152, v153
	v_cvt_pk_bf16_f32 v187, v154, v155
	global_store_dwordx2 v181, v[186:187], s[64:65] offset:128
	v_mul_f32_e32 v152, 0xbfb8aa3b, v28
	v_mul_f32_e32 v153, 0xbfb8aa3b, v29
	v_mul_f32_e32 v154, 0xbfb8aa3b, v30
	v_mul_f32_e32 v155, 0xbfb8aa3b, v31
	v_exp_f32_e32 v152, v152
	v_exp_f32_e32 v153, v153
	v_exp_f32_e32 v154, v154
	v_exp_f32_e32 v155, v155
	v_pk_add_f32 v[152:153], v[152:153], 1.0 op_sel_hi:[1,0]
	v_pk_add_f32 v[154:155], v[154:155], 1.0 op_sel_hi:[1,0]
	v_div_scale_f32 v156, s[38:39], v152, v152, 1.0
	v_div_scale_f32 v157, s[38:39], v153, v153, 1.0
	v_div_scale_f32 v158, s[38:39], v154, v154, 1.0
	v_div_scale_f32 v159, s[38:39], v155, v155, 1.0
	v_rcp_f32_e32 v160, v156
	v_rcp_f32_e32 v161, v157
	v_rcp_f32_e32 v162, v158
	v_rcp_f32_e32 v163, v159
	v_pk_fma_f32 v[164:165], v[156:157], v[160:161], 1.0 op_sel_hi:[1,1,0] neg_lo:[1,0,0] neg_hi:[1,0,0]
	v_pk_fma_f32 v[166:167], v[158:159], v[162:163], 1.0 op_sel_hi:[1,1,0] neg_lo:[1,0,0] neg_hi:[1,0,0]
	v_pk_fma_f32 v[160:161], v[164:165], v[160:161], v[160:161]
	v_pk_fma_f32 v[162:163], v[166:167], v[162:163], v[162:163]
	v_div_scale_f32 v168, s[2:3], 1.0, v152, 1.0
	v_div_scale_f32 v169, s[26:27], 1.0, v153, 1.0
	v_div_scale_f32 v170, s[28:29], 1.0, v154, 1.0
	v_div_scale_f32 v171, vcc, 1.0, v155, 1.0
	v_pk_mul_f32 v[128:129], v[168:169], v[160:161]
	v_pk_mul_f32 v[130:131], v[170:171], v[162:163]
	v_pk_fma_f32 v[164:165], v[156:157], v[128:129], v[168:169] neg_lo:[1,0,0] neg_hi:[1,0,0]
	v_pk_fma_f32 v[166:167], v[158:159], v[130:131], v[170:171] neg_lo:[1,0,0] neg_hi:[1,0,0]
	v_pk_fma_f32 v[128:129], v[164:165], v[160:161], v[128:129]
	v_pk_fma_f32 v[130:131], v[166:167], v[162:163], v[130:131]
	v_pk_fma_f32 v[156:157], v[156:157], v[128:129], v[168:169] neg_lo:[1,0,0] neg_hi:[1,0,0]
	v_pk_fma_f32 v[158:159], v[158:159], v[130:131], v[170:171] neg_lo:[1,0,0] neg_hi:[1,0,0]
	v_div_fmas_f32 v159, v159, v163, v131
	s_mov_b64 vcc, s[28:29]
	v_div_fmas_f32 v158, v158, v162, v130
	s_mov_b64 vcc, s[26:27]
	v_div_fmas_f32 v157, v157, v161, v129
	s_mov_b64 vcc, s[2:3]
	v_div_fmas_f32 v156, v156, v160, v128
	v_div_fixup_f32 v152, v156, v152, 1.0
	v_div_fixup_f32 v153, v157, v153, 1.0
	v_div_fixup_f32 v154, v158, v154, 1.0
	v_div_fixup_f32 v155, v159, v155, 1.0
	v_pk_mul_f32 v[152:153], v[28:29], v[152:153]
	v_pk_mul_f32 v[154:155], v[30:31], v[154:155]
	v_pk_mul_f32 v[152:153], v[24:25], v[152:153]
	v_pk_mul_f32 v[154:155], v[26:27], v[154:155]
	v_cvt_pk_bf16_f32 v184, v152, v153
	v_cvt_pk_bf16_f32 v185, v154, v155
	global_store_dwordx2 v182, v[184:185], s[64:65]
	v_mul_f32_e32 v152, 0xbfb8aa3b, v20
	v_mul_f32_e32 v153, 0xbfb8aa3b, v21
	v_mul_f32_e32 v154, 0xbfb8aa3b, v22
	v_mul_f32_e32 v155, 0xbfb8aa3b, v23
	v_exp_f32_e32 v152, v152
	v_exp_f32_e32 v153, v153
	v_exp_f32_e32 v154, v154
	v_exp_f32_e32 v155, v155
	v_pk_add_f32 v[152:153], v[152:153], 1.0 op_sel_hi:[1,0]
	v_pk_add_f32 v[154:155], v[154:155], 1.0 op_sel_hi:[1,0]
	v_div_scale_f32 v156, s[38:39], v152, v152, 1.0
	v_div_scale_f32 v157, s[38:39], v153, v153, 1.0
	v_div_scale_f32 v158, s[38:39], v154, v154, 1.0
	v_div_scale_f32 v159, s[38:39], v155, v155, 1.0
	v_rcp_f32_e32 v160, v156
	v_rcp_f32_e32 v161, v157
	v_rcp_f32_e32 v162, v158
	v_rcp_f32_e32 v163, v159
	v_pk_fma_f32 v[164:165], v[156:157], v[160:161], 1.0 op_sel_hi:[1,1,0] neg_lo:[1,0,0] neg_hi:[1,0,0]
; template <class Epi>
; __device__ __forceinline__ void gemm_phase(LAS unsigned char* lds, const Gemm g, const Epi& E) {
;     ...
; #pragma unroll
;       for (int ai = 0; ai < 2; ++ai)
; #pragma unroll
;         for (int m = 0; m < 4; ++m)
; #pragma unroll
;           for (int bj = 0; bj < 2; ++bj)
;           { E.st2(cur.w, cur.pm * BM + ai * HALF + wr * 64 + m * 16 + fr, cur.pn * BM + bj * HALF + wc * 32 + 8 * fq, acc[ai][bj][m][0], acc[ai][bj][m][1]); if (bj == 1 && (m & 1)) asm volatile("" ::: "memory"); }
	v_pk_fma_f32 v[166:167], v[158:159], v[162:163], 1.0 op_sel_hi:[1,1,0] neg_lo:[1,0,0] neg_hi:[1,0,0]
	v_pk_fma_f32 v[160:161], v[164:165], v[160:161], v[160:161]
	v_pk_fma_f32 v[162:163], v[166:167], v[162:163], v[162:163]
	v_div_scale_f32 v168, s[2:3], 1.0, v152, 1.0
	v_div_scale_f32 v169, s[26:27], 1.0, v153, 1.0
	v_div_scale_f32 v170, s[28:29], 1.0, v154, 1.0
	v_div_scale_f32 v171, vcc, 1.0, v155, 1.0
	v_pk_mul_f32 v[128:129], v[168:169], v[160:161]
	v_pk_mul_f32 v[130:131], v[170:171], v[162:163]
	v_pk_fma_f32 v[164:165], v[156:157], v[128:129], v[168:169] neg_lo:[1,0,0] neg_hi:[1,0,0]
	v_pk_fma_f32 v[166:167], v[158:159], v[130:131], v[170:171] neg_lo:[1,0,0] neg_hi:[1,0,0]
	v_pk_fma_f32 v[128:129], v[164:165], v[160:161], v[128:129]
	v_pk_fma_f32 v[130:131], v[166:167], v[162:163], v[130:131]
	v_pk_fma_f32 v[156:157], v[156:157], v[128:129], v[168:169] neg_lo:[1,0,0] neg_hi:[1,0,0]
	v_pk_fma_f32 v[158:159], v[158:159], v[130:131], v[170:171] neg_lo:[1,0,0] neg_hi:[1,0,0]
	v_div_fmas_f32 v159, v159, v163, v131
	s_mov_b64 vcc, s[28:29]
	v_div_fmas_f32 v158, v158, v162, v130
	s_mov_b64 vcc, s[26:27]
	v_div_fmas_f32 v157, v157, v161, v129
	s_mov_b64 vcc, s[2:3]
	v_div_fmas_f32 v156, v156, v160, v128
	v_div_fixup_f32 v152, v156, v152, 1.0
	v_div_fixup_f32 v153, v157, v153, 1.0
	v_div_fixup_f32 v154, v158, v154, 1.0
	v_div_fixup_f32 v155, v159, v155, 1.0
	v_pk_mul_f32 v[152:153], v[20:21], v[152:153]
	v_pk_mul_f32 v[154:155], v[22:23], v[154:155]
	v_pk_mul_f32 v[152:153], v[16:17], v[152:153]
	v_pk_mul_f32 v[154:155], v[18:19], v[154:155]
	v_cvt_pk_bf16_f32 v186, v152, v153
	v_cvt_pk_bf16_f32 v187, v154, v155
	global_store_dwordx2 v182, v[186:187], s[64:65] offset:128
	v_mul_f32_e32 v152, 0xbfb8aa3b, v12
	v_mul_f32_e32 v153, 0xbfb8aa3b, v13
	v_mul_f32_e32 v154, 0xbfb8aa3b, v14
	v_mul_f32_e32 v155, 0xbfb8aa3b, v15
	v_exp_f32_e32 v152, v152
	v_exp_f32_e32 v153, v153
	v_exp_f32_e32 v154, v154
	v_exp_f32_e32 v155, v155
	v_pk_add_f32 v[152:153], v[152:153], 1.0 op_sel_hi:[1,0]
	v_pk_add_f32 v[154:155], v[154:155], 1.0 op_sel_hi:[1,0]
	v_div_scale_f32 v156, s[38:39], v152, v152, 1.0
	v_div_scale_f32 v157, s[38:39], v153, v153, 1.0
	v_div_scale_f32 v158, s[38:39], v154, v154, 1.0
	v_div_scale_f32 v159, s[38:39], v155, v155, 1.0
	v_rcp_f32_e32 v160, v156
	v_rcp_f32_e32 v161, v157
	v_rcp_f32_e32 v162, v158
	v_rcp_f32_e32 v163, v159
	v_pk_fma_f32 v[164:165], v[156:157], v[160:161], 1.0 op_sel_hi:[1,1,0] neg_lo:[1,0,0] neg_hi:[1,0,0]
	v_pk_fma_f32 v[166:167], v[158:159], v[162:163], 1.0 op_sel_hi:[1,1,0] neg_lo:[1,0,0] neg_hi:[1,0,0]
	v_pk_fma_f32 v[160:161], v[164:165], v[160:161], v[160:161]
	v_pk_fma_f32 v[162:163], v[166:167], v[162:163], v[162:163]
	v_div_scale_f32 v168, s[2:3], 1.0, v152, 1.0
	v_div_scale_f32 v169, s[26:27], 1.0, v153, 1.0
	v_div_scale_f32 v170, s[28:29], 1.0, v154, 1.0
	v_div_scale_f32 v171, vcc, 1.0, v155, 1.0
	v_pk_mul_f32 v[128:129], v[168:169], v[160:161]
	v_pk_mul_f32 v[130:131], v[170:171], v[162:163]
	v_pk_fma_f32 v[164:165], v[156:157], v[128:129], v[168:169] neg_lo:[1,0,0] neg_hi:[1,0,0]
	v_pk_fma_f32 v[166:167], v[158:159], v[130:131], v[170:171] neg_lo:[1,0,0] neg_hi:[1,0,0]
	v_pk_fma_f32 v[128:129], v[164:165], v[160:161], v[128:129]
	v_pk_fma_f32 v[130:131], v[166:167], v[162:163], v[130:131]
	v_pk_fma_f32 v[156:157], v[156:157], v[128:129], v[168:169] neg_lo:[1,0,0] neg_hi:[1,0,0]
	v_pk_fma_f32 v[158:159], v[158:159], v[130:131], v[170:171] neg_lo:[1,0,0] neg_hi:[1,0,0]
	v_div_fmas_f32 v159, v159, v163, v131
	s_mov_b64 vcc, s[28:29]
	v_div_fmas_f32 v158, v158, v162, v130
	s_mov_b64 vcc, s[26:27]
	v_div_fmas_f32 v157, v157, v161, v129
	s_mov_b64 vcc, s[2:3]
	v_div_fmas_f32 v156, v156, v160, v128
	v_div_fixup_f32 v152, v156, v152, 1.0
	v_div_fixup_f32 v153, v157, v153, 1.0
	v_div_fixup_f32 v154, v158, v154, 1.0
	v_div_fixup_f32 v155, v159, v155, 1.0
	v_pk_mul_f32 v[152:153], v[12:13], v[152:153]
	v_pk_mul_f32 v[154:155], v[14:15], v[154:155]
	v_pk_mul_f32 v[152:153], v[8:9], v[152:153]
	v_pk_mul_f32 v[154:155], v[10:11], v[154:155]
	v_cvt_pk_bf16_f32 v184, v152, v153
	v_cvt_pk_bf16_f32 v185, v154, v155
	global_store_dwordx2 v183, v[184:185], s[64:65]
	v_mul_f32_e32 v152, 0xbfb8aa3b, v4
	v_mul_f32_e32 v153, 0xbfb8aa3b, v5
	v_mul_f32_e32 v154, 0xbfb8aa3b, v6
	v_mul_f32_e32 v155, 0xbfb8aa3b, v7
	v_exp_f32_e32 v152, v152
	v_exp_f32_e32 v153, v153
	v_exp_f32_e32 v154, v154
	v_exp_f32_e32 v155, v155
	v_pk_add_f32 v[152:153], v[152:153], 1.0 op_sel_hi:[1,0]
	v_pk_add_f32 v[154:155], v[154:155], 1.0 op_sel_hi:[1,0]
	v_div_scale_f32 v156, s[38:39], v152, v152, 1.0
	v_div_scale_f32 v157, s[38:39], v153, v153, 1.0
	v_div_scale_f32 v158, s[38:39], v154, v154, 1.0
	v_div_scale_f32 v159, s[38:39], v155, v155, 1.0
	v_rcp_f32_e32 v160, v156
	v_rcp_f32_e32 v161, v157
	v_rcp_f32_e32 v162, v158
	v_rcp_f32_e32 v163, v159
	v_pk_fma_f32 v[164:165], v[156:157], v[160:161], 1.0 op_sel_hi:[1,1,0] neg_lo:[1,0,0] neg_hi:[1,0,0]
	v_pk_fma_f32 v[166:167], v[158:159], v[162:163], 1.0 op_sel_hi:[1,1,0] neg_lo:[1,0,0] neg_hi:[1,0,0]
	v_pk_fma_f32 v[160:161], v[164:165], v[160:161], v[160:161]
	v_pk_fma_f32 v[162:163], v[166:167], v[162:163], v[162:163]
	v_div_scale_f32 v168, s[2:3], 1.0, v152, 1.0
	v_div_scale_f32 v169, s[26:27], 1.0, v153, 1.0
	v_div_scale_f32 v170, s[28:29], 1.0, v154, 1.0
	v_div_scale_f32 v171, vcc, 1.0, v155, 1.0
	v_pk_mul_f32 v[128:129], v[168:169], v[160:161]
	v_pk_mul_f32 v[130:131], v[170:171], v[162:163]
	v_pk_fma_f32 v[164:165], v[156:157], v[128:129], v[168:169] neg_lo:[1,0,0] neg_hi:[1,0,0]
	v_pk_fma_f32 v[166:167], v[158:159], v[130:131], v[170:171] neg_lo:[1,0,0] neg_hi:[1,0,0]
	v_pk_fma_f32 v[128:129], v[164:165], v[160:161], v[128:129]
	v_pk_fma_f32 v[130:131], v[166:167], v[162:163], v[130:131]
	v_pk_fma_f32 v[156:157], v[156:157], v[128:129], v[168:169] neg_lo:[1,0,0] neg_hi:[1,0,0]
	v_pk_fma_f32 v[158:159], v[158:159], v[130:131], v[170:171] neg_lo:[1,0,0] neg_hi:[1,0,0]
	v_div_fmas_f32 v159, v159, v163, v131
	s_mov_b64 vcc, s[28:29]
	v_div_fmas_f32 v158, v158, v162, v130
	s_mov_b64 vcc, s[26:27]
	v_div_fmas_f32 v157, v157, v161, v129
	s_mov_b64 vcc, s[2:3]
	v_div_fmas_f32 v156, v156, v160, v128
	v_div_fixup_f32 v152, v156, v152, 1.0
	v_div_fixup_f32 v153, v157, v153, 1.0
	v_div_fixup_f32 v154, v158, v154, 1.0
	v_div_fixup_f32 v155, v159, v155, 1.0
	v_pk_mul_f32 v[152:153], v[4:5], v[152:153]
	v_pk_mul_f32 v[154:155], v[6:7], v[154:155]
	v_pk_mul_f32 v[152:153], v[0:1], v[152:153]
	v_pk_mul_f32 v[154:155], v[2:3], v[154:155]
	v_cvt_pk_bf16_f32 v186, v152, v153
	v_cvt_pk_bf16_f32 v187, v154, v155
	global_store_dwordx2 v183, v[186:187], s[64:65] offset:128
	s_mov_b32 s32, 1
	s_branch .LBB0_567

.Lepi0_go:
	v_add_u32_e32 v177, s2, v176
	v_add_u32_e32 v178, s2, v177
	v_add_u32_e32 v179, s2, v178
	v_add_u32_e32 v180, s3, v176
	v_add_u32_e32 v181, s2, v180
	v_add_u32_e32 v182, s2, v181
	v_add_u32_e32 v183, s2, v182
	v_cvt_pk_bf16_f32 v184, v124, v125
	v_cvt_pk_bf16_f32 v185, v126, v127
	v_cvt_pk_bf16_f32 v186, v120, v121
	v_cvt_pk_bf16_f32 v187, v122, v123
	global_store_dwordx4 v176, v[184:187], s[26:27]
	v_cvt_pk_bf16_f32 v188, v116, v117
	v_cvt_pk_bf16_f32 v189, v118, v119
	v_cvt_pk_bf16_f32 v190, v112, v113
	v_cvt_pk_bf16_f32 v191, v114, v115
	global_store_dwordx4 v176, v[188:191], s[26:27] offset:256
	v_cvt_pk_bf16_f32 v184, v108, v109
	v_cvt_pk_bf16_f32 v185, v110, v111
	v_cvt_pk_bf16_f32 v186, v104, v105
	v_cvt_pk_bf16_f32 v187, v106, v107
	global_store_dwordx4 v177, v[184:187], s[26:27]
	v_cvt_pk_bf16_f32 v188, v100, v101
	v_cvt_pk_bf16_f32 v189, v102, v103
	v_cvt_pk_bf16_f32 v190, v96, v97
	v_cvt_pk_bf16_f32 v191, v98, v99
	global_store_dwordx4 v177, v[188:191], s[26:27] offset:256
	v_cvt_pk_bf16_f32 v184, v92, v93
	v_cvt_pk_bf16_f32 v185, v94, v95
	v_cvt_pk_bf16_f32 v186, v88, v89
	v_cvt_pk_bf16_f32 v187, v90, v91
	global_store_dwordx4 v178, v[184:187], s[26:27]
	v_cvt_pk_bf16_f32 v188, v84, v85
	v_cvt_pk_bf16_f32 v189, v86, v87
	v_cvt_pk_bf16_f32 v190, v80, v81
	v_cvt_pk_bf16_f32 v191, v82, v83
	global_store_dwordx4 v178, v[188:191], s[26:27] offset:256
	v_cvt_pk_bf16_f32 v184, v76, v77
	v_cvt_pk_bf16_f32 v185, v78, v79
	v_cvt_pk_bf16_f32 v186, v72, v73
	v_cvt_pk_bf16_f32 v187, v74, v75
	global_store_dwordx4 v179, v[184:187], s[26:27]
	v_cvt_pk_bf16_f32 v188, v68, v69
	v_cvt_pk_bf16_f32 v189, v70, v71
	v_cvt_pk_bf16_f32 v190, v64, v65
	v_cvt_pk_bf16_f32 v191, v66, v67
	global_store_dwordx4 v179, v[188:191], s[26:27] offset:256
	v_cvt_pk_bf16_f32 v184, v60, v61
	v_cvt_pk_bf16_f32 v185, v62, v63
	v_cvt_pk_bf16_f32 v186, v56, v57
	v_cvt_pk_bf16_f32 v187, v58, v59
	global_store_dwordx4 v180, v[184:187], s[26:27]
	v_cvt_pk_bf16_f32 v188, v52, v53
	v_cvt_pk_bf16_f32 v189, v54, v55
	v_cvt_pk_bf16_f32 v190, v48, v49
	v_cvt_pk_bf16_f32 v191, v50, v51
	global_store_dwordx4 v180, v[188:191], s[26:27] offset:256
	v_cvt_pk_bf16_f32 v184, v44, v45
	v_cvt_pk_bf16_f32 v185, v46, v47
	v_cvt_pk_bf16_f32 v186, v40, v41
	v_cvt_pk_bf16_f32 v187, v42, v43
	global_store_dwordx4 v181, v[184:187], s[26:27]
	v_cvt_pk_bf16_f32 v188, v36, v37
	v_cvt_pk_bf16_f32 v189, v38, v39
	v_cvt_pk_bf16_f32 v190, v32, v33
	v_cvt_pk_bf16_f32 v191, v34, v35
	global_store_dwordx4 v181, v[188:191], s[26:27] offset:256
	v_cvt_pk_bf16_f32 v184, v28, v29
	v_cvt_pk_bf16_f32 v185, v30, v31
	v_cvt_pk_bf16_f32 v186, v24, v25
	v_cvt_pk_bf16_f32 v187, v26, v27
	global_store_dwordx4 v182, v[184:187], s[26:27]
	v_cvt_pk_bf16_f32 v188, v20, v21
	v_cvt_pk_bf16_f32 v189, v22, v23
	v_cvt_pk_bf16_f32 v190, v16, v17
	v_cvt_pk_bf16_f32 v191, v18, v19
	global_store_dwordx4 v182, v[188:191], s[26:27] offset:256
	v_cvt_pk_bf16_f32 v184, v12, v13
	v_cvt_pk_bf16_f32 v185, v14, v15
	v_cvt_pk_bf16_f32 v186, v8, v9
	v_cvt_pk_bf16_f32 v187, v10, v11
	global_store_dwordx4 v183, v[184:187], s[26:27]
	v_cvt_pk_bf16_f32 v188, v4, v5
	v_cvt_pk_bf16_f32 v189, v6, v7
	v_cvt_pk_bf16_f32 v190, v0, v1
	v_cvt_pk_bf16_f32 v191, v2, v3
	global_store_dwordx4 v183, v[188:191], s[26:27] offset:256
	s_mov_b32 s32, 1
	s_branch .LBB0_567
.Lepi0_done:
	s_mov_b32 s32, 0
	s_branch .LBB0_567
.Lepi3:
	v_mul_u32_u24_e32 v176, 0x1800, v150
	v_lshl_add_u32 v176, v148, 1, v176
	v_add_u32_e32 v176, 0x800, v176
	v_lshlrev_b32_e32 v184, 11, v150
	v_lshl_add_u32 v184, v148, 1, v184
	v_add_u32_e32 v177, 0x18000, v176
	v_add_u32_e32 v185, 0x8000, v184
	v_add_u32_e32 v178, 0x30000, v176
	v_add_u32_e32 v186, 0x10000, v184
	v_add_u32_e32 v179, 0x48000, v176
	v_add_u32_e32 v187, 0x18000, v184
	v_add_u32_e32 v180, 0xc0000, v176
	v_add_u32_e32 v188, 0x40000, v184
	v_add_u32_e32 v181, 0xd8000, v176
	v_add_u32_e32 v189, 0x48000, v184
	v_add_u32_e32 v182, 0xf0000, v176
	v_add_u32_e32 v190, 0x50000, v184
	v_add_u32_e32 v183, 0x108000, v176
	v_add_u32_e32 v191, 0x58000, v184
	global_load_dwordx4 v[192:195], v176, s[64:65]
	global_load_dwordx4 v[200:203], v176, s[64:65] offset:256
	global_load_dwordx4 v[208:211], v177, s[64:65]
	global_load_dwordx4 v[216:219], v177, s[64:65] offset:256
	s_waitcnt vmcnt(3)
; __device__ __forceinline__ float sigmoidf_(float x) { return 1.f / (1.f + __expf(-x)); }
	v_lshlrev_b32_e32 v152, 16, v192
	v_and_b32_e32 v153, 0xffff0000, v192
	v_lshlrev_b32_e32 v154, 16, v193
	v_and_b32_e32 v155, 0xffff0000, v193
	v_lshlrev_b32_e32 v156, 16, v194
	v_and_b32_e32 v157, 0xffff0000, v194
	v_lshlrev_b32_e32 v158, 16, v195
	v_and_b32_e32 v159, 0xffff0000, v195
	v_mul_f32_e32 v152, 0xbfb8aa3b, v152
	v_mul_f32_e32 v153, 0xbfb8aa3b, v153
	v_mul_f32_e32 v154, 0xbfb8aa3b, v154
	v_mul_f32_e32 v155, 0xbfb8aa3b, v155
	v_mul_f32_e32 v156, 0xbfb8aa3b, v156
	v_mul_f32_e32 v157, 0xbfb8aa3b, v157
	v_mul_f32_e32 v158, 0xbfb8aa3b, v158
	v_mul_f32_e32 v159, 0xbfb8aa3b, v159
	v_exp_f32_e32 v152, v152
	v_exp_f32_e32 v153, v153
	v_exp_f32_e32 v154, v154
	v_exp_f32_e32 v155, v155
	v_exp_f32_e32 v156, v156
	v_exp_f32_e32 v157, v157
	v_exp_f32_e32 v158, v158
	v_exp_f32_e32 v159, v159
	v_pk_add_f32 v[152:153], v[152:153], 1.0 op_sel_hi:[1,0]
	v_pk_add_f32 v[154:155], v[154:155], 1.0 op_sel_hi:[1,0]
	v_pk_add_f32 v[156:157], v[156:157], 1.0 op_sel_hi:[1,0]
	v_pk_add_f32 v[158:159], v[158:159], 1.0 op_sel_hi:[1,0]
	v_div_scale_f32 v160, s[2:3], v152, v152, 1.0
	v_rcp_f32_e32 v161, v160
	s_nop 0
	v_fma_f32 v162, -v160, v161, 1.0
	v_fmac_f32_e32 v161, v162, v161
	v_div_scale_f32 v163, vcc, 1.0, v152, 1.0
	v_mul_f32_e32 v164, v163, v161
	v_div_scale_f32 v128, s[2:3], v153, v153, 1.0
	v_fma_f32 v162, -v160, v164, v163
	v_rcp_f32_e32 v129, v128
	v_fmac_f32_e32 v164, v162, v161
	s_nop 0
	v_fma_f32 v160, -v160, v164, v163
	v_fma_f32 v130, -v128, v129, 1.0
	v_div_fmas_f32 v160, v160, v161, v164
	v_fmac_f32_e32 v129, v130, v129
	v_div_fixup_f32 v152, v160, v152, 1.0
	v_div_scale_f32 v131, vcc, 1.0, v153, 1.0
	v_mul_f32_e32 v165, v131, v129
	v_div_scale_f32 v160, s[2:3], v154, v154, 1.0
	v_fma_f32 v130, -v128, v165, v131
	v_rcp_f32_e32 v161, v160
	v_fmac_f32_e32 v165, v130, v129
	s_nop 0
	v_fma_f32 v128, -v128, v165, v131
	v_fma_f32 v162, -v160, v161, 1.0
	v_div_fmas_f32 v128, v128, v129, v165
	v_fmac_f32_e32 v161, v162, v161
	v_div_fixup_f32 v153, v128, v153, 1.0
	v_div_scale_f32 v163, vcc, 1.0, v154, 1.0
	v_mul_f32_e32 v164, v163, v161
	v_div_scale_f32 v128, s[2:3], v155, v155, 1.0
	v_fma_f32 v162, -v160, v164, v163
	v_rcp_f32_e32 v129, v128
	v_fmac_f32_e32 v164, v162, v161
	s_nop 0
	v_fma_f32 v160, -v160, v164, v163
	v_fma_f32 v130, -v128, v129, 1.0
	v_div_fmas_f32 v160, v160, v161, v164
	v_fmac_f32_e32 v129, v130, v129
	v_div_fixup_f32 v154, v160, v154, 1.0
	v_div_scale_f32 v131, vcc, 1.0, v155, 1.0
	v_mul_f32_e32 v165, v131, v129
	v_div_scale_f32 v160, s[2:3], v156, v156, 1.0
	v_fma_f32 v130, -v128, v165, v131
	v_rcp_f32_e32 v161, v160
	v_fmac_f32_e32 v165, v130, v129
	s_nop 0
	v_fma_f32 v128, -v128, v165, v131
	v_fma_f32 v162, -v160, v161, 1.0
	v_div_fmas_f32 v128, v128, v129, v165
	v_fmac_f32_e32 v161, v162, v161
	v_div_fixup_f32 v155, v128, v155, 1.0
	v_div_scale_f32 v163, vcc, 1.0, v156, 1.0
	v_mul_f32_e32 v164, v163, v161
	v_div_scale_f32 v128, s[2:3], v157, v157, 1.0
	v_fma_f32 v162, -v160, v164, v163
	v_rcp_f32_e32 v129, v128
	v_fmac_f32_e32 v164, v162, v161
	s_nop 0
	v_fma_f32 v160, -v160, v164, v163
	v_fma_f32 v130, -v128, v129, 1.0
	v_div_fmas_f32 v160, v160, v161, v164
	v_fmac_f32_e32 v129, v130, v129
	v_div_fixup_f32 v156, v160, v156, 1.0
	v_div_scale_f32 v131, vcc, 1.0, v157, 1.0
	v_mul_f32_e32 v165, v131, v129
	v_div_scale_f32 v160, s[2:3], v158, v158, 1.0
	v_fma_f32 v130, -v128, v165, v131
	v_rcp_f32_e32 v161, v160
	v_fmac_f32_e32 v165, v130, v129
	s_nop 0
	v_fma_f32 v128, -v128, v165, v131
	v_fma_f32 v162, -v160, v161, 1.0
	v_div_fmas_f32 v128, v128, v129, v165
	v_fmac_f32_e32 v161, v162, v161
	v_div_fixup_f32 v157, v128, v157, 1.0
	v_div_scale_f32 v163, vcc, 1.0, v158, 1.0
	v_mul_f32_e32 v164, v163, v161
	v_div_scale_f32 v128, s[2:3], v159, v159, 1.0
	v_fma_f32 v162, -v160, v164, v163
	v_rcp_f32_e32 v129, v128
	v_fmac_f32_e32 v164, v162, v161
	s_nop 0
	v_fma_f32 v160, -v160, v164, v163
	v_fma_f32 v130, -v128, v129, 1.0
	v_div_fmas_f32 v160, v160, v161, v164
	v_fmac_f32_e32 v129, v130, v129
	v_div_fixup_f32 v158, v160, v158, 1.0
	v_div_scale_f32 v131, vcc, 1.0, v159, 1.0
	v_mul_f32_e32 v165, v131, v129
	v_fma_f32 v130, -v128, v165, v131
	v_fmac_f32_e32 v165, v130, v129
	v_fma_f32 v128, -v128, v165, v131
	v_div_fmas_f32 v128, v128, v129, v165
	v_div_fixup_f32 v159, v128, v159, 1.0
	v_pk_mul_f32 v[152:153], v[124:125], v[152:153]
	v_pk_mul_f32 v[154:155], v[126:127], v[154:155]
	v_pk_mul_f32 v[156:157], v[120:121], v[156:157]
	v_pk_mul_f32 v[158:159], v[122:123], v[158:159]
	v_cvt_pk_bf16_f32 v168, v152, v153
	v_cvt_pk_bf16_f32 v169, v154, v155
	v_cvt_pk_bf16_f32 v170, v156, v157
	v_cvt_pk_bf16_f32 v171, v158, v159
	global_store_dwordx4 v184, v[168:171], s[68:69]
	global_load_dwordx4 v[124:127], v178, s[64:65]
	s_waitcnt vmcnt(4)
; __device__ __forceinline__ float sigmoidf_(float x) { return 1.f / (1.f + __expf(-x)); }
	v_lshlrev_b32_e32 v152, 16, v200
	v_and_b32_e32 v153, 0xffff0000, v200
	v_lshlrev_b32_e32 v154, 16, v201
	v_and_b32_e32 v155, 0xffff0000, v201
	v_lshlrev_b32_e32 v156, 16, v202
	v_and_b32_e32 v157, 0xffff0000, v202
	v_lshlrev_b32_e32 v158, 16, v203
	v_and_b32_e32 v159, 0xffff0000, v203
	v_mul_f32_e32 v152, 0xbfb8aa3b, v152
	v_mul_f32_e32 v153, 0xbfb8aa3b, v153
	v_mul_f32_e32 v154, 0xbfb8aa3b, v154
	v_mul_f32_e32 v155, 0xbfb8aa3b, v155
	v_mul_f32_e32 v156, 0xbfb8aa3b, v156
	v_mul_f32_e32 v157, 0xbfb8aa3b, v157
	v_mul_f32_e32 v158, 0xbfb8aa3b, v158
	v_mul_f32_e32 v159, 0xbfb8aa3b, v159
	v_exp_f32_e32 v152, v152
	v_exp_f32_e32 v153, v153
	v_exp_f32_e32 v154, v154
	v_exp_f32_e32 v155, v155
	v_exp_f32_e32 v156, v156
	v_exp_f32_e32 v157, v157
	v_exp_f32_e32 v158, v158
	v_exp_f32_e32 v159, v159
	v_pk_add_f32 v[152:153], v[152:153], 1.0 op_sel_hi:[1,0]
	v_pk_add_f32 v[154:155], v[154:155], 1.0 op_sel_hi:[1,0]
	v_pk_add_f32 v[156:157], v[156:157], 1.0 op_sel_hi:[1,0]
	v_pk_add_f32 v[158:159], v[158:159], 1.0 op_sel_hi:[1,0]
	v_div_scale_f32 v160, s[2:3], v152, v152, 1.0
	v_rcp_f32_e32 v161, v160
	s_nop 0
	v_fma_f32 v162, -v160, v161, 1.0
	v_fmac_f32_e32 v161, v162, v161
	v_div_scale_f32 v163, vcc, 1.0, v152, 1.0
	v_mul_f32_e32 v164, v163, v161
	v_div_scale_f32 v128, s[2:3], v153, v153, 1.0
	v_fma_f32 v162, -v160, v164, v163
	v_rcp_f32_e32 v129, v128
	v_fmac_f32_e32 v164, v162, v161
	s_nop 0
	v_fma_f32 v160, -v160, v164, v163
	v_fma_f32 v130, -v128, v129, 1.0
	v_div_fmas_f32 v160, v160, v161, v164
	v_fmac_f32_e32 v129, v130, v129
	v_div_fixup_f32 v152, v160, v152, 1.0
	v_div_scale_f32 v131, vcc, 1.0, v153, 1.0
	v_mul_f32_e32 v165, v131, v129
	v_div_scale_f32 v160, s[2:3], v154, v154, 1.0
	v_fma_f32 v130, -v128, v165, v131
	v_rcp_f32_e32 v161, v160
	v_fmac_f32_e32 v165, v130, v129
	s_nop 0
	v_fma_f32 v128, -v128, v165, v131
	v_fma_f32 v162, -v160, v161, 1.0
	v_div_fmas_f32 v128, v128, v129, v165
	v_fmac_f32_e32 v161, v162, v161
	v_div_fixup_f32 v153, v128, v153, 1.0
	v_div_scale_f32 v163, vcc, 1.0, v154, 1.0
	v_mul_f32_e32 v164, v163, v161
	v_div_scale_f32 v128, s[2:3], v155, v155, 1.0
	v_fma_f32 v162, -v160, v164, v163
	v_rcp_f32_e32 v129, v128
	v_fmac_f32_e32 v164, v162, v161
	s_nop 0
	v_fma_f32 v160, -v160, v164, v163
	v_fma_f32 v130, -v128, v129, 1.0
	v_div_fmas_f32 v160, v160, v161, v164
	v_fmac_f32_e32 v129, v130, v129
	v_div_fixup_f32 v154, v160, v154, 1.0
	v_div_scale_f32 v131, vcc, 1.0, v155, 1.0
	v_mul_f32_e32 v165, v131, v129
	v_div_scale_f32 v160, s[2:3], v156, v156, 1.0
	v_fma_f32 v130, -v128, v165, v131
	v_rcp_f32_e32 v161, v160
	v_fmac_f32_e32 v165, v130, v129
	s_nop 0
	v_fma_f32 v128, -v128, v165, v131
	v_fma_f32 v162, -v160, v161, 1.0
	v_div_fmas_f32 v128, v128, v129, v165
	v_fmac_f32_e32 v161, v162, v161
	v_div_fixup_f32 v155, v128, v155, 1.0
	v_div_scale_f32 v163, vcc, 1.0, v156, 1.0
	v_mul_f32_e32 v164, v163, v161
	v_div_scale_f32 v128, s[2:3], v157, v157, 1.0
	v_fma_f32 v162, -v160, v164, v163
	v_rcp_f32_e32 v129, v128
	v_fmac_f32_e32 v164, v162, v161
	s_nop 0
	v_fma_f32 v160, -v160, v164, v163
	v_fma_f32 v130, -v128, v129, 1.0
	v_div_fmas_f32 v160, v160, v161, v164
	v_fmac_f32_e32 v129, v130, v129
	v_div_fixup_f32 v156, v160, v156, 1.0
	v_div_scale_f32 v131, vcc, 1.0, v157, 1.0
	v_mul_f32_e32 v165, v131, v129
	v_div_scale_f32 v160, s[2:3], v158, v158, 1.0
	v_fma_f32 v130, -v128, v165, v131
	v_rcp_f32_e32 v161, v160
	v_fmac_f32_e32 v165, v130, v129
	s_nop 0
	v_fma_f32 v128, -v128, v165, v131
	v_fma_f32 v162, -v160, v161, 1.0
	v_div_fmas_f32 v128, v128, v129, v165
	v_fmac_f32_e32 v161, v162, v161
	v_div_fixup_f32 v157, v128, v157, 1.0
	v_div_scale_f32 v163, vcc, 1.0, v158, 1.0
	v_mul_f32_e32 v164, v163, v161
	v_div_scale_f32 v128, s[2:3], v159, v159, 1.0
	v_fma_f32 v162, -v160, v164, v163
	v_rcp_f32_e32 v129, v128
	v_fmac_f32_e32 v164, v162, v161
	s_nop 0
	v_fma_f32 v160, -v160, v164, v163
	v_fma_f32 v130, -v128, v129, 1.0
	v_div_fmas_f32 v160, v160, v161, v164
	v_fmac_f32_e32 v129, v130, v129
	v_div_fixup_f32 v158, v160, v158, 1.0
	v_div_scale_f32 v131, vcc, 1.0, v159, 1.0
	v_mul_f32_e32 v165, v131, v129
	v_fma_f32 v130, -v128, v165, v131
	v_fmac_f32_e32 v165, v130, v129
	v_fma_f32 v128, -v128, v165, v131
	v_div_fmas_f32 v128, v128, v129, v165
	v_div_fixup_f32 v159, v128, v159, 1.0
	v_pk_mul_f32 v[152:153], v[116:117], v[152:153]
	v_pk_mul_f32 v[154:155], v[118:119], v[154:155]
	v_pk_mul_f32 v[156:157], v[112:113], v[156:157]
	v_pk_mul_f32 v[158:159], v[114:115], v[158:159]
	v_cvt_pk_bf16_f32 v168, v152, v153
	v_cvt_pk_bf16_f32 v169, v154, v155
	v_cvt_pk_bf16_f32 v170, v156, v157
	v_cvt_pk_bf16_f32 v171, v158, v159
	global_store_dwordx4 v184, v[168:171], s[68:69] offset:256
	global_load_dwordx4 v[116:119], v178, s[64:65] offset:256
	s_waitcnt vmcnt(5)
; __device__ __forceinline__ float sigmoidf_(float x) { return 1.f / (1.f + __expf(-x)); }
	v_lshlrev_b32_e32 v152, 16, v208
	v_and_b32_e32 v153, 0xffff0000, v208
	v_lshlrev_b32_e32 v154, 16, v209
	v_and_b32_e32 v155, 0xffff0000, v209
	v_lshlrev_b32_e32 v156, 16, v210
	v_and_b32_e32 v157, 0xffff0000, v210
	v_lshlrev_b32_e32 v158, 16, v211
	v_and_b32_e32 v159, 0xffff0000, v211
	v_mul_f32_e32 v152, 0xbfb8aa3b, v152
	v_mul_f32_e32 v153, 0xbfb8aa3b, v153
	v_mul_f32_e32 v154, 0xbfb8aa3b, v154
	v_mul_f32_e32 v155, 0xbfb8aa3b, v155
	v_mul_f32_e32 v156, 0xbfb8aa3b, v156
	v_mul_f32_e32 v157, 0xbfb8aa3b, v157
	v_mul_f32_e32 v158, 0xbfb8aa3b, v158
	v_mul_f32_e32 v159, 0xbfb8aa3b, v159
	v_exp_f32_e32 v152, v152
	v_exp_f32_e32 v153, v153
	v_exp_f32_e32 v154, v154
	v_exp_f32_e32 v155, v155
	v_exp_f32_e32 v156, v156
	v_exp_f32_e32 v157, v157
	v_exp_f32_e32 v158, v158
	v_exp_f32_e32 v159, v159
	v_pk_add_f32 v[152:153], v[152:153], 1.0 op_sel_hi:[1,0]
	v_pk_add_f32 v[154:155], v[154:155], 1.0 op_sel_hi:[1,0]
	v_pk_add_f32 v[156:157], v[156:157], 1.0 op_sel_hi:[1,0]
	v_pk_add_f32 v[158:159], v[158:159], 1.0 op_sel_hi:[1,0]
	v_div_scale_f32 v160, s[2:3], v152, v152, 1.0
	v_rcp_f32_e32 v161, v160
	s_nop 0
	v_fma_f32 v162, -v160, v161, 1.0
	v_fmac_f32_e32 v161, v162, v161
	v_div_scale_f32 v163, vcc, 1.0, v152, 1.0
	v_mul_f32_e32 v164, v163, v161
	v_div_scale_f32 v128, s[2:3], v153, v153, 1.0
	v_fma_f32 v162, -v160, v164, v163
	v_rcp_f32_e32 v129, v128
	v_fmac_f32_e32 v164, v162, v161
	s_nop 0
	v_fma_f32 v160, -v160, v164, v163
	v_fma_f32 v130, -v128, v129, 1.0
	v_div_fmas_f32 v160, v160, v161, v164
	v_fmac_f32_e32 v129, v130, v129
	v_div_fixup_f32 v152, v160, v152, 1.0
	v_div_scale_f32 v131, vcc, 1.0, v153, 1.0
	v_mul_f32_e32 v165, v131, v129
	v_div_scale_f32 v160, s[2:3], v154, v154, 1.0
	v_fma_f32 v130, -v128, v165, v131
	v_rcp_f32_e32 v161, v160
	v_fmac_f32_e32 v165, v130, v129
	s_nop 0
	v_fma_f32 v128, -v128, v165, v131
	v_fma_f32 v162, -v160, v161, 1.0
	v_div_fmas_f32 v128, v128, v129, v165
	v_fmac_f32_e32 v161, v162, v161
	v_div_fixup_f32 v153, v128, v153, 1.0
	v_div_scale_f32 v163, vcc, 1.0, v154, 1.0
	v_mul_f32_e32 v164, v163, v161
	v_div_scale_f32 v128, s[2:3], v155, v155, 1.0
	v_fma_f32 v162, -v160, v164, v163
	v_rcp_f32_e32 v129, v128
	v_fmac_f32_e32 v164, v162, v161
	s_nop 0
	v_fma_f32 v160, -v160, v164, v163
	v_fma_f32 v130, -v128, v129, 1.0
	v_div_fmas_f32 v160, v160, v161, v164
	v_fmac_f32_e32 v129, v130, v129
	v_div_fixup_f32 v154, v160, v154, 1.0
	v_div_scale_f32 v131, vcc, 1.0, v155, 1.0
	v_mul_f32_e32 v165, v131, v129
	v_div_scale_f32 v160, s[2:3], v156, v156, 1.0
	v_fma_f32 v130, -v128, v165, v131
	v_rcp_f32_e32 v161, v160
	v_fmac_f32_e32 v165, v130, v129
	s_nop 0
	v_fma_f32 v128, -v128, v165, v131
	v_fma_f32 v162, -v160, v161, 1.0
	v_div_fmas_f32 v128, v128, v129, v165
	v_fmac_f32_e32 v161, v162, v161
	v_div_fixup_f32 v155, v128, v155, 1.0
	v_div_scale_f32 v163, vcc, 1.0, v156, 1.0
	v_mul_f32_e32 v164, v163, v161
	v_div_scale_f32 v128, s[2:3], v157, v157, 1.0
	v_fma_f32 v162, -v160, v164, v163
	v_rcp_f32_e32 v129, v128
	v_fmac_f32_e32 v164, v162, v161
	s_nop 0
	v_fma_f32 v160, -v160, v164, v163
	v_fma_f32 v130, -v128, v129, 1.0
	v_div_fmas_f32 v160, v160, v161, v164
	v_fmac_f32_e32 v129, v130, v129
	v_div_fixup_f32 v156, v160, v156, 1.0
	v_div_scale_f32 v131, vcc, 1.0, v157, 1.0
	v_mul_f32_e32 v165, v131, v129
	v_div_scale_f32 v160, s[2:3], v158, v158, 1.0
	v_fma_f32 v130, -v128, v165, v131
	v_rcp_f32_e32 v161, v160
	v_fmac_f32_e32 v165, v130, v129
	s_nop 0
	v_fma_f32 v128, -v128, v165, v131
	v_fma_f32 v162, -v160, v161, 1.0
	v_div_fmas_f32 v128, v128, v129, v165
	v_fmac_f32_e32 v161, v162, v161
	v_div_fixup_f32 v157, v128, v157, 1.0
	v_div_scale_f32 v163, vcc, 1.0, v158, 1.0
	v_mul_f32_e32 v164, v163, v161
	v_div_scale_f32 v128, s[2:3], v159, v159, 1.0
	v_fma_f32 v162, -v160, v164, v163
	v_rcp_f32_e32 v129, v128
	v_fmac_f32_e32 v164, v162, v161
	s_nop 0
	v_fma_f32 v160, -v160, v164, v163
	v_fma_f32 v130, -v128, v129, 1.0
	v_div_fmas_f32 v160, v160, v161, v164
	v_fmac_f32_e32 v129, v130, v129
	v_div_fixup_f32 v158, v160, v158, 1.0
	v_div_scale_f32 v131, vcc, 1.0, v159, 1.0
	v_mul_f32_e32 v165, v131, v129
	v_fma_f32 v130, -v128, v165, v131
	v_fmac_f32_e32 v165, v130, v129
	v_fma_f32 v128, -v128, v165, v131
	v_div_fmas_f32 v128, v128, v129, v165
	v_div_fixup_f32 v159, v128, v159, 1.0
	v_pk_mul_f32 v[152:153], v[108:109], v[152:153]
	v_pk_mul_f32 v[154:155], v[110:111], v[154:155]
	v_pk_mul_f32 v[156:157], v[104:105], v[156:157]
	v_pk_mul_f32 v[158:159], v[106:107], v[158:159]
	v_cvt_pk_bf16_f32 v168, v152, v153
	v_cvt_pk_bf16_f32 v169, v154, v155
	v_cvt_pk_bf16_f32 v170, v156, v157
	v_cvt_pk_bf16_f32 v171, v158, v159
	global_store_dwordx4 v185, v[168:171], s[68:69]
	global_load_dwordx4 v[108:111], v179, s[64:65]
	s_waitcnt vmcnt(6)
; __device__ __forceinline__ float sigmoidf_(float x) { return 1.f / (1.f + __expf(-x)); }
	v_lshlrev_b32_e32 v152, 16, v216
	v_and_b32_e32 v153, 0xffff0000, v216
	v_lshlrev_b32_e32 v154, 16, v217
	v_and_b32_e32 v155, 0xffff0000, v217
	v_lshlrev_b32_e32 v156, 16, v218
	v_and_b32_e32 v157, 0xffff0000, v218
	v_lshlrev_b32_e32 v158, 16, v219
	v_and_b32_e32 v159, 0xffff0000, v219
	v_mul_f32_e32 v152, 0xbfb8aa3b, v152
	v_mul_f32_e32 v153, 0xbfb8aa3b, v153
	v_mul_f32_e32 v154, 0xbfb8aa3b, v154
	v_mul_f32_e32 v155, 0xbfb8aa3b, v155
	v_mul_f32_e32 v156, 0xbfb8aa3b, v156
	v_mul_f32_e32 v157, 0xbfb8aa3b, v157
	v_mul_f32_e32 v158, 0xbfb8aa3b, v158
	v_mul_f32_e32 v159, 0xbfb8aa3b, v159
	v_exp_f32_e32 v152, v152
	v_exp_f32_e32 v153, v153
	v_exp_f32_e32 v154, v154
	v_exp_f32_e32 v155, v155
	v_exp_f32_e32 v156, v156
	v_exp_f32_e32 v157, v157
	v_exp_f32_e32 v158, v158
	v_exp_f32_e32 v159, v159
	v_pk_add_f32 v[152:153], v[152:153], 1.0 op_sel_hi:[1,0]
	v_pk_add_f32 v[154:155], v[154:155], 1.0 op_sel_hi:[1,0]
	v_pk_add_f32 v[156:157], v[156:157], 1.0 op_sel_hi:[1,0]
	v_pk_add_f32 v[158:159], v[158:159], 1.0 op_sel_hi:[1,0]
	v_div_scale_f32 v160, s[2:3], v152, v152, 1.0
	v_rcp_f32_e32 v161, v160
	s_nop 0
	v_fma_f32 v162, -v160, v161, 1.0
	v_fmac_f32_e32 v161, v162, v161
	v_div_scale_f32 v163, vcc, 1.0, v152, 1.0
	v_mul_f32_e32 v164, v163, v161
	v_div_scale_f32 v128, s[2:3], v153, v153, 1.0
	v_fma_f32 v162, -v160, v164, v163
	v_rcp_f32_e32 v129, v128
	v_fmac_f32_e32 v164, v162, v161
	s_nop 0
	v_fma_f32 v160, -v160, v164, v163
	v_fma_f32 v130, -v128, v129, 1.0
	v_div_fmas_f32 v160, v160, v161, v164
	v_fmac_f32_e32 v129, v130, v129
	v_div_fixup_f32 v152, v160, v152, 1.0
	v_div_scale_f32 v131, vcc, 1.0, v153, 1.0
	v_mul_f32_e32 v165, v131, v129
	v_div_scale_f32 v160, s[2:3], v154, v154, 1.0
	v_fma_f32 v130, -v128, v165, v131
	v_rcp_f32_e32 v161, v160
	v_fmac_f32_e32 v165, v130, v129
	s_nop 0
	v_fma_f32 v128, -v128, v165, v131
	v_fma_f32 v162, -v160, v161, 1.0
	v_div_fmas_f32 v128, v128, v129, v165
	v_fmac_f32_e32 v161, v162, v161
	v_div_fixup_f32 v153, v128, v153, 1.0
	v_div_scale_f32 v163, vcc, 1.0, v154, 1.0
	v_mul_f32_e32 v164, v163, v161
	v_div_scale_f32 v128, s[2:3], v155, v155, 1.0
	v_fma_f32 v162, -v160, v164, v163
	v_rcp_f32_e32 v129, v128
	v_fmac_f32_e32 v164, v162, v161
	s_nop 0
	v_fma_f32 v160, -v160, v164, v163
	v_fma_f32 v130, -v128, v129, 1.0
	v_div_fmas_f32 v160, v160, v161, v164
	v_fmac_f32_e32 v129, v130, v129
	v_div_fixup_f32 v154, v160, v154, 1.0
	v_div_scale_f32 v131, vcc, 1.0, v155, 1.0
	v_mul_f32_e32 v165, v131, v129
	v_div_scale_f32 v160, s[2:3], v156, v156, 1.0
	v_fma_f32 v130, -v128, v165, v131
	v_rcp_f32_e32 v161, v160
	v_fmac_f32_e32 v165, v130, v129
	s_nop 0
	v_fma_f32 v128, -v128, v165, v131
	v_fma_f32 v162, -v160, v161, 1.0
	v_div_fmas_f32 v128, v128, v129, v165
	v_fmac_f32_e32 v161, v162, v161
	v_div_fixup_f32 v155, v128, v155, 1.0
	v_div_scale_f32 v163, vcc, 1.0, v156, 1.0
	v_mul_f32_e32 v164, v163, v161
	v_div_scale_f32 v128, s[2:3], v157, v157, 1.0
	v_fma_f32 v162, -v160, v164, v163
	v_rcp_f32_e32 v129, v128
	v_fmac_f32_e32 v164, v162, v161
	s_nop 0
	v_fma_f32 v160, -v160, v164, v163
	v_fma_f32 v130, -v128, v129, 1.0
	v_div_fmas_f32 v160, v160, v161, v164
	v_fmac_f32_e32 v129, v130, v129
	v_div_fixup_f32 v156, v160, v156, 1.0
	v_div_scale_f32 v131, vcc, 1.0, v157, 1.0
	v_mul_f32_e32 v165, v131, v129
	v_div_scale_f32 v160, s[2:3], v158, v158, 1.0
	v_fma_f32 v130, -v128, v165, v131
	v_rcp_f32_e32 v161, v160
	v_fmac_f32_e32 v165, v130, v129
	s_nop 0
	v_fma_f32 v128, -v128, v165, v131
	v_fma_f32 v162, -v160, v161, 1.0
	v_div_fmas_f32 v128, v128, v129, v165
	v_fmac_f32_e32 v161, v162, v161
	v_div_fixup_f32 v157, v128, v157, 1.0
	v_div_scale_f32 v163, vcc, 1.0, v158, 1.0
	v_mul_f32_e32 v164, v163, v161
	v_div_scale_f32 v128, s[2:3], v159, v159, 1.0
	v_fma_f32 v162, -v160, v164, v163
	v_rcp_f32_e32 v129, v128
	v_fmac_f32_e32 v164, v162, v161
	s_nop 0
	v_fma_f32 v160, -v160, v164, v163
	v_fma_f32 v130, -v128, v129, 1.0
	v_div_fmas_f32 v160, v160, v161, v164
	v_fmac_f32_e32 v129, v130, v129
	v_div_fixup_f32 v158, v160, v158, 1.0
	v_div_scale_f32 v131, vcc, 1.0, v159, 1.0
	v_mul_f32_e32 v165, v131, v129
	v_fma_f32 v130, -v128, v165, v131
	v_fmac_f32_e32 v165, v130, v129
	v_fma_f32 v128, -v128, v165, v131
	v_div_fmas_f32 v128, v128, v129, v165
	v_div_fixup_f32 v159, v128, v159, 1.0
	v_pk_mul_f32 v[152:153], v[100:101], v[152:153]
	v_pk_mul_f32 v[154:155], v[102:103], v[154:155]
	v_pk_mul_f32 v[156:157], v[96:97], v[156:157]
	v_pk_mul_f32 v[158:159], v[98:99], v[158:159]
	v_cvt_pk_bf16_f32 v168, v152, v153
	v_cvt_pk_bf16_f32 v169, v154, v155
	v_cvt_pk_bf16_f32 v170, v156, v157
	v_cvt_pk_bf16_f32 v171, v158, v159
	global_store_dwordx4 v185, v[168:171], s[68:69] offset:256
	global_load_dwordx4 v[100:103], v179, s[64:65] offset:256
	s_waitcnt vmcnt(6)
; __device__ __forceinline__ float sigmoidf_(float x) { return 1.f / (1.f + __expf(-x)); }
	v_lshlrev_b32_e32 v152, 16, v124
	v_and_b32_e32 v153, 0xffff0000, v124
	v_lshlrev_b32_e32 v154, 16, v125
	v_and_b32_e32 v155, 0xffff0000, v125
	v_lshlrev_b32_e32 v156, 16, v126
	v_and_b32_e32 v157, 0xffff0000, v126
	v_lshlrev_b32_e32 v158, 16, v127
	v_and_b32_e32 v159, 0xffff0000, v127
	v_mul_f32_e32 v152, 0xbfb8aa3b, v152
	v_mul_f32_e32 v153, 0xbfb8aa3b, v153
	v_mul_f32_e32 v154, 0xbfb8aa3b, v154
	v_mul_f32_e32 v155, 0xbfb8aa3b, v155
	v_mul_f32_e32 v156, 0xbfb8aa3b, v156
	v_mul_f32_e32 v157, 0xbfb8aa3b, v157
	v_mul_f32_e32 v158, 0xbfb8aa3b, v158
	v_mul_f32_e32 v159, 0xbfb8aa3b, v159
	v_exp_f32_e32 v152, v152
	v_exp_f32_e32 v153, v153
	v_exp_f32_e32 v154, v154
	v_exp_f32_e32 v155, v155
	v_exp_f32_e32 v156, v156
	v_exp_f32_e32 v157, v157
	v_exp_f32_e32 v158, v158
	v_exp_f32_e32 v159, v159
	v_pk_add_f32 v[152:153], v[152:153], 1.0 op_sel_hi:[1,0]
	v_pk_add_f32 v[154:155], v[154:155], 1.0 op_sel_hi:[1,0]
	v_pk_add_f32 v[156:157], v[156:157], 1.0 op_sel_hi:[1,0]
	v_pk_add_f32 v[158:159], v[158:159], 1.0 op_sel_hi:[1,0]
	v_div_scale_f32 v160, s[2:3], v152, v152, 1.0
	v_rcp_f32_e32 v161, v160
	s_nop 0
	v_fma_f32 v162, -v160, v161, 1.0
	v_fmac_f32_e32 v161, v162, v161
	v_div_scale_f32 v163, vcc, 1.0, v152, 1.0
	v_mul_f32_e32 v164, v163, v161
	v_div_scale_f32 v128, s[2:3], v153, v153, 1.0
	v_fma_f32 v162, -v160, v164, v163
	v_rcp_f32_e32 v129, v128
	v_fmac_f32_e32 v164, v162, v161
	s_nop 0
	v_fma_f32 v160, -v160, v164, v163
	v_fma_f32 v130, -v128, v129, 1.0
	v_div_fmas_f32 v160, v160, v161, v164
	v_fmac_f32_e32 v129, v130, v129
	v_div_fixup_f32 v152, v160, v152, 1.0
	v_div_scale_f32 v131, vcc, 1.0, v153, 1.0
	v_mul_f32_e32 v165, v131, v129
	v_div_scale_f32 v160, s[2:3], v154, v154, 1.0
	v_fma_f32 v130, -v128, v165, v131
	v_rcp_f32_e32 v161, v160
	v_fmac_f32_e32 v165, v130, v129
	s_nop 0
	v_fma_f32 v128, -v128, v165, v131
	v_fma_f32 v162, -v160, v161, 1.0
	v_div_fmas_f32 v128, v128, v129, v165
	v_fmac_f32_e32 v161, v162, v161
	v_div_fixup_f32 v153, v128, v153, 1.0
	v_div_scale_f32 v163, vcc, 1.0, v154, 1.0
	v_mul_f32_e32 v164, v163, v161
	v_div_scale_f32 v128, s[2:3], v155, v155, 1.0
	v_fma_f32 v162, -v160, v164, v163
	v_rcp_f32_e32 v129, v128
	v_fmac_f32_e32 v164, v162, v161
	s_nop 0
	v_fma_f32 v160, -v160, v164, v163
	v_fma_f32 v130, -v128, v129, 1.0
	v_div_fmas_f32 v160, v160, v161, v164
	v_fmac_f32_e32 v129, v130, v129
	v_div_fixup_f32 v154, v160, v154, 1.0
	v_div_scale_f32 v131, vcc, 1.0, v155, 1.0
	v_mul_f32_e32 v165, v131, v129
	v_div_scale_f32 v160, s[2:3], v156, v156, 1.0
	v_fma_f32 v130, -v128, v165, v131
	v_rcp_f32_e32 v161, v160
	v_fmac_f32_e32 v165, v130, v129
	s_nop 0
	v_fma_f32 v128, -v128, v165, v131
	v_fma_f32 v162, -v160, v161, 1.0
	v_div_fmas_f32 v128, v128, v129, v165
	v_fmac_f32_e32 v161, v162, v161
	v_div_fixup_f32 v155, v128, v155, 1.0
	v_div_scale_f32 v163, vcc, 1.0, v156, 1.0
	v_mul_f32_e32 v164, v163, v161
	v_div_scale_f32 v128, s[2:3], v157, v157, 1.0
	v_fma_f32 v162, -v160, v164, v163
	v_rcp_f32_e32 v129, v128
	v_fmac_f32_e32 v164, v162, v161
	s_nop 0
	v_fma_f32 v160, -v160, v164, v163
	v_fma_f32 v130, -v128, v129, 1.0
	v_div_fmas_f32 v160, v160, v161, v164
	v_fmac_f32_e32 v129, v130, v129
	v_div_fixup_f32 v156, v160, v156, 1.0
	v_div_scale_f32 v131, vcc, 1.0, v157, 1.0
	v_mul_f32_e32 v165, v131, v129
	v_div_scale_f32 v160, s[2:3], v158, v158, 1.0
	v_fma_f32 v130, -v128, v165, v131
	v_rcp_f32_e32 v161, v160
	v_fmac_f32_e32 v165, v130, v129
	s_nop 0
	v_fma_f32 v128, -v128, v165, v131
	v_fma_f32 v162, -v160, v161, 1.0
	v_div_fmas_f32 v128, v128, v129, v165
	v_fmac_f32_e32 v161, v162, v161
	v_div_fixup_f32 v157, v128, v157, 1.0
	v_div_scale_f32 v163, vcc, 1.0, v158, 1.0
	v_mul_f32_e32 v164, v163, v161
	v_div_scale_f32 v128, s[2:3], v159, v159, 1.0
	v_fma_f32 v162, -v160, v164, v163
	v_rcp_f32_e32 v129, v128
	v_fmac_f32_e32 v164, v162, v161
	s_nop 0
	v_fma_f32 v160, -v160, v164, v163
	v_fma_f32 v130, -v128, v129, 1.0
	v_div_fmas_f32 v160, v160, v161, v164
	v_fmac_f32_e32 v129, v130, v129
	v_div_fixup_f32 v158, v160, v158, 1.0
	v_div_scale_f32 v131, vcc, 1.0, v159, 1.0
	v_mul_f32_e32 v165, v131, v129
	v_fma_f32 v130, -v128, v165, v131
	v_fmac_f32_e32 v165, v130, v129
	v_fma_f32 v128, -v128, v165, v131
	v_div_fmas_f32 v128, v128, v129, v165
	v_div_fixup_f32 v159, v128, v159, 1.0
	v_pk_mul_f32 v[152:153], v[92:93], v[152:153]
	v_pk_mul_f32 v[154:155], v[94:95], v[154:155]
	v_pk_mul_f32 v[156:157], v[88:89], v[156:157]
	v_pk_mul_f32 v[158:159], v[90:91], v[158:159]
	v_cvt_pk_bf16_f32 v168, v152, v153
	v_cvt_pk_bf16_f32 v169, v154, v155
	v_cvt_pk_bf16_f32 v170, v156, v157
	v_cvt_pk_bf16_f32 v171, v158, v159
	global_store_dwordx4 v186, v[168:171], s[68:69]
	global_load_dwordx4 v[92:95], v180, s[64:65]
	s_waitcnt vmcnt(6)
; __device__ __forceinline__ float sigmoidf_(float x) { return 1.f / (1.f + __expf(-x)); }
	v_lshlrev_b32_e32 v152, 16, v116
	v_and_b32_e32 v153, 0xffff0000, v116
	v_lshlrev_b32_e32 v154, 16, v117
	v_and_b32_e32 v155, 0xffff0000, v117
	v_lshlrev_b32_e32 v156, 16, v118
	v_and_b32_e32 v157, 0xffff0000, v118
	v_lshlrev_b32_e32 v158, 16, v119
	v_and_b32_e32 v159, 0xffff0000, v119
	v_mul_f32_e32 v152, 0xbfb8aa3b, v152
	v_mul_f32_e32 v153, 0xbfb8aa3b, v153
	v_mul_f32_e32 v154, 0xbfb8aa3b, v154
	v_mul_f32_e32 v155, 0xbfb8aa3b, v155
	v_mul_f32_e32 v156, 0xbfb8aa3b, v156
	v_mul_f32_e32 v157, 0xbfb8aa3b, v157
	v_mul_f32_e32 v158, 0xbfb8aa3b, v158
	v_mul_f32_e32 v159, 0xbfb8aa3b, v159
	v_exp_f32_e32 v152, v152
	v_exp_f32_e32 v153, v153
	v_exp_f32_e32 v154, v154
	v_exp_f32_e32 v155, v155
	v_exp_f32_e32 v156, v156
	v_exp_f32_e32 v157, v157
	v_exp_f32_e32 v158, v158
	v_exp_f32_e32 v159, v159
	v_pk_add_f32 v[152:153], v[152:153], 1.0 op_sel_hi:[1,0]
	v_pk_add_f32 v[154:155], v[154:155], 1.0 op_sel_hi:[1,0]
	v_pk_add_f32 v[156:157], v[156:157], 1.0 op_sel_hi:[1,0]
	v_pk_add_f32 v[158:159], v[158:159], 1.0 op_sel_hi:[1,0]
	v_div_scale_f32 v160, s[2:3], v152, v152, 1.0
	v_rcp_f32_e32 v161, v160
	s_nop 0
	v_fma_f32 v162, -v160, v161, 1.0
	v_fmac_f32_e32 v161, v162, v161
	v_div_scale_f32 v163, vcc, 1.0, v152, 1.0
	v_mul_f32_e32 v164, v163, v161
	v_div_scale_f32 v128, s[2:3], v153, v153, 1.0
	v_fma_f32 v162, -v160, v164, v163
	v_rcp_f32_e32 v129, v128
	v_fmac_f32_e32 v164, v162, v161
	s_nop 0
	v_fma_f32 v160, -v160, v164, v163
	v_fma_f32 v130, -v128, v129, 1.0
	v_div_fmas_f32 v160, v160, v161, v164
	v_fmac_f32_e32 v129, v130, v129
	v_div_fixup_f32 v152, v160, v152, 1.0
	v_div_scale_f32 v131, vcc, 1.0, v153, 1.0
	v_mul_f32_e32 v165, v131, v129
	v_div_scale_f32 v160, s[2:3], v154, v154, 1.0
	v_fma_f32 v130, -v128, v165, v131
	v_rcp_f32_e32 v161, v160
	v_fmac_f32_e32 v165, v130, v129
	s_nop 0
	v_fma_f32 v128, -v128, v165, v131
	v_fma_f32 v162, -v160, v161, 1.0
	v_div_fmas_f32 v128, v128, v129, v165
	v_fmac_f32_e32 v161, v162, v161
	v_div_fixup_f32 v153, v128, v153, 1.0
	v_div_scale_f32 v163, vcc, 1.0, v154, 1.0
	v_mul_f32_e32 v164, v163, v161
	v_div_scale_f32 v128, s[2:3], v155, v155, 1.0
	v_fma_f32 v162, -v160, v164, v163
	v_rcp_f32_e32 v129, v128
	v_fmac_f32_e32 v164, v162, v161
	s_nop 0
	v_fma_f32 v160, -v160, v164, v163
	v_fma_f32 v130, -v128, v129, 1.0
	v_div_fmas_f32 v160, v160, v161, v164
	v_fmac_f32_e32 v129, v130, v129
	v_div_fixup_f32 v154, v160, v154, 1.0
	v_div_scale_f32 v131, vcc, 1.0, v155, 1.0
	v_mul_f32_e32 v165, v131, v129
	v_div_scale_f32 v160, s[2:3], v156, v156, 1.0
	v_fma_f32 v130, -v128, v165, v131
	v_rcp_f32_e32 v161, v160
	v_fmac_f32_e32 v165, v130, v129
	s_nop 0
	v_fma_f32 v128, -v128, v165, v131
	v_fma_f32 v162, -v160, v161, 1.0
	v_div_fmas_f32 v128, v128, v129, v165
	v_fmac_f32_e32 v161, v162, v161
	v_div_fixup_f32 v155, v128, v155, 1.0
	v_div_scale_f32 v163, vcc, 1.0, v156, 1.0
	v_mul_f32_e32 v164, v163, v161
	v_div_scale_f32 v128, s[2:3], v157, v157, 1.0
	v_fma_f32 v162, -v160, v164, v163
	v_rcp_f32_e32 v129, v128
	v_fmac_f32_e32 v164, v162, v161
	s_nop 0
	v_fma_f32 v160, -v160, v164, v163
	v_fma_f32 v130, -v128, v129, 1.0
	v_div_fmas_f32 v160, v160, v161, v164
	v_fmac_f32_e32 v129, v130, v129
	v_div_fixup_f32 v156, v160, v156, 1.0
	v_div_scale_f32 v131, vcc, 1.0, v157, 1.0
	v_mul_f32_e32 v165, v131, v129
	v_div_scale_f32 v160, s[2:3], v158, v158, 1.0
	v_fma_f32 v130, -v128, v165, v131
	v_rcp_f32_e32 v161, v160
	v_fmac_f32_e32 v165, v130, v129
	s_nop 0
	v_fma_f32 v128, -v128, v165, v131
	v_fma_f32 v162, -v160, v161, 1.0
	v_div_fmas_f32 v128, v128, v129, v165
	v_fmac_f32_e32 v161, v162, v161
	v_div_fixup_f32 v157, v128, v157, 1.0
	v_div_scale_f32 v163, vcc, 1.0, v158, 1.0
	v_mul_f32_e32 v164, v163, v161
	v_div_scale_f32 v128, s[2:3], v159, v159, 1.0
	v_fma_f32 v162, -v160, v164, v163
	v_rcp_f32_e32 v129, v128
	v_fmac_f32_e32 v164, v162, v161
	s_nop 0
	v_fma_f32 v160, -v160, v164, v163
	v_fma_f32 v130, -v128, v129, 1.0
	v_div_fmas_f32 v160, v160, v161, v164
	v_fmac_f32_e32 v129, v130, v129
	v_div_fixup_f32 v158, v160, v158, 1.0
	v_div_scale_f32 v131, vcc, 1.0, v159, 1.0
	v_mul_f32_e32 v165, v131, v129
	v_fma_f32 v130, -v128, v165, v131
	v_fmac_f32_e32 v165, v130, v129
	v_fma_f32 v128, -v128, v165, v131
	v_div_fmas_f32 v128, v128, v129, v165
	v_div_fixup_f32 v159, v128, v159, 1.0
	v_pk_mul_f32 v[152:153], v[84:85], v[152:153]
	v_pk_mul_f32 v[154:155], v[86:87], v[154:155]
	v_pk_mul_f32 v[156:157], v[80:81], v[156:157]
	v_pk_mul_f32 v[158:159], v[82:83], v[158:159]
	v_cvt_pk_bf16_f32 v168, v152, v153
	v_cvt_pk_bf16_f32 v169, v154, v155
	v_cvt_pk_bf16_f32 v170, v156, v157
	v_cvt_pk_bf16_f32 v171, v158, v159
	global_store_dwordx4 v186, v[168:171], s[68:69] offset:256
	global_load_dwordx4 v[84:87], v180, s[64:65] offset:256
	s_waitcnt vmcnt(6)
; __device__ __forceinline__ float sigmoidf_(float x) { return 1.f / (1.f + __expf(-x)); }
	v_lshlrev_b32_e32 v152, 16, v108
	v_and_b32_e32 v153, 0xffff0000, v108
	v_lshlrev_b32_e32 v154, 16, v109
	v_and_b32_e32 v155, 0xffff0000, v109
	v_lshlrev_b32_e32 v156, 16, v110
	v_and_b32_e32 v157, 0xffff0000, v110
	v_lshlrev_b32_e32 v158, 16, v111
	v_and_b32_e32 v159, 0xffff0000, v111
	v_mul_f32_e32 v152, 0xbfb8aa3b, v152
	v_mul_f32_e32 v153, 0xbfb8aa3b, v153
	v_mul_f32_e32 v154, 0xbfb8aa3b, v154
	v_mul_f32_e32 v155, 0xbfb8aa3b, v155
	v_mul_f32_e32 v156, 0xbfb8aa3b, v156
	v_mul_f32_e32 v157, 0xbfb8aa3b, v157
	v_mul_f32_e32 v158, 0xbfb8aa3b, v158
	v_mul_f32_e32 v159, 0xbfb8aa3b, v159
	v_exp_f32_e32 v152, v152
	v_exp_f32_e32 v153, v153
	v_exp_f32_e32 v154, v154
	v_exp_f32_e32 v155, v155
	v_exp_f32_e32 v156, v156
	v_exp_f32_e32 v157, v157
	v_exp_f32_e32 v158, v158
	v_exp_f32_e32 v159, v159
	v_pk_add_f32 v[152:153], v[152:153], 1.0 op_sel_hi:[1,0]
	v_pk_add_f32 v[154:155], v[154:155], 1.0 op_sel_hi:[1,0]
	v_pk_add_f32 v[156:157], v[156:157], 1.0 op_sel_hi:[1,0]
	v_pk_add_f32 v[158:159], v[158:159], 1.0 op_sel_hi:[1,0]
	v_div_scale_f32 v160, s[2:3], v152, v152, 1.0
	v_rcp_f32_e32 v161, v160
	s_nop 0
	v_fma_f32 v162, -v160, v161, 1.0
	v_fmac_f32_e32 v161, v162, v161
	v_div_scale_f32 v163, vcc, 1.0, v152, 1.0
	v_mul_f32_e32 v164, v163, v161
	v_div_scale_f32 v128, s[2:3], v153, v153, 1.0
	v_fma_f32 v162, -v160, v164, v163
	v_rcp_f32_e32 v129, v128
	v_fmac_f32_e32 v164, v162, v161
	s_nop 0
	v_fma_f32 v160, -v160, v164, v163
	v_fma_f32 v130, -v128, v129, 1.0
	v_div_fmas_f32 v160, v160, v161, v164
	v_fmac_f32_e32 v129, v130, v129
	v_div_fixup_f32 v152, v160, v152, 1.0
	v_div_scale_f32 v131, vcc, 1.0, v153, 1.0
	v_mul_f32_e32 v165, v131, v129
	v_div_scale_f32 v160, s[2:3], v154, v154, 1.0
	v_fma_f32 v130, -v128, v165, v131
	v_rcp_f32_e32 v161, v160
	v_fmac_f32_e32 v165, v130, v129
	s_nop 0
	v_fma_f32 v128, -v128, v165, v131
	v_fma_f32 v162, -v160, v161, 1.0
	v_div_fmas_f32 v128, v128, v129, v165
	v_fmac_f32_e32 v161, v162, v161
	v_div_fixup_f32 v153, v128, v153, 1.0
	v_div_scale_f32 v163, vcc, 1.0, v154, 1.0
	v_mul_f32_e32 v164, v163, v161
	v_div_scale_f32 v128, s[2:3], v155, v155, 1.0
	v_fma_f32 v162, -v160, v164, v163
	v_rcp_f32_e32 v129, v128
	v_fmac_f32_e32 v164, v162, v161
	s_nop 0
	v_fma_f32 v160, -v160, v164, v163
	v_fma_f32 v130, -v128, v129, 1.0
	v_div_fmas_f32 v160, v160, v161, v164
	v_fmac_f32_e32 v129, v130, v129
	v_div_fixup_f32 v154, v160, v154, 1.0
	v_div_scale_f32 v131, vcc, 1.0, v155, 1.0
	v_mul_f32_e32 v165, v131, v129
	v_div_scale_f32 v160, s[2:3], v156, v156, 1.0
	v_fma_f32 v130, -v128, v165, v131
	v_rcp_f32_e32 v161, v160
	v_fmac_f32_e32 v165, v130, v129
	s_nop 0
	v_fma_f32 v128, -v128, v165, v131
	v_fma_f32 v162, -v160, v161, 1.0
	v_div_fmas_f32 v128, v128, v129, v165
	v_fmac_f32_e32 v161, v162, v161
	v_div_fixup_f32 v155, v128, v155, 1.0
	v_div_scale_f32 v163, vcc, 1.0, v156, 1.0
	v_mul_f32_e32 v164, v163, v161
	v_div_scale_f32 v128, s[2:3], v157, v157, 1.0
	v_fma_f32 v162, -v160, v164, v163
	v_rcp_f32_e32 v129, v128
	v_fmac_f32_e32 v164, v162, v161
	s_nop 0
	v_fma_f32 v160, -v160, v164, v163
	v_fma_f32 v130, -v128, v129, 1.0
	v_div_fmas_f32 v160, v160, v161, v164
	v_fmac_f32_e32 v129, v130, v129
	v_div_fixup_f32 v156, v160, v156, 1.0
	v_div_scale_f32 v131, vcc, 1.0, v157, 1.0
	v_mul_f32_e32 v165, v131, v129
	v_div_scale_f32 v160, s[2:3], v158, v158, 1.0
	v_fma_f32 v130, -v128, v165, v131
	v_rcp_f32_e32 v161, v160
	v_fmac_f32_e32 v165, v130, v129
	s_nop 0
	v_fma_f32 v128, -v128, v165, v131
	v_fma_f32 v162, -v160, v161, 1.0
	v_div_fmas_f32 v128, v128, v129, v165
	v_fmac_f32_e32 v161, v162, v161
	v_div_fixup_f32 v157, v128, v157, 1.0
	v_div_scale_f32 v163, vcc, 1.0, v158, 1.0
	v_mul_f32_e32 v164, v163, v161
	v_div_scale_f32 v128, s[2:3], v159, v159, 1.0
	v_fma_f32 v162, -v160, v164, v163
	v_rcp_f32_e32 v129, v128
	v_fmac_f32_e32 v164, v162, v161
	s_nop 0
	v_fma_f32 v160, -v160, v164, v163
	v_fma_f32 v130, -v128, v129, 1.0
	v_div_fmas_f32 v160, v160, v161, v164
	v_fmac_f32_e32 v129, v130, v129
	v_div_fixup_f32 v158, v160, v158, 1.0
	v_div_scale_f32 v131, vcc, 1.0, v159, 1.0
	v_mul_f32_e32 v165, v131, v129
	v_fma_f32 v130, -v128, v165, v131
	v_fmac_f32_e32 v165, v130, v129
	v_fma_f32 v128, -v128, v165, v131
	v_div_fmas_f32 v128, v128, v129, v165
	v_div_fixup_f32 v159, v128, v159, 1.0
	v_pk_mul_f32 v[152:153], v[76:77], v[152:153]
	v_pk_mul_f32 v[154:155], v[78:79], v[154:155]
	v_pk_mul_f32 v[156:157], v[72:73], v[156:157]
	v_pk_mul_f32 v[158:159], v[74:75], v[158:159]
	v_cvt_pk_bf16_f32 v168, v152, v153
	v_cvt_pk_bf16_f32 v169, v154, v155
	v_cvt_pk_bf16_f32 v170, v156, v157
	v_cvt_pk_bf16_f32 v171, v158, v159
	global_store_dwordx4 v187, v[168:171], s[68:69]
	global_load_dwordx4 v[76:79], v181, s[64:65]
	s_waitcnt vmcnt(6)
; __device__ __forceinline__ float sigmoidf_(float x) { return 1.f / (1.f + __expf(-x)); }
	v_lshlrev_b32_e32 v152, 16, v100
	v_and_b32_e32 v153, 0xffff0000, v100
	v_lshlrev_b32_e32 v154, 16, v101
	v_and_b32_e32 v155, 0xffff0000, v101
	v_lshlrev_b32_e32 v156, 16, v102
	v_and_b32_e32 v157, 0xffff0000, v102
	v_lshlrev_b32_e32 v158, 16, v103
	v_and_b32_e32 v159, 0xffff0000, v103
	v_mul_f32_e32 v152, 0xbfb8aa3b, v152
	v_mul_f32_e32 v153, 0xbfb8aa3b, v153
	v_mul_f32_e32 v154, 0xbfb8aa3b, v154
	v_mul_f32_e32 v155, 0xbfb8aa3b, v155
	v_mul_f32_e32 v156, 0xbfb8aa3b, v156
	v_mul_f32_e32 v157, 0xbfb8aa3b, v157
	v_mul_f32_e32 v158, 0xbfb8aa3b, v158
	v_mul_f32_e32 v159, 0xbfb8aa3b, v159
	v_exp_f32_e32 v152, v152
	v_exp_f32_e32 v153, v153
	v_exp_f32_e32 v154, v154
	v_exp_f32_e32 v155, v155
	v_exp_f32_e32 v156, v156
	v_exp_f32_e32 v157, v157
	v_exp_f32_e32 v158, v158
	v_exp_f32_e32 v159, v159
	v_pk_add_f32 v[152:153], v[152:153], 1.0 op_sel_hi:[1,0]
	v_pk_add_f32 v[154:155], v[154:155], 1.0 op_sel_hi:[1,0]
	v_pk_add_f32 v[156:157], v[156:157], 1.0 op_sel_hi:[1,0]
	v_pk_add_f32 v[158:159], v[158:159], 1.0 op_sel_hi:[1,0]
	v_div_scale_f32 v160, s[2:3], v152, v152, 1.0
	v_rcp_f32_e32 v161, v160
	s_nop 0
	v_fma_f32 v162, -v160, v161, 1.0
	v_fmac_f32_e32 v161, v162, v161
	v_div_scale_f32 v163, vcc, 1.0, v152, 1.0
	v_mul_f32_e32 v164, v163, v161
	v_div_scale_f32 v128, s[2:3], v153, v153, 1.0
	v_fma_f32 v162, -v160, v164, v163
	v_rcp_f32_e32 v129, v128
	v_fmac_f32_e32 v164, v162, v161
	s_nop 0
	v_fma_f32 v160, -v160, v164, v163
	v_fma_f32 v130, -v128, v129, 1.0
	v_div_fmas_f32 v160, v160, v161, v164
	v_fmac_f32_e32 v129, v130, v129
	v_div_fixup_f32 v152, v160, v152, 1.0
	v_div_scale_f32 v131, vcc, 1.0, v153, 1.0
	v_mul_f32_e32 v165, v131, v129
	v_div_scale_f32 v160, s[2:3], v154, v154, 1.0
	v_fma_f32 v130, -v128, v165, v131
	v_rcp_f32_e32 v161, v160
	v_fmac_f32_e32 v165, v130, v129
	s_nop 0
	v_fma_f32 v128, -v128, v165, v131
	v_fma_f32 v162, -v160, v161, 1.0
	v_div_fmas_f32 v128, v128, v129, v165
	v_fmac_f32_e32 v161, v162, v161
	v_div_fixup_f32 v153, v128, v153, 1.0
	v_div_scale_f32 v163, vcc, 1.0, v154, 1.0
	v_mul_f32_e32 v164, v163, v161
	v_div_scale_f32 v128, s[2:3], v155, v155, 1.0
	v_fma_f32 v162, -v160, v164, v163
	v_rcp_f32_e32 v129, v128
	v_fmac_f32_e32 v164, v162, v161
	s_nop 0
	v_fma_f32 v160, -v160, v164, v163
	v_fma_f32 v130, -v128, v129, 1.0
	v_div_fmas_f32 v160, v160, v161, v164
	v_fmac_f32_e32 v129, v130, v129
	v_div_fixup_f32 v154, v160, v154, 1.0
	v_div_scale_f32 v131, vcc, 1.0, v155, 1.0
	v_mul_f32_e32 v165, v131, v129
	v_div_scale_f32 v160, s[2:3], v156, v156, 1.0
	v_fma_f32 v130, -v128, v165, v131
	v_rcp_f32_e32 v161, v160
	v_fmac_f32_e32 v165, v130, v129
	s_nop 0
	v_fma_f32 v128, -v128, v165, v131
	v_fma_f32 v162, -v160, v161, 1.0
	v_div_fmas_f32 v128, v128, v129, v165
	v_fmac_f32_e32 v161, v162, v161
	v_div_fixup_f32 v155, v128, v155, 1.0
	v_div_scale_f32 v163, vcc, 1.0, v156, 1.0
	v_mul_f32_e32 v164, v163, v161
	v_div_scale_f32 v128, s[2:3], v157, v157, 1.0
	v_fma_f32 v162, -v160, v164, v163
	v_rcp_f32_e32 v129, v128
	v_fmac_f32_e32 v164, v162, v161
	s_nop 0
	v_fma_f32 v160, -v160, v164, v163
	v_fma_f32 v130, -v128, v129, 1.0
	v_div_fmas_f32 v160, v160, v161, v164
	v_fmac_f32_e32 v129, v130, v129
	v_div_fixup_f32 v156, v160, v156, 1.0
	v_div_scale_f32 v131, vcc, 1.0, v157, 1.0
	v_mul_f32_e32 v165, v131, v129
	v_div_scale_f32 v160, s[2:3], v158, v158, 1.0
	v_fma_f32 v130, -v128, v165, v131
	v_rcp_f32_e32 v161, v160
	v_fmac_f32_e32 v165, v130, v129
	s_nop 0
	v_fma_f32 v128, -v128, v165, v131
	v_fma_f32 v162, -v160, v161, 1.0
	v_div_fmas_f32 v128, v128, v129, v165
	v_fmac_f32_e32 v161, v162, v161
	v_div_fixup_f32 v157, v128, v157, 1.0
	v_div_scale_f32 v163, vcc, 1.0, v158, 1.0
	v_mul_f32_e32 v164, v163, v161
	v_div_scale_f32 v128, s[2:3], v159, v159, 1.0
	v_fma_f32 v162, -v160, v164, v163
	v_rcp_f32_e32 v129, v128
	v_fmac_f32_e32 v164, v162, v161
	s_nop 0
	v_fma_f32 v160, -v160, v164, v163
	v_fma_f32 v130, -v128, v129, 1.0
	v_div_fmas_f32 v160, v160, v161, v164
	v_fmac_f32_e32 v129, v130, v129
	v_div_fixup_f32 v158, v160, v158, 1.0
	v_div_scale_f32 v131, vcc, 1.0, v159, 1.0
	v_mul_f32_e32 v165, v131, v129
	v_fma_f32 v130, -v128, v165, v131
	v_fmac_f32_e32 v165, v130, v129
	v_fma_f32 v128, -v128, v165, v131
	v_div_fmas_f32 v128, v128, v129, v165
	v_div_fixup_f32 v159, v128, v159, 1.0
	v_pk_mul_f32 v[152:153], v[68:69], v[152:153]
	v_pk_mul_f32 v[154:155], v[70:71], v[154:155]
	v_pk_mul_f32 v[156:157], v[64:65], v[156:157]
	v_pk_mul_f32 v[158:159], v[66:67], v[158:159]
	v_cvt_pk_bf16_f32 v168, v152, v153
	v_cvt_pk_bf16_f32 v169, v154, v155
	v_cvt_pk_bf16_f32 v170, v156, v157
	v_cvt_pk_bf16_f32 v171, v158, v159
	global_store_dwordx4 v187, v[168:171], s[68:69] offset:256
	global_load_dwordx4 v[68:71], v181, s[64:65] offset:256
	s_waitcnt vmcnt(6)
; __device__ __forceinline__ float sigmoidf_(float x) { return 1.f / (1.f + __expf(-x)); }
	v_lshlrev_b32_e32 v152, 16, v92
	v_and_b32_e32 v153, 0xffff0000, v92
	v_lshlrev_b32_e32 v154, 16, v93
	v_and_b32_e32 v155, 0xffff0000, v93
	v_lshlrev_b32_e32 v156, 16, v94
	v_and_b32_e32 v157, 0xffff0000, v94
	v_lshlrev_b32_e32 v158, 16, v95
	v_and_b32_e32 v159, 0xffff0000, v95
	v_mul_f32_e32 v152, 0xbfb8aa3b, v152
	v_mul_f32_e32 v153, 0xbfb8aa3b, v153
	v_mul_f32_e32 v154, 0xbfb8aa3b, v154
	v_mul_f32_e32 v155, 0xbfb8aa3b, v155
	v_mul_f32_e32 v156, 0xbfb8aa3b, v156
	v_mul_f32_e32 v157, 0xbfb8aa3b, v157
	v_mul_f32_e32 v158, 0xbfb8aa3b, v158
	v_mul_f32_e32 v159, 0xbfb8aa3b, v159
	v_exp_f32_e32 v152, v152
	v_exp_f32_e32 v153, v153
	v_exp_f32_e32 v154, v154
	v_exp_f32_e32 v155, v155
	v_exp_f32_e32 v156, v156
	v_exp_f32_e32 v157, v157
	v_exp_f32_e32 v158, v158
	v_exp_f32_e32 v159, v159
	v_pk_add_f32 v[152:153], v[152:153], 1.0 op_sel_hi:[1,0]
	v_pk_add_f32 v[154:155], v[154:155], 1.0 op_sel_hi:[1,0]
	v_pk_add_f32 v[156:157], v[156:157], 1.0 op_sel_hi:[1,0]
	v_pk_add_f32 v[158:159], v[158:159], 1.0 op_sel_hi:[1,0]
	v_div_scale_f32 v160, s[2:3], v152, v152, 1.0
	v_rcp_f32_e32 v161, v160
	s_nop 0
	v_fma_f32 v162, -v160, v161, 1.0
	v_fmac_f32_e32 v161, v162, v161
	v_div_scale_f32 v163, vcc, 1.0, v152, 1.0
	v_mul_f32_e32 v164, v163, v161
	v_div_scale_f32 v128, s[2:3], v153, v153, 1.0
	v_fma_f32 v162, -v160, v164, v163
	v_rcp_f32_e32 v129, v128
	v_fmac_f32_e32 v164, v162, v161
	s_nop 0
	v_fma_f32 v160, -v160, v164, v163
	v_fma_f32 v130, -v128, v129, 1.0
	v_div_fmas_f32 v160, v160, v161, v164
	v_fmac_f32_e32 v129, v130, v129
	v_div_fixup_f32 v152, v160, v152, 1.0
	v_div_scale_f32 v131, vcc, 1.0, v153, 1.0
	v_mul_f32_e32 v165, v131, v129
	v_div_scale_f32 v160, s[2:3], v154, v154, 1.0
	v_fma_f32 v130, -v128, v165, v131
	v_rcp_f32_e32 v161, v160
	v_fmac_f32_e32 v165, v130, v129
	s_nop 0
	v_fma_f32 v128, -v128, v165, v131
	v_fma_f32 v162, -v160, v161, 1.0
	v_div_fmas_f32 v128, v128, v129, v165
	v_fmac_f32_e32 v161, v162, v161
	v_div_fixup_f32 v153, v128, v153, 1.0
	v_div_scale_f32 v163, vcc, 1.0, v154, 1.0
	v_mul_f32_e32 v164, v163, v161
	v_div_scale_f32 v128, s[2:3], v155, v155, 1.0
	v_fma_f32 v162, -v160, v164, v163
	v_rcp_f32_e32 v129, v128
	v_fmac_f32_e32 v164, v162, v161
	s_nop 0
	v_fma_f32 v160, -v160, v164, v163
	v_fma_f32 v130, -v128, v129, 1.0
	v_div_fmas_f32 v160, v160, v161, v164
	v_fmac_f32_e32 v129, v130, v129
	v_div_fixup_f32 v154, v160, v154, 1.0
	v_div_scale_f32 v131, vcc, 1.0, v155, 1.0
	v_mul_f32_e32 v165, v131, v129
	v_div_scale_f32 v160, s[2:3], v156, v156, 1.0
	v_fma_f32 v130, -v128, v165, v131
	v_rcp_f32_e32 v161, v160
	v_fmac_f32_e32 v165, v130, v129
	s_nop 0
	v_fma_f32 v128, -v128, v165, v131
	v_fma_f32 v162, -v160, v161, 1.0
	v_div_fmas_f32 v128, v128, v129, v165
	v_fmac_f32_e32 v161, v162, v161
	v_div_fixup_f32 v155, v128, v155, 1.0
	v_div_scale_f32 v163, vcc, 1.0, v156, 1.0
	v_mul_f32_e32 v164, v163, v161
	v_div_scale_f32 v128, s[2:3], v157, v157, 1.0
	v_fma_f32 v162, -v160, v164, v163
	v_rcp_f32_e32 v129, v128
	v_fmac_f32_e32 v164, v162, v161
	s_nop 0
	v_fma_f32 v160, -v160, v164, v163
	v_fma_f32 v130, -v128, v129, 1.0
	v_div_fmas_f32 v160, v160, v161, v164
	v_fmac_f32_e32 v129, v130, v129
	v_div_fixup_f32 v156, v160, v156, 1.0
	v_div_scale_f32 v131, vcc, 1.0, v157, 1.0
	v_mul_f32_e32 v165, v131, v129
	v_div_scale_f32 v160, s[2:3], v158, v158, 1.0
	v_fma_f32 v130, -v128, v165, v131
	v_rcp_f32_e32 v161, v160
	v_fmac_f32_e32 v165, v130, v129
	s_nop 0
	v_fma_f32 v128, -v128, v165, v131
	v_fma_f32 v162, -v160, v161, 1.0
	v_div_fmas_f32 v128, v128, v129, v165
	v_fmac_f32_e32 v161, v162, v161
	v_div_fixup_f32 v157, v128, v157, 1.0
	v_div_scale_f32 v163, vcc, 1.0, v158, 1.0
	v_mul_f32_e32 v164, v163, v161
	v_div_scale_f32 v128, s[2:3], v159, v159, 1.0
	v_fma_f32 v162, -v160, v164, v163
	v_rcp_f32_e32 v129, v128
	v_fmac_f32_e32 v164, v162, v161
	s_nop 0
	v_fma_f32 v160, -v160, v164, v163
	v_fma_f32 v130, -v128, v129, 1.0
	v_div_fmas_f32 v160, v160, v161, v164
	v_fmac_f32_e32 v129, v130, v129
	v_div_fixup_f32 v158, v160, v158, 1.0
	v_div_scale_f32 v131, vcc, 1.0, v159, 1.0
	v_mul_f32_e32 v165, v131, v129
	v_fma_f32 v130, -v128, v165, v131
	v_fmac_f32_e32 v165, v130, v129
	v_fma_f32 v128, -v128, v165, v131
	v_div_fmas_f32 v128, v128, v129, v165
	v_div_fixup_f32 v159, v128, v159, 1.0
	v_pk_mul_f32 v[152:153], v[60:61], v[152:153]
	v_pk_mul_f32 v[154:155], v[62:63], v[154:155]
	v_pk_mul_f32 v[156:157], v[56:57], v[156:157]
	v_pk_mul_f32 v[158:159], v[58:59], v[158:159]
	v_cvt_pk_bf16_f32 v168, v152, v153
	v_cvt_pk_bf16_f32 v169, v154, v155
	v_cvt_pk_bf16_f32 v170, v156, v157
	v_cvt_pk_bf16_f32 v171, v158, v159
	global_store_dwordx4 v188, v[168:171], s[68:69]
	global_load_dwordx4 v[60:63], v182, s[64:65]
	s_waitcnt vmcnt(6)
; __device__ __forceinline__ float sigmoidf_(float x) { return 1.f / (1.f + __expf(-x)); }
	v_lshlrev_b32_e32 v152, 16, v84
	v_and_b32_e32 v153, 0xffff0000, v84
	v_lshlrev_b32_e32 v154, 16, v85
	v_and_b32_e32 v155, 0xffff0000, v85
	v_lshlrev_b32_e32 v156, 16, v86
	v_and_b32_e32 v157, 0xffff0000, v86
	v_lshlrev_b32_e32 v158, 16, v87
	v_and_b32_e32 v159, 0xffff0000, v87
	v_mul_f32_e32 v152, 0xbfb8aa3b, v152
	v_mul_f32_e32 v153, 0xbfb8aa3b, v153
	v_mul_f32_e32 v154, 0xbfb8aa3b, v154
	v_mul_f32_e32 v155, 0xbfb8aa3b, v155
	v_mul_f32_e32 v156, 0xbfb8aa3b, v156
	v_mul_f32_e32 v157, 0xbfb8aa3b, v157
	v_mul_f32_e32 v158, 0xbfb8aa3b, v158
	v_mul_f32_e32 v159, 0xbfb8aa3b, v159
	v_exp_f32_e32 v152, v152
	v_exp_f32_e32 v153, v153
	v_exp_f32_e32 v154, v154
	v_exp_f32_e32 v155, v155
	v_exp_f32_e32 v156, v156
	v_exp_f32_e32 v157, v157
	v_exp_f32_e32 v158, v158
	v_exp_f32_e32 v159, v159
	v_pk_add_f32 v[152:153], v[152:153], 1.0 op_sel_hi:[1,0]
	v_pk_add_f32 v[154:155], v[154:155], 1.0 op_sel_hi:[1,0]
	v_pk_add_f32 v[156:157], v[156:157], 1.0 op_sel_hi:[1,0]
	v_pk_add_f32 v[158:159], v[158:159], 1.0 op_sel_hi:[1,0]
	v_div_scale_f32 v160, s[2:3], v152, v152, 1.0
	v_rcp_f32_e32 v161, v160
	s_nop 0
	v_fma_f32 v162, -v160, v161, 1.0
	v_fmac_f32_e32 v161, v162, v161
	v_div_scale_f32 v163, vcc, 1.0, v152, 1.0
	v_mul_f32_e32 v164, v163, v161
	v_div_scale_f32 v128, s[2:3], v153, v153, 1.0
	v_fma_f32 v162, -v160, v164, v163
	v_rcp_f32_e32 v129, v128
	v_fmac_f32_e32 v164, v162, v161
	s_nop 0
	v_fma_f32 v160, -v160, v164, v163
	v_fma_f32 v130, -v128, v129, 1.0
	v_div_fmas_f32 v160, v160, v161, v164
	v_fmac_f32_e32 v129, v130, v129
	v_div_fixup_f32 v152, v160, v152, 1.0
	v_div_scale_f32 v131, vcc, 1.0, v153, 1.0
	v_mul_f32_e32 v165, v131, v129
	v_div_scale_f32 v160, s[2:3], v154, v154, 1.0
	v_fma_f32 v130, -v128, v165, v131
	v_rcp_f32_e32 v161, v160
	v_fmac_f32_e32 v165, v130, v129
	s_nop 0
	v_fma_f32 v128, -v128, v165, v131
	v_fma_f32 v162, -v160, v161, 1.0
	v_div_fmas_f32 v128, v128, v129, v165
	v_fmac_f32_e32 v161, v162, v161
	v_div_fixup_f32 v153, v128, v153, 1.0
	v_div_scale_f32 v163, vcc, 1.0, v154, 1.0
	v_mul_f32_e32 v164, v163, v161
	v_div_scale_f32 v128, s[2:3], v155, v155, 1.0
	v_fma_f32 v162, -v160, v164, v163
	v_rcp_f32_e32 v129, v128
	v_fmac_f32_e32 v164, v162, v161
	s_nop 0
	v_fma_f32 v160, -v160, v164, v163
	v_fma_f32 v130, -v128, v129, 1.0
	v_div_fmas_f32 v160, v160, v161, v164
	v_fmac_f32_e32 v129, v130, v129
	v_div_fixup_f32 v154, v160, v154, 1.0
	v_div_scale_f32 v131, vcc, 1.0, v155, 1.0
	v_mul_f32_e32 v165, v131, v129
	v_div_scale_f32 v160, s[2:3], v156, v156, 1.0
	v_fma_f32 v130, -v128, v165, v131
	v_rcp_f32_e32 v161, v160
	v_fmac_f32_e32 v165, v130, v129
	s_nop 0
	v_fma_f32 v128, -v128, v165, v131
	v_fma_f32 v162, -v160, v161, 1.0
	v_div_fmas_f32 v128, v128, v129, v165
	v_fmac_f32_e32 v161, v162, v161
	v_div_fixup_f32 v155, v128, v155, 1.0
	v_div_scale_f32 v163, vcc, 1.0, v156, 1.0
	v_mul_f32_e32 v164, v163, v161
	v_div_scale_f32 v128, s[2:3], v157, v157, 1.0
	v_fma_f32 v162, -v160, v164, v163
	v_rcp_f32_e32 v129, v128
	v_fmac_f32_e32 v164, v162, v161
	s_nop 0
	v_fma_f32 v160, -v160, v164, v163
	v_fma_f32 v130, -v128, v129, 1.0
	v_div_fmas_f32 v160, v160, v161, v164
	v_fmac_f32_e32 v129, v130, v129
	v_div_fixup_f32 v156, v160, v156, 1.0
	v_div_scale_f32 v131, vcc, 1.0, v157, 1.0
	v_mul_f32_e32 v165, v131, v129
	v_div_scale_f32 v160, s[2:3], v158, v158, 1.0
	v_fma_f32 v130, -v128, v165, v131
	v_rcp_f32_e32 v161, v160
	v_fmac_f32_e32 v165, v130, v129
	s_nop 0
	v_fma_f32 v128, -v128, v165, v131
	v_fma_f32 v162, -v160, v161, 1.0
	v_div_fmas_f32 v128, v128, v129, v165
	v_fmac_f32_e32 v161, v162, v161
	v_div_fixup_f32 v157, v128, v157, 1.0
	v_div_scale_f32 v163, vcc, 1.0, v158, 1.0
	v_mul_f32_e32 v164, v163, v161
	v_div_scale_f32 v128, s[2:3], v159, v159, 1.0
	v_fma_f32 v162, -v160, v164, v163
	v_rcp_f32_e32 v129, v128
	v_fmac_f32_e32 v164, v162, v161
	s_nop 0
	v_fma_f32 v160, -v160, v164, v163
	v_fma_f32 v130, -v128, v129, 1.0
	v_div_fmas_f32 v160, v160, v161, v164
	v_fmac_f32_e32 v129, v130, v129
	v_div_fixup_f32 v158, v160, v158, 1.0
	v_div_scale_f32 v131, vcc, 1.0, v159, 1.0
	v_mul_f32_e32 v165, v131, v129
	v_fma_f32 v130, -v128, v165, v131
	v_fmac_f32_e32 v165, v130, v129
	v_fma_f32 v128, -v128, v165, v131
	v_div_fmas_f32 v128, v128, v129, v165
	v_div_fixup_f32 v159, v128, v159, 1.0
	v_pk_mul_f32 v[152:153], v[52:53], v[152:153]
	v_pk_mul_f32 v[154:155], v[54:55], v[154:155]
	v_pk_mul_f32 v[156:157], v[48:49], v[156:157]
	v_pk_mul_f32 v[158:159], v[50:51], v[158:159]
	v_cvt_pk_bf16_f32 v168, v152, v153
	v_cvt_pk_bf16_f32 v169, v154, v155
	v_cvt_pk_bf16_f32 v170, v156, v157
	v_cvt_pk_bf16_f32 v171, v158, v159
	global_store_dwordx4 v188, v[168:171], s[68:69] offset:256
	global_load_dwordx4 v[52:55], v182, s[64:65] offset:256
	s_waitcnt vmcnt(6)
; __device__ __forceinline__ float sigmoidf_(float x) { return 1.f / (1.f + __expf(-x)); }
	v_lshlrev_b32_e32 v152, 16, v76
	v_and_b32_e32 v153, 0xffff0000, v76
	v_lshlrev_b32_e32 v154, 16, v77
	v_and_b32_e32 v155, 0xffff0000, v77
	v_lshlrev_b32_e32 v156, 16, v78
	v_and_b32_e32 v157, 0xffff0000, v78
	v_lshlrev_b32_e32 v158, 16, v79
	v_and_b32_e32 v159, 0xffff0000, v79
	v_mul_f32_e32 v152, 0xbfb8aa3b, v152
	v_mul_f32_e32 v153, 0xbfb8aa3b, v153
	v_mul_f32_e32 v154, 0xbfb8aa3b, v154
	v_mul_f32_e32 v155, 0xbfb8aa3b, v155
	v_mul_f32_e32 v156, 0xbfb8aa3b, v156
	v_mul_f32_e32 v157, 0xbfb8aa3b, v157
	v_mul_f32_e32 v158, 0xbfb8aa3b, v158
	v_mul_f32_e32 v159, 0xbfb8aa3b, v159
	v_exp_f32_e32 v152, v152
	v_exp_f32_e32 v153, v153
	v_exp_f32_e32 v154, v154
	v_exp_f32_e32 v155, v155
	v_exp_f32_e32 v156, v156
	v_exp_f32_e32 v157, v157
	v_exp_f32_e32 v158, v158
	v_exp_f32_e32 v159, v159
	v_pk_add_f32 v[152:153], v[152:153], 1.0 op_sel_hi:[1,0]
	v_pk_add_f32 v[154:155], v[154:155], 1.0 op_sel_hi:[1,0]
	v_pk_add_f32 v[156:157], v[156:157], 1.0 op_sel_hi:[1,0]
	v_pk_add_f32 v[158:159], v[158:159], 1.0 op_sel_hi:[1,0]
	v_div_scale_f32 v160, s[2:3], v152, v152, 1.0
	v_rcp_f32_e32 v161, v160
	s_nop 0
	v_fma_f32 v162, -v160, v161, 1.0
	v_fmac_f32_e32 v161, v162, v161
	v_div_scale_f32 v163, vcc, 1.0, v152, 1.0
	v_mul_f32_e32 v164, v163, v161
	v_div_scale_f32 v128, s[2:3], v153, v153, 1.0
	v_fma_f32 v162, -v160, v164, v163
	v_rcp_f32_e32 v129, v128
	v_fmac_f32_e32 v164, v162, v161
	s_nop 0
	v_fma_f32 v160, -v160, v164, v163
	v_fma_f32 v130, -v128, v129, 1.0
	v_div_fmas_f32 v160, v160, v161, v164
	v_fmac_f32_e32 v129, v130, v129
	v_div_fixup_f32 v152, v160, v152, 1.0
	v_div_scale_f32 v131, vcc, 1.0, v153, 1.0
	v_mul_f32_e32 v165, v131, v129
	v_div_scale_f32 v160, s[2:3], v154, v154, 1.0
	v_fma_f32 v130, -v128, v165, v131
	v_rcp_f32_e32 v161, v160
	v_fmac_f32_e32 v165, v130, v129
	s_nop 0
	v_fma_f32 v128, -v128, v165, v131
	v_fma_f32 v162, -v160, v161, 1.0
	v_div_fmas_f32 v128, v128, v129, v165
	v_fmac_f32_e32 v161, v162, v161
	v_div_fixup_f32 v153, v128, v153, 1.0
	v_div_scale_f32 v163, vcc, 1.0, v154, 1.0
	v_mul_f32_e32 v164, v163, v161
	v_div_scale_f32 v128, s[2:3], v155, v155, 1.0
	v_fma_f32 v162, -v160, v164, v163
	v_rcp_f32_e32 v129, v128
	v_fmac_f32_e32 v164, v162, v161
	s_nop 0
	v_fma_f32 v160, -v160, v164, v163
	v_fma_f32 v130, -v128, v129, 1.0
	v_div_fmas_f32 v160, v160, v161, v164
	v_fmac_f32_e32 v129, v130, v129
	v_div_fixup_f32 v154, v160, v154, 1.0
	v_div_scale_f32 v131, vcc, 1.0, v155, 1.0
	v_mul_f32_e32 v165, v131, v129
	v_div_scale_f32 v160, s[2:3], v156, v156, 1.0
	v_fma_f32 v130, -v128, v165, v131
	v_rcp_f32_e32 v161, v160
	v_fmac_f32_e32 v165, v130, v129
	s_nop 0
	v_fma_f32 v128, -v128, v165, v131
	v_fma_f32 v162, -v160, v161, 1.0
	v_div_fmas_f32 v128, v128, v129, v165
	v_fmac_f32_e32 v161, v162, v161
	v_div_fixup_f32 v155, v128, v155, 1.0
	v_div_scale_f32 v163, vcc, 1.0, v156, 1.0
	v_mul_f32_e32 v164, v163, v161
	v_div_scale_f32 v128, s[2:3], v157, v157, 1.0
	v_fma_f32 v162, -v160, v164, v163
	v_rcp_f32_e32 v129, v128
	v_fmac_f32_e32 v164, v162, v161
	s_nop 0
	v_fma_f32 v160, -v160, v164, v163
	v_fma_f32 v130, -v128, v129, 1.0
	v_div_fmas_f32 v160, v160, v161, v164
	v_fmac_f32_e32 v129, v130, v129
	v_div_fixup_f32 v156, v160, v156, 1.0
	v_div_scale_f32 v131, vcc, 1.0, v157, 1.0
	v_mul_f32_e32 v165, v131, v129
	v_div_scale_f32 v160, s[2:3], v158, v158, 1.0
	v_fma_f32 v130, -v128, v165, v131
	v_rcp_f32_e32 v161, v160
	v_fmac_f32_e32 v165, v130, v129
	s_nop 0
	v_fma_f32 v128, -v128, v165, v131
	v_fma_f32 v162, -v160, v161, 1.0
	v_div_fmas_f32 v128, v128, v129, v165
	v_fmac_f32_e32 v161, v162, v161
	v_div_fixup_f32 v157, v128, v157, 1.0
	v_div_scale_f32 v163, vcc, 1.0, v158, 1.0
	v_mul_f32_e32 v164, v163, v161
	v_div_scale_f32 v128, s[2:3], v159, v159, 1.0
	v_fma_f32 v162, -v160, v164, v163
	v_rcp_f32_e32 v129, v128
	v_fmac_f32_e32 v164, v162, v161
	s_nop 0
	v_fma_f32 v160, -v160, v164, v163
	v_fma_f32 v130, -v128, v129, 1.0
	v_div_fmas_f32 v160, v160, v161, v164
	v_fmac_f32_e32 v129, v130, v129
	v_div_fixup_f32 v158, v160, v158, 1.0
	v_div_scale_f32 v131, vcc, 1.0, v159, 1.0
	v_mul_f32_e32 v165, v131, v129
	v_fma_f32 v130, -v128, v165, v131
	v_fmac_f32_e32 v165, v130, v129
	v_fma_f32 v128, -v128, v165, v131
	v_div_fmas_f32 v128, v128, v129, v165
	v_div_fixup_f32 v159, v128, v159, 1.0
	v_pk_mul_f32 v[152:153], v[44:45], v[152:153]
	v_pk_mul_f32 v[154:155], v[46:47], v[154:155]
	v_pk_mul_f32 v[156:157], v[40:41], v[156:157]
	v_pk_mul_f32 v[158:159], v[42:43], v[158:159]
	v_cvt_pk_bf16_f32 v168, v152, v153
	v_cvt_pk_bf16_f32 v169, v154, v155
	v_cvt_pk_bf16_f32 v170, v156, v157
	v_cvt_pk_bf16_f32 v171, v158, v159
	global_store_dwordx4 v189, v[168:171], s[68:69]
	global_load_dwordx4 v[44:47], v183, s[64:65]
	s_waitcnt vmcnt(6)
; __device__ __forceinline__ float sigmoidf_(float x) { return 1.f / (1.f + __expf(-x)); }
	v_lshlrev_b32_e32 v152, 16, v68
	v_and_b32_e32 v153, 0xffff0000, v68
	v_lshlrev_b32_e32 v154, 16, v69
	v_and_b32_e32 v155, 0xffff0000, v69
	v_lshlrev_b32_e32 v156, 16, v70
	v_and_b32_e32 v157, 0xffff0000, v70
	v_lshlrev_b32_e32 v158, 16, v71
	v_and_b32_e32 v159, 0xffff0000, v71
	v_mul_f32_e32 v152, 0xbfb8aa3b, v152
	v_mul_f32_e32 v153, 0xbfb8aa3b, v153
	v_mul_f32_e32 v154, 0xbfb8aa3b, v154
	v_mul_f32_e32 v155, 0xbfb8aa3b, v155
	v_mul_f32_e32 v156, 0xbfb8aa3b, v156
	v_mul_f32_e32 v157, 0xbfb8aa3b, v157
	v_mul_f32_e32 v158, 0xbfb8aa3b, v158
	v_mul_f32_e32 v159, 0xbfb8aa3b, v159
	v_exp_f32_e32 v152, v152
	v_exp_f32_e32 v153, v153
	v_exp_f32_e32 v154, v154
	v_exp_f32_e32 v155, v155
	v_exp_f32_e32 v156, v156
	v_exp_f32_e32 v157, v157
	v_exp_f32_e32 v158, v158
	v_exp_f32_e32 v159, v159
	v_pk_add_f32 v[152:153], v[152:153], 1.0 op_sel_hi:[1,0]
	v_pk_add_f32 v[154:155], v[154:155], 1.0 op_sel_hi:[1,0]
	v_pk_add_f32 v[156:157], v[156:157], 1.0 op_sel_hi:[1,0]
	v_pk_add_f32 v[158:159], v[158:159], 1.0 op_sel_hi:[1,0]
	v_div_scale_f32 v160, s[2:3], v152, v152, 1.0
	v_rcp_f32_e32 v161, v160
	s_nop 0
	v_fma_f32 v162, -v160, v161, 1.0
	v_fmac_f32_e32 v161, v162, v161
	v_div_scale_f32 v163, vcc, 1.0, v152, 1.0
	v_mul_f32_e32 v164, v163, v161
	v_div_scale_f32 v128, s[2:3], v153, v153, 1.0
	v_fma_f32 v162, -v160, v164, v163
	v_rcp_f32_e32 v129, v128
	v_fmac_f32_e32 v164, v162, v161
	s_nop 0
	v_fma_f32 v160, -v160, v164, v163
	v_fma_f32 v130, -v128, v129, 1.0
	v_div_fmas_f32 v160, v160, v161, v164
	v_fmac_f32_e32 v129, v130, v129
	v_div_fixup_f32 v152, v160, v152, 1.0
	v_div_scale_f32 v131, vcc, 1.0, v153, 1.0
	v_mul_f32_e32 v165, v131, v129
	v_div_scale_f32 v160, s[2:3], v154, v154, 1.0
	v_fma_f32 v130, -v128, v165, v131
	v_rcp_f32_e32 v161, v160
	v_fmac_f32_e32 v165, v130, v129
	s_nop 0
	v_fma_f32 v128, -v128, v165, v131
	v_fma_f32 v162, -v160, v161, 1.0
	v_div_fmas_f32 v128, v128, v129, v165
	v_fmac_f32_e32 v161, v162, v161
	v_div_fixup_f32 v153, v128, v153, 1.0
	v_div_scale_f32 v163, vcc, 1.0, v154, 1.0
	v_mul_f32_e32 v164, v163, v161
	v_div_scale_f32 v128, s[2:3], v155, v155, 1.0
	v_fma_f32 v162, -v160, v164, v163
	v_rcp_f32_e32 v129, v128
	v_fmac_f32_e32 v164, v162, v161
	s_nop 0
	v_fma_f32 v160, -v160, v164, v163
	v_fma_f32 v130, -v128, v129, 1.0
	v_div_fmas_f32 v160, v160, v161, v164
	v_fmac_f32_e32 v129, v130, v129
	v_div_fixup_f32 v154, v160, v154, 1.0
	v_div_scale_f32 v131, vcc, 1.0, v155, 1.0
	v_mul_f32_e32 v165, v131, v129
	v_div_scale_f32 v160, s[2:3], v156, v156, 1.0
	v_fma_f32 v130, -v128, v165, v131
	v_rcp_f32_e32 v161, v160
	v_fmac_f32_e32 v165, v130, v129
	s_nop 0
	v_fma_f32 v128, -v128, v165, v131
	v_fma_f32 v162, -v160, v161, 1.0
	v_div_fmas_f32 v128, v128, v129, v165
	v_fmac_f32_e32 v161, v162, v161
	v_div_fixup_f32 v155, v128, v155, 1.0
	v_div_scale_f32 v163, vcc, 1.0, v156, 1.0
	v_mul_f32_e32 v164, v163, v161
	v_div_scale_f32 v128, s[2:3], v157, v157, 1.0
	v_fma_f32 v162, -v160, v164, v163
	v_rcp_f32_e32 v129, v128
	v_fmac_f32_e32 v164, v162, v161
	s_nop 0
	v_fma_f32 v160, -v160, v164, v163
	v_fma_f32 v130, -v128, v129, 1.0
	v_div_fmas_f32 v160, v160, v161, v164
	v_fmac_f32_e32 v129, v130, v129
	v_div_fixup_f32 v156, v160, v156, 1.0
	v_div_scale_f32 v131, vcc, 1.0, v157, 1.0
	v_mul_f32_e32 v165, v131, v129
	v_div_scale_f32 v160, s[2:3], v158, v158, 1.0
	v_fma_f32 v130, -v128, v165, v131
	v_rcp_f32_e32 v161, v160
	v_fmac_f32_e32 v165, v130, v129
	s_nop 0
	v_fma_f32 v128, -v128, v165, v131
	v_fma_f32 v162, -v160, v161, 1.0
	v_div_fmas_f32 v128, v128, v129, v165
	v_fmac_f32_e32 v161, v162, v161
	v_div_fixup_f32 v157, v128, v157, 1.0
	v_div_scale_f32 v163, vcc, 1.0, v158, 1.0
	v_mul_f32_e32 v164, v163, v161
	v_div_scale_f32 v128, s[2:3], v159, v159, 1.0
	v_fma_f32 v162, -v160, v164, v163
	v_rcp_f32_e32 v129, v128
	v_fmac_f32_e32 v164, v162, v161
	s_nop 0
	v_fma_f32 v160, -v160, v164, v163
	v_fma_f32 v130, -v128, v129, 1.0
	v_div_fmas_f32 v160, v160, v161, v164
	v_fmac_f32_e32 v129, v130, v129
	v_div_fixup_f32 v158, v160, v158, 1.0
	v_div_scale_f32 v131, vcc, 1.0, v159, 1.0
	v_mul_f32_e32 v165, v131, v129
	v_fma_f32 v130, -v128, v165, v131
	v_fmac_f32_e32 v165, v130, v129
	v_fma_f32 v128, -v128, v165, v131
	v_div_fmas_f32 v128, v128, v129, v165
	v_div_fixup_f32 v159, v128, v159, 1.0
	v_pk_mul_f32 v[152:153], v[36:37], v[152:153]
	v_pk_mul_f32 v[154:155], v[38:39], v[154:155]
	v_pk_mul_f32 v[156:157], v[32:33], v[156:157]
	v_pk_mul_f32 v[158:159], v[34:35], v[158:159]
	v_cvt_pk_bf16_f32 v168, v152, v153
	v_cvt_pk_bf16_f32 v169, v154, v155
	v_cvt_pk_bf16_f32 v170, v156, v157
	v_cvt_pk_bf16_f32 v171, v158, v159
	global_store_dwordx4 v189, v[168:171], s[68:69] offset:256
	global_load_dwordx4 v[36:39], v183, s[64:65] offset:256
	s_waitcnt vmcnt(6)
; __device__ __forceinline__ float sigmoidf_(float x) { return 1.f / (1.f + __expf(-x)); }
	v_lshlrev_b32_e32 v152, 16, v60
	v_and_b32_e32 v153, 0xffff0000, v60
	v_lshlrev_b32_e32 v154, 16, v61
	v_and_b32_e32 v155, 0xffff0000, v61
	v_lshlrev_b32_e32 v156, 16, v62
	v_and_b32_e32 v157, 0xffff0000, v62
	v_lshlrev_b32_e32 v158, 16, v63
	v_and_b32_e32 v159, 0xffff0000, v63
	v_mul_f32_e32 v152, 0xbfb8aa3b, v152
	v_mul_f32_e32 v153, 0xbfb8aa3b, v153
	v_mul_f32_e32 v154, 0xbfb8aa3b, v154
	v_mul_f32_e32 v155, 0xbfb8aa3b, v155
	v_mul_f32_e32 v156, 0xbfb8aa3b, v156
	v_mul_f32_e32 v157, 0xbfb8aa3b, v157
	v_mul_f32_e32 v158, 0xbfb8aa3b, v158
	v_mul_f32_e32 v159, 0xbfb8aa3b, v159
	v_exp_f32_e32 v152, v152
	v_exp_f32_e32 v153, v153
	v_exp_f32_e32 v154, v154
	v_exp_f32_e32 v155, v155
	v_exp_f32_e32 v156, v156
	v_exp_f32_e32 v157, v157
	v_exp_f32_e32 v158, v158
	v_exp_f32_e32 v159, v159
	v_pk_add_f32 v[152:153], v[152:153], 1.0 op_sel_hi:[1,0]
	v_pk_add_f32 v[154:155], v[154:155], 1.0 op_sel_hi:[1,0]
	v_pk_add_f32 v[156:157], v[156:157], 1.0 op_sel_hi:[1,0]
	v_pk_add_f32 v[158:159], v[158:159], 1.0 op_sel_hi:[1,0]
	v_div_scale_f32 v160, s[2:3], v152, v152, 1.0
	v_rcp_f32_e32 v161, v160
	s_nop 0
	v_fma_f32 v162, -v160, v161, 1.0
	v_fmac_f32_e32 v161, v162, v161
	v_div_scale_f32 v163, vcc, 1.0, v152, 1.0
	v_mul_f32_e32 v164, v163, v161
	v_div_scale_f32 v128, s[2:3], v153, v153, 1.0
	v_fma_f32 v162, -v160, v164, v163
	v_rcp_f32_e32 v129, v128
	v_fmac_f32_e32 v164, v162, v161
	s_nop 0
	v_fma_f32 v160, -v160, v164, v163
	v_fma_f32 v130, -v128, v129, 1.0
	v_div_fmas_f32 v160, v160, v161, v164
	v_fmac_f32_e32 v129, v130, v129
	v_div_fixup_f32 v152, v160, v152, 1.0
	v_div_scale_f32 v131, vcc, 1.0, v153, 1.0
	v_mul_f32_e32 v165, v131, v129
	v_div_scale_f32 v160, s[2:3], v154, v154, 1.0
	v_fma_f32 v130, -v128, v165, v131
	v_rcp_f32_e32 v161, v160
	v_fmac_f32_e32 v165, v130, v129
	s_nop 0
	v_fma_f32 v128, -v128, v165, v131
	v_fma_f32 v162, -v160, v161, 1.0
	v_div_fmas_f32 v128, v128, v129, v165
	v_fmac_f32_e32 v161, v162, v161
	v_div_fixup_f32 v153, v128, v153, 1.0
	v_div_scale_f32 v163, vcc, 1.0, v154, 1.0
	v_mul_f32_e32 v164, v163, v161
	v_div_scale_f32 v128, s[2:3], v155, v155, 1.0
	v_fma_f32 v162, -v160, v164, v163
	v_rcp_f32_e32 v129, v128
	v_fmac_f32_e32 v164, v162, v161
	s_nop 0
	v_fma_f32 v160, -v160, v164, v163
	v_fma_f32 v130, -v128, v129, 1.0
	v_div_fmas_f32 v160, v160, v161, v164
	v_fmac_f32_e32 v129, v130, v129
	v_div_fixup_f32 v154, v160, v154, 1.0
	v_div_scale_f32 v131, vcc, 1.0, v155, 1.0
	v_mul_f32_e32 v165, v131, v129
	v_div_scale_f32 v160, s[2:3], v156, v156, 1.0
	v_fma_f32 v130, -v128, v165, v131
	v_rcp_f32_e32 v161, v160
	v_fmac_f32_e32 v165, v130, v129
	s_nop 0
	v_fma_f32 v128, -v128, v165, v131
	v_fma_f32 v162, -v160, v161, 1.0
	v_div_fmas_f32 v128, v128, v129, v165
	v_fmac_f32_e32 v161, v162, v161
	v_div_fixup_f32 v155, v128, v155, 1.0
	v_div_scale_f32 v163, vcc, 1.0, v156, 1.0
	v_mul_f32_e32 v164, v163, v161
	v_div_scale_f32 v128, s[2:3], v157, v157, 1.0
	v_fma_f32 v162, -v160, v164, v163
	v_rcp_f32_e32 v129, v128
	v_fmac_f32_e32 v164, v162, v161
	s_nop 0
	v_fma_f32 v160, -v160, v164, v163
	v_fma_f32 v130, -v128, v129, 1.0
	v_div_fmas_f32 v160, v160, v161, v164
	v_fmac_f32_e32 v129, v130, v129
	v_div_fixup_f32 v156, v160, v156, 1.0
	v_div_scale_f32 v131, vcc, 1.0, v157, 1.0
	v_mul_f32_e32 v165, v131, v129
	v_div_scale_f32 v160, s[2:3], v158, v158, 1.0
	v_fma_f32 v130, -v128, v165, v131
	v_rcp_f32_e32 v161, v160
	v_fmac_f32_e32 v165, v130, v129
	s_nop 0
	v_fma_f32 v128, -v128, v165, v131
	v_fma_f32 v162, -v160, v161, 1.0
	v_div_fmas_f32 v128, v128, v129, v165
	v_fmac_f32_e32 v161, v162, v161
	v_div_fixup_f32 v157, v128, v157, 1.0
	v_div_scale_f32 v163, vcc, 1.0, v158, 1.0
	v_mul_f32_e32 v164, v163, v161
	v_div_scale_f32 v128, s[2:3], v159, v159, 1.0
	v_fma_f32 v162, -v160, v164, v163
	v_rcp_f32_e32 v129, v128
	v_fmac_f32_e32 v164, v162, v161
	s_nop 0
	v_fma_f32 v160, -v160, v164, v163
	v_fma_f32 v130, -v128, v129, 1.0
	v_div_fmas_f32 v160, v160, v161, v164
	v_fmac_f32_e32 v129, v130, v129
	v_div_fixup_f32 v158, v160, v158, 1.0
	v_div_scale_f32 v131, vcc, 1.0, v159, 1.0
	v_mul_f32_e32 v165, v131, v129
	v_fma_f32 v130, -v128, v165, v131
	v_fmac_f32_e32 v165, v130, v129
	v_fma_f32 v128, -v128, v165, v131
	v_div_fmas_f32 v128, v128, v129, v165
	v_div_fixup_f32 v159, v128, v159, 1.0
	v_pk_mul_f32 v[152:153], v[28:29], v[152:153]
	v_pk_mul_f32 v[154:155], v[30:31], v[154:155]
	v_pk_mul_f32 v[156:157], v[24:25], v[156:157]
	v_pk_mul_f32 v[158:159], v[26:27], v[158:159]
	v_cvt_pk_bf16_f32 v168, v152, v153
	v_cvt_pk_bf16_f32 v169, v154, v155
	v_cvt_pk_bf16_f32 v170, v156, v157
	v_cvt_pk_bf16_f32 v171, v158, v159
	global_store_dwordx4 v190, v[168:171], s[68:69]
	s_waitcnt vmcnt(5)
; __device__ __forceinline__ float sigmoidf_(float x) { return 1.f / (1.f + __expf(-x)); }
	v_lshlrev_b32_e32 v152, 16, v52
	v_and_b32_e32 v153, 0xffff0000, v52
	v_lshlrev_b32_e32 v154, 16, v53
	v_and_b32_e32 v155, 0xffff0000, v53
	v_lshlrev_b32_e32 v156, 16, v54
	v_and_b32_e32 v157, 0xffff0000, v54
	v_lshlrev_b32_e32 v158, 16, v55
	v_and_b32_e32 v159, 0xffff0000, v55
	v_mul_f32_e32 v152, 0xbfb8aa3b, v152
	v_mul_f32_e32 v153, 0xbfb8aa3b, v153
	v_mul_f32_e32 v154, 0xbfb8aa3b, v154
	v_mul_f32_e32 v155, 0xbfb8aa3b, v155
	v_mul_f32_e32 v156, 0xbfb8aa3b, v156
	v_mul_f32_e32 v157, 0xbfb8aa3b, v157
	v_mul_f32_e32 v158, 0xbfb8aa3b, v158
	v_mul_f32_e32 v159, 0xbfb8aa3b, v159
	v_exp_f32_e32 v152, v152
	v_exp_f32_e32 v153, v153
	v_exp_f32_e32 v154, v154
	v_exp_f32_e32 v155, v155
	v_exp_f32_e32 v156, v156
	v_exp_f32_e32 v157, v157
	v_exp_f32_e32 v158, v158
	v_exp_f32_e32 v159, v159
	v_pk_add_f32 v[152:153], v[152:153], 1.0 op_sel_hi:[1,0]
	v_pk_add_f32 v[154:155], v[154:155], 1.0 op_sel_hi:[1,0]
	v_pk_add_f32 v[156:157], v[156:157], 1.0 op_sel_hi:[1,0]
	v_pk_add_f32 v[158:159], v[158:159], 1.0 op_sel_hi:[1,0]
	v_div_scale_f32 v160, s[2:3], v152, v152, 1.0
	v_rcp_f32_e32 v161, v160
	s_nop 0
	v_fma_f32 v162, -v160, v161, 1.0
	v_fmac_f32_e32 v161, v162, v161
	v_div_scale_f32 v163, vcc, 1.0, v152, 1.0
	v_mul_f32_e32 v164, v163, v161
	v_div_scale_f32 v128, s[2:3], v153, v153, 1.0
	v_fma_f32 v162, -v160, v164, v163
	v_rcp_f32_e32 v129, v128
	v_fmac_f32_e32 v164, v162, v161
	s_nop 0
	v_fma_f32 v160, -v160, v164, v163
	v_fma_f32 v130, -v128, v129, 1.0
	v_div_fmas_f32 v160, v160, v161, v164
	v_fmac_f32_e32 v129, v130, v129
	v_div_fixup_f32 v152, v160, v152, 1.0
	v_div_scale_f32 v131, vcc, 1.0, v153, 1.0
	v_mul_f32_e32 v165, v131, v129
	v_div_scale_f32 v160, s[2:3], v154, v154, 1.0
	v_fma_f32 v130, -v128, v165, v131
	v_rcp_f32_e32 v161, v160
	v_fmac_f32_e32 v165, v130, v129
	s_nop 0
	v_fma_f32 v128, -v128, v165, v131
	v_fma_f32 v162, -v160, v161, 1.0
	v_div_fmas_f32 v128, v128, v129, v165
	v_fmac_f32_e32 v161, v162, v161
	v_div_fixup_f32 v153, v128, v153, 1.0
	v_div_scale_f32 v163, vcc, 1.0, v154, 1.0
	v_mul_f32_e32 v164, v163, v161
	v_div_scale_f32 v128, s[2:3], v155, v155, 1.0
	v_fma_f32 v162, -v160, v164, v163
	v_rcp_f32_e32 v129, v128
	v_fmac_f32_e32 v164, v162, v161
	s_nop 0
	v_fma_f32 v160, -v160, v164, v163
	v_fma_f32 v130, -v128, v129, 1.0
	v_div_fmas_f32 v160, v160, v161, v164
	v_fmac_f32_e32 v129, v130, v129
	v_div_fixup_f32 v154, v160, v154, 1.0
	v_div_scale_f32 v131, vcc, 1.0, v155, 1.0
	v_mul_f32_e32 v165, v131, v129
	v_div_scale_f32 v160, s[2:3], v156, v156, 1.0
	v_fma_f32 v130, -v128, v165, v131
	v_rcp_f32_e32 v161, v160
	v_fmac_f32_e32 v165, v130, v129
	s_nop 0
	v_fma_f32 v128, -v128, v165, v131
	v_fma_f32 v162, -v160, v161, 1.0
	v_div_fmas_f32 v128, v128, v129, v165
	v_fmac_f32_e32 v161, v162, v161
	v_div_fixup_f32 v155, v128, v155, 1.0
	v_div_scale_f32 v163, vcc, 1.0, v156, 1.0
	v_mul_f32_e32 v164, v163, v161
	v_div_scale_f32 v128, s[2:3], v157, v157, 1.0
	v_fma_f32 v162, -v160, v164, v163
	v_rcp_f32_e32 v129, v128
	v_fmac_f32_e32 v164, v162, v161
	s_nop 0
	v_fma_f32 v160, -v160, v164, v163
	v_fma_f32 v130, -v128, v129, 1.0
	v_div_fmas_f32 v160, v160, v161, v164
	v_fmac_f32_e32 v129, v130, v129
	v_div_fixup_f32 v156, v160, v156, 1.0
	v_div_scale_f32 v131, vcc, 1.0, v157, 1.0
	v_mul_f32_e32 v165, v131, v129
	v_div_scale_f32 v160, s[2:3], v158, v158, 1.0
	v_fma_f32 v130, -v128, v165, v131
	v_rcp_f32_e32 v161, v160
	v_fmac_f32_e32 v165, v130, v129
	s_nop 0
	v_fma_f32 v128, -v128, v165, v131
	v_fma_f32 v162, -v160, v161, 1.0
	v_div_fmas_f32 v128, v128, v129, v165
	v_fmac_f32_e32 v161, v162, v161
	v_div_fixup_f32 v157, v128, v157, 1.0
	v_div_scale_f32 v163, vcc, 1.0, v158, 1.0
	v_mul_f32_e32 v164, v163, v161
	v_div_scale_f32 v128, s[2:3], v159, v159, 1.0
	v_fma_f32 v162, -v160, v164, v163
	v_rcp_f32_e32 v129, v128
	v_fmac_f32_e32 v164, v162, v161
	s_nop 0
	v_fma_f32 v160, -v160, v164, v163
	v_fma_f32 v130, -v128, v129, 1.0
	v_div_fmas_f32 v160, v160, v161, v164
	v_fmac_f32_e32 v129, v130, v129
	v_div_fixup_f32 v158, v160, v158, 1.0
	v_div_scale_f32 v131, vcc, 1.0, v159, 1.0
	v_mul_f32_e32 v165, v131, v129
	v_fma_f32 v130, -v128, v165, v131
	v_fmac_f32_e32 v165, v130, v129
	v_fma_f32 v128, -v128, v165, v131
	v_div_fmas_f32 v128, v128, v129, v165
	v_div_fixup_f32 v159, v128, v159, 1.0
	v_pk_mul_f32 v[152:153], v[20:21], v[152:153]
	v_pk_mul_f32 v[154:155], v[22:23], v[154:155]
	v_pk_mul_f32 v[156:157], v[16:17], v[156:157]
	v_pk_mul_f32 v[158:159], v[18:19], v[158:159]
	v_cvt_pk_bf16_f32 v168, v152, v153
	v_cvt_pk_bf16_f32 v169, v154, v155
	v_cvt_pk_bf16_f32 v170, v156, v157
	v_cvt_pk_bf16_f32 v171, v158, v159
	global_store_dwordx4 v190, v[168:171], s[68:69] offset:256
	s_waitcnt vmcnt(4)
; __device__ __forceinline__ float sigmoidf_(float x) { return 1.f / (1.f + __expf(-x)); }
	v_lshlrev_b32_e32 v152, 16, v44
	v_and_b32_e32 v153, 0xffff0000, v44
	v_lshlrev_b32_e32 v154, 16, v45
	v_and_b32_e32 v155, 0xffff0000, v45
	v_lshlrev_b32_e32 v156, 16, v46
	v_and_b32_e32 v157, 0xffff0000, v46
	v_lshlrev_b32_e32 v158, 16, v47
	v_and_b32_e32 v159, 0xffff0000, v47
	v_mul_f32_e32 v152, 0xbfb8aa3b, v152
	v_mul_f32_e32 v153, 0xbfb8aa3b, v153
	v_mul_f32_e32 v154, 0xbfb8aa3b, v154
	v_mul_f32_e32 v155, 0xbfb8aa3b, v155
	v_mul_f32_e32 v156, 0xbfb8aa3b, v156
	v_mul_f32_e32 v157, 0xbfb8aa3b, v157
	v_mul_f32_e32 v158, 0xbfb8aa3b, v158
	v_mul_f32_e32 v159, 0xbfb8aa3b, v159
	v_exp_f32_e32 v152, v152
	v_exp_f32_e32 v153, v153
	v_exp_f32_e32 v154, v154
	v_exp_f32_e32 v155, v155
	v_exp_f32_e32 v156, v156
	v_exp_f32_e32 v157, v157
	v_exp_f32_e32 v158, v158
	v_exp_f32_e32 v159, v159
	v_pk_add_f32 v[152:153], v[152:153], 1.0 op_sel_hi:[1,0]
	v_pk_add_f32 v[154:155], v[154:155], 1.0 op_sel_hi:[1,0]
	v_pk_add_f32 v[156:157], v[156:157], 1.0 op_sel_hi:[1,0]
	v_pk_add_f32 v[158:159], v[158:159], 1.0 op_sel_hi:[1,0]
	v_div_scale_f32 v160, s[2:3], v152, v152, 1.0
	v_rcp_f32_e32 v161, v160
	s_nop 0
	v_fma_f32 v162, -v160, v161, 1.0
	v_fmac_f32_e32 v161, v162, v161
	v_div_scale_f32 v163, vcc, 1.0, v152, 1.0
	v_mul_f32_e32 v164, v163, v161
	v_div_scale_f32 v128, s[2:3], v153, v153, 1.0
	v_fma_f32 v162, -v160, v164, v163
	v_rcp_f32_e32 v129, v128
	v_fmac_f32_e32 v164, v162, v161
	s_nop 0
	v_fma_f32 v160, -v160, v164, v163
	v_fma_f32 v130, -v128, v129, 1.0
	v_div_fmas_f32 v160, v160, v161, v164
	v_fmac_f32_e32 v129, v130, v129
	v_div_fixup_f32 v152, v160, v152, 1.0
	v_div_scale_f32 v131, vcc, 1.0, v153, 1.0
	v_mul_f32_e32 v165, v131, v129
	v_div_scale_f32 v160, s[2:3], v154, v154, 1.0
	v_fma_f32 v130, -v128, v165, v131
	v_rcp_f32_e32 v161, v160
	v_fmac_f32_e32 v165, v130, v129
	s_nop 0
	v_fma_f32 v128, -v128, v165, v131
	v_fma_f32 v162, -v160, v161, 1.0
	v_div_fmas_f32 v128, v128, v129, v165
	v_fmac_f32_e32 v161, v162, v161
	v_div_fixup_f32 v153, v128, v153, 1.0
	v_div_scale_f32 v163, vcc, 1.0, v154, 1.0
	v_mul_f32_e32 v164, v163, v161
	v_div_scale_f32 v128, s[2:3], v155, v155, 1.0
	v_fma_f32 v162, -v160, v164, v163
	v_rcp_f32_e32 v129, v128
	v_fmac_f32_e32 v164, v162, v161
	s_nop 0
	v_fma_f32 v160, -v160, v164, v163
	v_fma_f32 v130, -v128, v129, 1.0
	v_div_fmas_f32 v160, v160, v161, v164
	v_fmac_f32_e32 v129, v130, v129
	v_div_fixup_f32 v154, v160, v154, 1.0
	v_div_scale_f32 v131, vcc, 1.0, v155, 1.0
	v_mul_f32_e32 v165, v131, v129
	v_div_scale_f32 v160, s[2:3], v156, v156, 1.0
	v_fma_f32 v130, -v128, v165, v131
	v_rcp_f32_e32 v161, v160
	v_fmac_f32_e32 v165, v130, v129
	s_nop 0
	v_fma_f32 v128, -v128, v165, v131
	v_fma_f32 v162, -v160, v161, 1.0
	v_div_fmas_f32 v128, v128, v129, v165
	v_fmac_f32_e32 v161, v162, v161
	v_div_fixup_f32 v155, v128, v155, 1.0
	v_div_scale_f32 v163, vcc, 1.0, v156, 1.0
	v_mul_f32_e32 v164, v163, v161
	v_div_scale_f32 v128, s[2:3], v157, v157, 1.0
	v_fma_f32 v162, -v160, v164, v163
	v_rcp_f32_e32 v129, v128
	v_fmac_f32_e32 v164, v162, v161
	s_nop 0
	v_fma_f32 v160, -v160, v164, v163
	v_fma_f32 v130, -v128, v129, 1.0
	v_div_fmas_f32 v160, v160, v161, v164
	v_fmac_f32_e32 v129, v130, v129
	v_div_fixup_f32 v156, v160, v156, 1.0
	v_div_scale_f32 v131, vcc, 1.0, v157, 1.0
	v_mul_f32_e32 v165, v131, v129
	v_div_scale_f32 v160, s[2:3], v158, v158, 1.0
	v_fma_f32 v130, -v128, v165, v131
	v_rcp_f32_e32 v161, v160
	v_fmac_f32_e32 v165, v130, v129
	s_nop 0
	v_fma_f32 v128, -v128, v165, v131
	v_fma_f32 v162, -v160, v161, 1.0
	v_div_fmas_f32 v128, v128, v129, v165
	v_fmac_f32_e32 v161, v162, v161
	v_div_fixup_f32 v157, v128, v157, 1.0
	v_div_scale_f32 v163, vcc, 1.0, v158, 1.0
	v_mul_f32_e32 v164, v163, v161
	v_div_scale_f32 v128, s[2:3], v159, v159, 1.0
	v_fma_f32 v162, -v160, v164, v163
	v_rcp_f32_e32 v129, v128
	v_fmac_f32_e32 v164, v162, v161
	s_nop 0
	v_fma_f32 v160, -v160, v164, v163
	v_fma_f32 v130, -v128, v129, 1.0
	v_div_fmas_f32 v160, v160, v161, v164
	v_fmac_f32_e32 v129, v130, v129
	v_div_fixup_f32 v158, v160, v158, 1.0
	v_div_scale_f32 v131, vcc, 1.0, v159, 1.0
	v_mul_f32_e32 v165, v131, v129
	v_fma_f32 v130, -v128, v165, v131
	v_fmac_f32_e32 v165, v130, v129
	v_fma_f32 v128, -v128, v165, v131
	v_div_fmas_f32 v128, v128, v129, v165
	v_div_fixup_f32 v159, v128, v159, 1.0
	v_pk_mul_f32 v[152:153], v[12:13], v[152:153]
	v_pk_mul_f32 v[154:155], v[14:15], v[154:155]
	v_pk_mul_f32 v[156:157], v[8:9], v[156:157]
	v_pk_mul_f32 v[158:159], v[10:11], v[158:159]
	v_cvt_pk_bf16_f32 v168, v152, v153
	v_cvt_pk_bf16_f32 v169, v154, v155
	v_cvt_pk_bf16_f32 v170, v156, v157
	v_cvt_pk_bf16_f32 v171, v158, v159
	global_store_dwordx4 v191, v[168:171], s[68:69]
	s_waitcnt vmcnt(3)
; template <class Epi>
; __device__ __forceinline__ void gemm_phase(LAS unsigned char* lds, const Gemm g, const Epi& E) {
;     ...
; #pragma unroll
;       for (int ai = 0; ai < 2; ++ai)
; #pragma unroll
;         for (int m = 0; m < 4; ++m)
; #pragma unroll
;           for (int bj = 0; bj < 2; ++bj)
;           { E.st2(cur.w, cur.pm * BM + ai * HALF + wr * 64 + m * 16 + fr, cur.pn * BM + bj * HALF + wc * 32 + 8 * fq, acc[ai][bj][m][0], acc[ai][bj][m][1]); if (bj == 1 && (m & 1)) asm volatile("" ::: "memory"); }
	v_lshlrev_b32_e32 v152, 16, v36
	v_and_b32_e32 v153, 0xffff0000, v36
	v_lshlrev_b32_e32 v154, 16, v37
	v_and_b32_e32 v155, 0xffff0000, v37
	v_lshlrev_b32_e32 v156, 16, v38
	v_and_b32_e32 v157, 0xffff0000, v38
	v_lshlrev_b32_e32 v158, 16, v39
	v_and_b32_e32 v159, 0xffff0000, v39
	v_mul_f32_e32 v152, 0xbfb8aa3b, v152
	v_mul_f32_e32 v153, 0xbfb8aa3b, v153
	v_mul_f32_e32 v154, 0xbfb8aa3b, v154
	v_mul_f32_e32 v155, 0xbfb8aa3b, v155
	v_mul_f32_e32 v156, 0xbfb8aa3b, v156
	v_mul_f32_e32 v157, 0xbfb8aa3b, v157
	v_mul_f32_e32 v158, 0xbfb8aa3b, v158
	v_mul_f32_e32 v159, 0xbfb8aa3b, v159
	v_exp_f32_e32 v152, v152
	v_exp_f32_e32 v153, v153
	v_exp_f32_e32 v154, v154
	v_exp_f32_e32 v155, v155
	v_exp_f32_e32 v156, v156
	v_exp_f32_e32 v157, v157
	v_exp_f32_e32 v158, v158
	v_exp_f32_e32 v159, v159
	v_pk_add_f32 v[152:153], v[152:153], 1.0 op_sel_hi:[1,0]
	v_pk_add_f32 v[154:155], v[154:155], 1.0 op_sel_hi:[1,0]
	v_pk_add_f32 v[156:157], v[156:157], 1.0 op_sel_hi:[1,0]
	v_pk_add_f32 v[158:159], v[158:159], 1.0 op_sel_hi:[1,0]
	v_div_scale_f32 v160, s[2:3], v152, v152, 1.0
	v_rcp_f32_e32 v161, v160
	s_nop 0
	v_fma_f32 v162, -v160, v161, 1.0
	v_fmac_f32_e32 v161, v162, v161
	v_div_scale_f32 v163, vcc, 1.0, v152, 1.0
	v_mul_f32_e32 v164, v163, v161
	v_div_scale_f32 v128, s[2:3], v153, v153, 1.0
	v_fma_f32 v162, -v160, v164, v163
	v_rcp_f32_e32 v129, v128
	v_fmac_f32_e32 v164, v162, v161
	s_nop 0
	v_fma_f32 v160, -v160, v164, v163
	v_fma_f32 v130, -v128, v129, 1.0
	v_div_fmas_f32 v160, v160, v161, v164
	v_fmac_f32_e32 v129, v130, v129
	v_div_fixup_f32 v152, v160, v152, 1.0
	v_div_scale_f32 v131, vcc, 1.0, v153, 1.0
	v_mul_f32_e32 v165, v131, v129
	v_div_scale_f32 v160, s[2:3], v154, v154, 1.0
	v_fma_f32 v130, -v128, v165, v131
	v_rcp_f32_e32 v161, v160
	v_fmac_f32_e32 v165, v130, v129
	s_nop 0
	v_fma_f32 v128, -v128, v165, v131
	v_fma_f32 v162, -v160, v161, 1.0
	v_div_fmas_f32 v128, v128, v129, v165
	v_fmac_f32_e32 v161, v162, v161
	v_div_fixup_f32 v153, v128, v153, 1.0
	v_div_scale_f32 v163, vcc, 1.0, v154, 1.0
	v_mul_f32_e32 v164, v163, v161
	v_div_scale_f32 v128, s[2:3], v155, v155, 1.0
	v_fma_f32 v162, -v160, v164, v163
	v_rcp_f32_e32 v129, v128
	v_fmac_f32_e32 v164, v162, v161
	s_nop 0
	v_fma_f32 v160, -v160, v164, v163
	v_fma_f32 v130, -v128, v129, 1.0
	v_div_fmas_f32 v160, v160, v161, v164
	v_fmac_f32_e32 v129, v130, v129
	v_div_fixup_f32 v154, v160, v154, 1.0
	v_div_scale_f32 v131, vcc, 1.0, v155, 1.0
	v_mul_f32_e32 v165, v131, v129
	v_div_scale_f32 v160, s[2:3], v156, v156, 1.0
	v_fma_f32 v130, -v128, v165, v131
	v_rcp_f32_e32 v161, v160
	v_fmac_f32_e32 v165, v130, v129
	s_nop 0
	v_fma_f32 v128, -v128, v165, v131
	v_fma_f32 v162, -v160, v161, 1.0
	v_div_fmas_f32 v128, v128, v129, v165
	v_fmac_f32_e32 v161, v162, v161
	v_div_fixup_f32 v155, v128, v155, 1.0
	v_div_scale_f32 v163, vcc, 1.0, v156, 1.0
	v_mul_f32_e32 v164, v163, v161
	v_div_scale_f32 v128, s[2:3], v157, v157, 1.0
	v_fma_f32 v162, -v160, v164, v163
	v_rcp_f32_e32 v129, v128
	v_fmac_f32_e32 v164, v162, v161
	s_nop 0
	v_fma_f32 v160, -v160, v164, v163
	v_fma_f32 v130, -v128, v129, 1.0
	v_div_fmas_f32 v160, v160, v161, v164
	v_fmac_f32_e32 v129, v130, v129
	v_div_fixup_f32 v156, v160, v156, 1.0
	v_div_scale_f32 v131, vcc, 1.0, v157, 1.0
	v_mul_f32_e32 v165, v131, v129
	v_div_scale_f32 v160, s[2:3], v158, v158, 1.0
	v_fma_f32 v130, -v128, v165, v131
	v_rcp_f32_e32 v161, v160
	v_fmac_f32_e32 v165, v130, v129
	s_nop 0
	v_fma_f32 v128, -v128, v165, v131
	v_fma_f32 v162, -v160, v161, 1.0
	v_div_fmas_f32 v128, v128, v129, v165
	v_fmac_f32_e32 v161, v162, v161
	v_div_fixup_f32 v157, v128, v157, 1.0
	v_div_scale_f32 v163, vcc, 1.0, v158, 1.0
	v_mul_f32_e32 v164, v163, v161
	v_div_scale_f32 v128, s[2:3], v159, v159, 1.0
	v_fma_f32 v162, -v160, v164, v163
	v_rcp_f32_e32 v129, v128
	v_fmac_f32_e32 v164, v162, v161
	s_nop 0
	v_fma_f32 v160, -v160, v164, v163
	v_fma_f32 v130, -v128, v129, 1.0
	v_div_fmas_f32 v160, v160, v161, v164
	v_fmac_f32_e32 v129, v130, v129
	v_div_fixup_f32 v158, v160, v158, 1.0
	v_div_scale_f32 v131, vcc, 1.0, v159, 1.0
	v_mul_f32_e32 v165, v131, v129
	v_fma_f32 v130, -v128, v165, v131
	v_fmac_f32_e32 v165, v130, v129
	v_fma_f32 v128, -v128, v165, v131
	v_div_fmas_f32 v128, v128, v129, v165
	v_div_fixup_f32 v159, v128, v159, 1.0
	v_pk_mul_f32 v[152:153], v[4:5], v[152:153]
	v_pk_mul_f32 v[154:155], v[6:7], v[154:155]
	v_pk_mul_f32 v[156:157], v[0:1], v[156:157]
	v_pk_mul_f32 v[158:159], v[2:3], v[158:159]
	v_cvt_pk_bf16_f32 v168, v152, v153
	v_cvt_pk_bf16_f32 v169, v154, v155
	v_cvt_pk_bf16_f32 v170, v156, v157
	v_cvt_pk_bf16_f32 v171, v158, v159
	global_store_dwordx4 v191, v[168:171], s[68:69] offset:256
	s_mov_b32 s32, 1
	s_branch .LBB0_567
; __device__ __forceinline__ float sigmoidf_(float x) { return 1.f / (1.f + __expf(-x)); }
.Lepi4:
	v_mul_u32_u24_e32 v176, 0x1800, v150
	v_lshl_add_u32 v176, v148, 1, v176
	v_add_u32_e32 v176, 0x1000, v176
	v_lshlrev_b32_e32 v184, 11, v150
	v_lshl_add_u32 v184, v148, 1, v184
	v_add_u32_e32 v177, 0x18000, v176
	v_add_u32_e32 v185, 0x8000, v184
	v_add_u32_e32 v178, 0x30000, v176
	v_add_u32_e32 v186, 0x10000, v184
	v_add_u32_e32 v179, 0x48000, v176
	v_add_u32_e32 v187, 0x18000, v184
	v_add_u32_e32 v180, 0xc0000, v176
	v_add_u32_e32 v188, 0x40000, v184
	v_add_u32_e32 v181, 0xd8000, v176
	v_add_u32_e32 v189, 0x48000, v184
	v_add_u32_e32 v182, 0xf0000, v176
	v_add_u32_e32 v190, 0x50000, v184
	v_add_u32_e32 v183, 0x108000, v176
	v_add_u32_e32 v191, 0x58000, v184
	global_load_dwordx4 v[192:195], v176, s[64:65]
	global_load_dwordx4 v[196:199], v184, s[68:69]
	global_load_dwordx4 v[200:203], v176, s[64:65] offset:256
	global_load_dwordx4 v[204:207], v184, s[68:69] offset:256
	global_load_dwordx4 v[208:211], v177, s[64:65]
	global_load_dwordx4 v[212:215], v185, s[68:69]
	global_load_dwordx4 v[216:219], v177, s[64:65] offset:256
	global_load_dwordx4 v[220:223], v185, s[68:69] offset:256
	s_waitcnt vmcnt(6)
	v_lshlrev_b32_e32 v152, 16, v192
	v_and_b32_e32 v153, 0xffff0000, v192
	v_lshlrev_b32_e32 v154, 16, v193
	v_and_b32_e32 v155, 0xffff0000, v193
	v_lshlrev_b32_e32 v156, 16, v194
	v_and_b32_e32 v157, 0xffff0000, v194
	v_lshlrev_b32_e32 v158, 16, v195
	v_and_b32_e32 v159, 0xffff0000, v195
	v_mul_f32_e32 v152, 0xbfb8aa3b, v152
	v_mul_f32_e32 v153, 0xbfb8aa3b, v153
	v_mul_f32_e32 v154, 0xbfb8aa3b, v154
	v_mul_f32_e32 v155, 0xbfb8aa3b, v155
	v_mul_f32_e32 v156, 0xbfb8aa3b, v156
	v_mul_f32_e32 v157, 0xbfb8aa3b, v157
	v_mul_f32_e32 v158, 0xbfb8aa3b, v158
	v_mul_f32_e32 v159, 0xbfb8aa3b, v159
	v_exp_f32_e32 v152, v152
	v_exp_f32_e32 v153, v153
	v_exp_f32_e32 v154, v154
	v_exp_f32_e32 v155, v155
	v_exp_f32_e32 v156, v156
	v_exp_f32_e32 v157, v157
	v_exp_f32_e32 v158, v158
	v_exp_f32_e32 v159, v159
	v_pk_add_f32 v[152:153], v[152:153], 1.0 op_sel_hi:[1,0]
	v_pk_add_f32 v[154:155], v[154:155], 1.0 op_sel_hi:[1,0]
	v_pk_add_f32 v[156:157], v[156:157], 1.0 op_sel_hi:[1,0]
	v_pk_add_f32 v[158:159], v[158:159], 1.0 op_sel_hi:[1,0]
	v_div_scale_f32 v160, s[2:3], v152, v152, 1.0
	v_rcp_f32_e32 v161, v160
	s_nop 0
	v_fma_f32 v162, -v160, v161, 1.0
	v_fmac_f32_e32 v161, v162, v161
	v_div_scale_f32 v163, vcc, 1.0, v152, 1.0
	v_mul_f32_e32 v164, v163, v161
	v_div_scale_f32 v128, s[2:3], v153, v153, 1.0
	v_fma_f32 v162, -v160, v164, v163
	v_rcp_f32_e32 v129, v128
	v_fmac_f32_e32 v164, v162, v161
	s_nop 0
	v_fma_f32 v160, -v160, v164, v163
	v_fma_f32 v130, -v128, v129, 1.0
	v_div_fmas_f32 v160, v160, v161, v164
	v_fmac_f32_e32 v129, v130, v129
	v_div_fixup_f32 v152, v160, v152, 1.0
	v_div_scale_f32 v131, vcc, 1.0, v153, 1.0
	v_mul_f32_e32 v165, v131, v129
	v_div_scale_f32 v160, s[2:3], v154, v154, 1.0
	v_fma_f32 v130, -v128, v165, v131
	v_rcp_f32_e32 v161, v160
	v_fmac_f32_e32 v165, v130, v129
	s_nop 0
	v_fma_f32 v128, -v128, v165, v131
	v_fma_f32 v162, -v160, v161, 1.0
	v_div_fmas_f32 v128, v128, v129, v165
	v_fmac_f32_e32 v161, v162, v161
	v_div_fixup_f32 v153, v128, v153, 1.0
	v_div_scale_f32 v163, vcc, 1.0, v154, 1.0
	v_mul_f32_e32 v164, v163, v161
	v_div_scale_f32 v128, s[2:3], v155, v155, 1.0
	v_fma_f32 v162, -v160, v164, v163
	v_rcp_f32_e32 v129, v128
	v_fmac_f32_e32 v164, v162, v161
	s_nop 0
	v_fma_f32 v160, -v160, v164, v163
	v_fma_f32 v130, -v128, v129, 1.0
	v_div_fmas_f32 v160, v160, v161, v164
	v_fmac_f32_e32 v129, v130, v129
	v_div_fixup_f32 v154, v160, v154, 1.0
	v_div_scale_f32 v131, vcc, 1.0, v155, 1.0
	v_mul_f32_e32 v165, v131, v129
	v_div_scale_f32 v160, s[2:3], v156, v156, 1.0
	v_fma_f32 v130, -v128, v165, v131
	v_rcp_f32_e32 v161, v160
	v_fmac_f32_e32 v165, v130, v129
	s_nop 0
	v_fma_f32 v128, -v128, v165, v131
	v_fma_f32 v162, -v160, v161, 1.0
	v_div_fmas_f32 v128, v128, v129, v165
	v_fmac_f32_e32 v161, v162, v161
	v_div_fixup_f32 v155, v128, v155, 1.0
	v_div_scale_f32 v163, vcc, 1.0, v156, 1.0
	v_mul_f32_e32 v164, v163, v161
	v_div_scale_f32 v128, s[2:3], v157, v157, 1.0
	v_fma_f32 v162, -v160, v164, v163
	v_rcp_f32_e32 v129, v128
	v_fmac_f32_e32 v164, v162, v161
	s_nop 0
	v_fma_f32 v160, -v160, v164, v163
	v_fma_f32 v130, -v128, v129, 1.0
	v_div_fmas_f32 v160, v160, v161, v164
	v_fmac_f32_e32 v129, v130, v129
	v_div_fixup_f32 v156, v160, v156, 1.0
	v_div_scale_f32 v131, vcc, 1.0, v157, 1.0
	v_mul_f32_e32 v165, v131, v129
	v_div_scale_f32 v160, s[2:3], v158, v158, 1.0
	v_fma_f32 v130, -v128, v165, v131
	v_rcp_f32_e32 v161, v160
	v_fmac_f32_e32 v165, v130, v129
	s_nop 0
	v_fma_f32 v128, -v128, v165, v131
	v_fma_f32 v162, -v160, v161, 1.0
	v_div_fmas_f32 v128, v128, v129, v165
	v_fmac_f32_e32 v161, v162, v161
	v_div_fixup_f32 v157, v128, v157, 1.0
	v_div_scale_f32 v163, vcc, 1.0, v158, 1.0
	v_mul_f32_e32 v164, v163, v161
	v_div_scale_f32 v128, s[2:3], v159, v159, 1.0
	v_fma_f32 v162, -v160, v164, v163
	v_rcp_f32_e32 v129, v128
	v_fmac_f32_e32 v164, v162, v161
	s_nop 0
	v_fma_f32 v160, -v160, v164, v163
	v_fma_f32 v130, -v128, v129, 1.0
	v_div_fmas_f32 v160, v160, v161, v164
	v_fmac_f32_e32 v129, v130, v129
	v_div_fixup_f32 v158, v160, v158, 1.0
	v_div_scale_f32 v131, vcc, 1.0, v159, 1.0
	v_mul_f32_e32 v165, v131, v129
	v_fma_f32 v130, -v128, v165, v131
	v_fmac_f32_e32 v165, v130, v129
	v_fma_f32 v128, -v128, v165, v131
	v_div_fmas_f32 v128, v128, v129, v165
	v_div_fixup_f32 v159, v128, v159, 1.0
	v_lshlrev_b32_e32 v166, 16, v196
	v_and_b32_e32 v167, 0xffff0000, v196
	v_pk_fma_f32 v[152:153], v[124:125], v[152:153], v[166:167]
	v_lshlrev_b32_e32 v166, 16, v197
	v_and_b32_e32 v167, 0xffff0000, v197
	v_pk_fma_f32 v[154:155], v[126:127], v[154:155], v[166:167]
	v_lshlrev_b32_e32 v166, 16, v198
	v_and_b32_e32 v167, 0xffff0000, v198
	v_pk_fma_f32 v[156:157], v[120:121], v[156:157], v[166:167]
	v_lshlrev_b32_e32 v166, 16, v199
	v_and_b32_e32 v167, 0xffff0000, v199
	v_pk_fma_f32 v[158:159], v[122:123], v[158:159], v[166:167]
	v_cvt_pk_bf16_f32 v168, v152, v153
	v_cvt_pk_bf16_f32 v169, v154, v155
	v_cvt_pk_bf16_f32 v170, v156, v157
	v_cvt_pk_bf16_f32 v171, v158, v159
	global_store_dwordx4 v184, v[168:171], s[66:67]
	global_load_dwordx4 v[124:127], v178, s[64:65]
	global_load_dwordx4 v[120:123], v186, s[68:69]
	s_waitcnt vmcnt(7)
; __device__ __forceinline__ float sigmoidf_(float x) { return 1.f / (1.f + __expf(-x)); }
	v_lshlrev_b32_e32 v152, 16, v200
	v_and_b32_e32 v153, 0xffff0000, v200
	v_lshlrev_b32_e32 v154, 16, v201
	v_and_b32_e32 v155, 0xffff0000, v201
	v_lshlrev_b32_e32 v156, 16, v202
	v_and_b32_e32 v157, 0xffff0000, v202
	v_lshlrev_b32_e32 v158, 16, v203
	v_and_b32_e32 v159, 0xffff0000, v203
	v_mul_f32_e32 v152, 0xbfb8aa3b, v152
	v_mul_f32_e32 v153, 0xbfb8aa3b, v153
	v_mul_f32_e32 v154, 0xbfb8aa3b, v154
	v_mul_f32_e32 v155, 0xbfb8aa3b, v155
	v_mul_f32_e32 v156, 0xbfb8aa3b, v156
	v_mul_f32_e32 v157, 0xbfb8aa3b, v157
	v_mul_f32_e32 v158, 0xbfb8aa3b, v158
	v_mul_f32_e32 v159, 0xbfb8aa3b, v159
	v_exp_f32_e32 v152, v152
	v_exp_f32_e32 v153, v153
	v_exp_f32_e32 v154, v154
	v_exp_f32_e32 v155, v155
	v_exp_f32_e32 v156, v156
	v_exp_f32_e32 v157, v157
	v_exp_f32_e32 v158, v158
	v_exp_f32_e32 v159, v159
	v_pk_add_f32 v[152:153], v[152:153], 1.0 op_sel_hi:[1,0]
	v_pk_add_f32 v[154:155], v[154:155], 1.0 op_sel_hi:[1,0]
	v_pk_add_f32 v[156:157], v[156:157], 1.0 op_sel_hi:[1,0]
	v_pk_add_f32 v[158:159], v[158:159], 1.0 op_sel_hi:[1,0]
	v_div_scale_f32 v160, s[2:3], v152, v152, 1.0
	v_rcp_f32_e32 v161, v160
	s_nop 0
	v_fma_f32 v162, -v160, v161, 1.0
	v_fmac_f32_e32 v161, v162, v161
	v_div_scale_f32 v163, vcc, 1.0, v152, 1.0
	v_mul_f32_e32 v164, v163, v161
	v_div_scale_f32 v128, s[2:3], v153, v153, 1.0
	v_fma_f32 v162, -v160, v164, v163
	v_rcp_f32_e32 v129, v128
	v_fmac_f32_e32 v164, v162, v161
	s_nop 0
	v_fma_f32 v160, -v160, v164, v163
	v_fma_f32 v130, -v128, v129, 1.0
	v_div_fmas_f32 v160, v160, v161, v164
	v_fmac_f32_e32 v129, v130, v129
	v_div_fixup_f32 v152, v160, v152, 1.0
	v_div_scale_f32 v131, vcc, 1.0, v153, 1.0
	v_mul_f32_e32 v165, v131, v129
	v_div_scale_f32 v160, s[2:3], v154, v154, 1.0
	v_fma_f32 v130, -v128, v165, v131
	v_rcp_f32_e32 v161, v160
	v_fmac_f32_e32 v165, v130, v129
	s_nop 0
	v_fma_f32 v128, -v128, v165, v131
	v_fma_f32 v162, -v160, v161, 1.0
	v_div_fmas_f32 v128, v128, v129, v165
	v_fmac_f32_e32 v161, v162, v161
	v_div_fixup_f32 v153, v128, v153, 1.0
	v_div_scale_f32 v163, vcc, 1.0, v154, 1.0
	v_mul_f32_e32 v164, v163, v161
	v_div_scale_f32 v128, s[2:3], v155, v155, 1.0
	v_fma_f32 v162, -v160, v164, v163
	v_rcp_f32_e32 v129, v128
	v_fmac_f32_e32 v164, v162, v161
	s_nop 0
	v_fma_f32 v160, -v160, v164, v163
	v_fma_f32 v130, -v128, v129, 1.0
	v_div_fmas_f32 v160, v160, v161, v164
	v_fmac_f32_e32 v129, v130, v129
	v_div_fixup_f32 v154, v160, v154, 1.0
	v_div_scale_f32 v131, vcc, 1.0, v155, 1.0
	v_mul_f32_e32 v165, v131, v129
	v_div_scale_f32 v160, s[2:3], v156, v156, 1.0
	v_fma_f32 v130, -v128, v165, v131
	v_rcp_f32_e32 v161, v160
	v_fmac_f32_e32 v165, v130, v129
	s_nop 0
	v_fma_f32 v128, -v128, v165, v131
	v_fma_f32 v162, -v160, v161, 1.0
	v_div_fmas_f32 v128, v128, v129, v165
	v_fmac_f32_e32 v161, v162, v161
	v_div_fixup_f32 v155, v128, v155, 1.0
	v_div_scale_f32 v163, vcc, 1.0, v156, 1.0
	v_mul_f32_e32 v164, v163, v161
	v_div_scale_f32 v128, s[2:3], v157, v157, 1.0
	v_fma_f32 v162, -v160, v164, v163
	v_rcp_f32_e32 v129, v128
	v_fmac_f32_e32 v164, v162, v161
	s_nop 0
	v_fma_f32 v160, -v160, v164, v163
	v_fma_f32 v130, -v128, v129, 1.0
	v_div_fmas_f32 v160, v160, v161, v164
	v_fmac_f32_e32 v129, v130, v129
	v_div_fixup_f32 v156, v160, v156, 1.0
	v_div_scale_f32 v131, vcc, 1.0, v157, 1.0
	v_mul_f32_e32 v165, v131, v129
	v_div_scale_f32 v160, s[2:3], v158, v158, 1.0
	v_fma_f32 v130, -v128, v165, v131
	v_rcp_f32_e32 v161, v160
	v_fmac_f32_e32 v165, v130, v129
	s_nop 0
	v_fma_f32 v128, -v128, v165, v131
	v_fma_f32 v162, -v160, v161, 1.0
	v_div_fmas_f32 v128, v128, v129, v165
	v_fmac_f32_e32 v161, v162, v161
	v_div_fixup_f32 v157, v128, v157, 1.0
	v_div_scale_f32 v163, vcc, 1.0, v158, 1.0
	v_mul_f32_e32 v164, v163, v161
	v_div_scale_f32 v128, s[2:3], v159, v159, 1.0
	v_fma_f32 v162, -v160, v164, v163
	v_rcp_f32_e32 v129, v128
	v_fmac_f32_e32 v164, v162, v161
	s_nop 0
	v_fma_f32 v160, -v160, v164, v163
	v_fma_f32 v130, -v128, v129, 1.0
	v_div_fmas_f32 v160, v160, v161, v164
	v_fmac_f32_e32 v129, v130, v129
	v_div_fixup_f32 v158, v160, v158, 1.0
	v_div_scale_f32 v131, vcc, 1.0, v159, 1.0
	v_mul_f32_e32 v165, v131, v129
	v_fma_f32 v130, -v128, v165, v131
	v_fmac_f32_e32 v165, v130, v129
	v_fma_f32 v128, -v128, v165, v131
	v_div_fmas_f32 v128, v128, v129, v165
	v_div_fixup_f32 v159, v128, v159, 1.0
	v_lshlrev_b32_e32 v166, 16, v204
	v_and_b32_e32 v167, 0xffff0000, v204
	v_pk_fma_f32 v[152:153], v[116:117], v[152:153], v[166:167]
	v_lshlrev_b32_e32 v166, 16, v205
	v_and_b32_e32 v167, 0xffff0000, v205
	v_pk_fma_f32 v[154:155], v[118:119], v[154:155], v[166:167]
	v_lshlrev_b32_e32 v166, 16, v206
	v_and_b32_e32 v167, 0xffff0000, v206
	v_pk_fma_f32 v[156:157], v[112:113], v[156:157], v[166:167]
	v_lshlrev_b32_e32 v166, 16, v207
	v_and_b32_e32 v167, 0xffff0000, v207
	v_pk_fma_f32 v[158:159], v[114:115], v[158:159], v[166:167]
	v_cvt_pk_bf16_f32 v168, v152, v153
	v_cvt_pk_bf16_f32 v169, v154, v155
	v_cvt_pk_bf16_f32 v170, v156, v157
	v_cvt_pk_bf16_f32 v171, v158, v159
	global_store_dwordx4 v184, v[168:171], s[66:67] offset:256
	global_load_dwordx4 v[116:119], v178, s[64:65] offset:256
	global_load_dwordx4 v[112:115], v186, s[68:69] offset:256
	s_waitcnt vmcnt(8)
; __device__ __forceinline__ float sigmoidf_(float x) { return 1.f / (1.f + __expf(-x)); }
	v_lshlrev_b32_e32 v152, 16, v208
	v_and_b32_e32 v153, 0xffff0000, v208
	v_lshlrev_b32_e32 v154, 16, v209
	v_and_b32_e32 v155, 0xffff0000, v209
	v_lshlrev_b32_e32 v156, 16, v210
	v_and_b32_e32 v157, 0xffff0000, v210
	v_lshlrev_b32_e32 v158, 16, v211
	v_and_b32_e32 v159, 0xffff0000, v211
	v_mul_f32_e32 v152, 0xbfb8aa3b, v152
	v_mul_f32_e32 v153, 0xbfb8aa3b, v153
	v_mul_f32_e32 v154, 0xbfb8aa3b, v154
	v_mul_f32_e32 v155, 0xbfb8aa3b, v155
	v_mul_f32_e32 v156, 0xbfb8aa3b, v156
	v_mul_f32_e32 v157, 0xbfb8aa3b, v157
	v_mul_f32_e32 v158, 0xbfb8aa3b, v158
	v_mul_f32_e32 v159, 0xbfb8aa3b, v159
	v_exp_f32_e32 v152, v152
	v_exp_f32_e32 v153, v153
	v_exp_f32_e32 v154, v154
	v_exp_f32_e32 v155, v155
	v_exp_f32_e32 v156, v156
	v_exp_f32_e32 v157, v157
	v_exp_f32_e32 v158, v158
	v_exp_f32_e32 v159, v159
	v_pk_add_f32 v[152:153], v[152:153], 1.0 op_sel_hi:[1,0]
	v_pk_add_f32 v[154:155], v[154:155], 1.0 op_sel_hi:[1,0]
	v_pk_add_f32 v[156:157], v[156:157], 1.0 op_sel_hi:[1,0]
	v_pk_add_f32 v[158:159], v[158:159], 1.0 op_sel_hi:[1,0]
	v_div_scale_f32 v160, s[2:3], v152, v152, 1.0
	v_rcp_f32_e32 v161, v160
	s_nop 0
	v_fma_f32 v162, -v160, v161, 1.0
	v_fmac_f32_e32 v161, v162, v161
	v_div_scale_f32 v163, vcc, 1.0, v152, 1.0
	v_mul_f32_e32 v164, v163, v161
	v_div_scale_f32 v128, s[2:3], v153, v153, 1.0
	v_fma_f32 v162, -v160, v164, v163
	v_rcp_f32_e32 v129, v128
	v_fmac_f32_e32 v164, v162, v161
	s_nop 0
	v_fma_f32 v160, -v160, v164, v163
	v_fma_f32 v130, -v128, v129, 1.0
	v_div_fmas_f32 v160, v160, v161, v164
	v_fmac_f32_e32 v129, v130, v129
	v_div_fixup_f32 v152, v160, v152, 1.0
	v_div_scale_f32 v131, vcc, 1.0, v153, 1.0
	v_mul_f32_e32 v165, v131, v129
	v_div_scale_f32 v160, s[2:3], v154, v154, 1.0
	v_fma_f32 v130, -v128, v165, v131
	v_rcp_f32_e32 v161, v160
	v_fmac_f32_e32 v165, v130, v129
	s_nop 0
	v_fma_f32 v128, -v128, v165, v131
	v_fma_f32 v162, -v160, v161, 1.0
	v_div_fmas_f32 v128, v128, v129, v165
	v_fmac_f32_e32 v161, v162, v161
	v_div_fixup_f32 v153, v128, v153, 1.0
	v_div_scale_f32 v163, vcc, 1.0, v154, 1.0
	v_mul_f32_e32 v164, v163, v161
	v_div_scale_f32 v128, s[2:3], v155, v155, 1.0
	v_fma_f32 v162, -v160, v164, v163
	v_rcp_f32_e32 v129, v128
	v_fmac_f32_e32 v164, v162, v161
	s_nop 0
	v_fma_f32 v160, -v160, v164, v163
	v_fma_f32 v130, -v128, v129, 1.0
	v_div_fmas_f32 v160, v160, v161, v164
	v_fmac_f32_e32 v129, v130, v129
	v_div_fixup_f32 v154, v160, v154, 1.0
	v_div_scale_f32 v131, vcc, 1.0, v155, 1.0
	v_mul_f32_e32 v165, v131, v129
	v_div_scale_f32 v160, s[2:3], v156, v156, 1.0
	v_fma_f32 v130, -v128, v165, v131
	v_rcp_f32_e32 v161, v160
	v_fmac_f32_e32 v165, v130, v129
	s_nop 0
	v_fma_f32 v128, -v128, v165, v131
	v_fma_f32 v162, -v160, v161, 1.0
	v_div_fmas_f32 v128, v128, v129, v165
	v_fmac_f32_e32 v161, v162, v161
	v_div_fixup_f32 v155, v128, v155, 1.0
	v_div_scale_f32 v163, vcc, 1.0, v156, 1.0
	v_mul_f32_e32 v164, v163, v161
	v_div_scale_f32 v128, s[2:3], v157, v157, 1.0
	v_fma_f32 v162, -v160, v164, v163
	v_rcp_f32_e32 v129, v128
	v_fmac_f32_e32 v164, v162, v161
	s_nop 0
	v_fma_f32 v160, -v160, v164, v163
	v_fma_f32 v130, -v128, v129, 1.0
	v_div_fmas_f32 v160, v160, v161, v164
	v_fmac_f32_e32 v129, v130, v129
	v_div_fixup_f32 v156, v160, v156, 1.0
	v_div_scale_f32 v131, vcc, 1.0, v157, 1.0
	v_mul_f32_e32 v165, v131, v129
	v_div_scale_f32 v160, s[2:3], v158, v158, 1.0
	v_fma_f32 v130, -v128, v165, v131
	v_rcp_f32_e32 v161, v160
	v_fmac_f32_e32 v165, v130, v129
	s_nop 0
	v_fma_f32 v128, -v128, v165, v131
	v_fma_f32 v162, -v160, v161, 1.0
	v_div_fmas_f32 v128, v128, v129, v165
	v_fmac_f32_e32 v161, v162, v161
	v_div_fixup_f32 v157, v128, v157, 1.0
	v_div_scale_f32 v163, vcc, 1.0, v158, 1.0
	v_mul_f32_e32 v164, v163, v161
	v_div_scale_f32 v128, s[2:3], v159, v159, 1.0
	v_fma_f32 v162, -v160, v164, v163
	v_rcp_f32_e32 v129, v128
	v_fmac_f32_e32 v164, v162, v161
	s_nop 0
	v_fma_f32 v160, -v160, v164, v163
	v_fma_f32 v130, -v128, v129, 1.0
	v_div_fmas_f32 v160, v160, v161, v164
	v_fmac_f32_e32 v129, v130, v129
	v_div_fixup_f32 v158, v160, v158, 1.0
	v_div_scale_f32 v131, vcc, 1.0, v159, 1.0
	v_mul_f32_e32 v165, v131, v129
	v_fma_f32 v130, -v128, v165, v131
	v_fmac_f32_e32 v165, v130, v129
	v_fma_f32 v128, -v128, v165, v131
	v_div_fmas_f32 v128, v128, v129, v165
	v_div_fixup_f32 v159, v128, v159, 1.0
	v_lshlrev_b32_e32 v166, 16, v212
	v_and_b32_e32 v167, 0xffff0000, v212
	v_pk_fma_f32 v[152:153], v[108:109], v[152:153], v[166:167]
	v_lshlrev_b32_e32 v166, 16, v213
	v_and_b32_e32 v167, 0xffff0000, v213
	v_pk_fma_f32 v[154:155], v[110:111], v[154:155], v[166:167]
	v_lshlrev_b32_e32 v166, 16, v214
	v_and_b32_e32 v167, 0xffff0000, v214
	v_pk_fma_f32 v[156:157], v[104:105], v[156:157], v[166:167]
	v_lshlrev_b32_e32 v166, 16, v215
	v_and_b32_e32 v167, 0xffff0000, v215
	v_pk_fma_f32 v[158:159], v[106:107], v[158:159], v[166:167]
	v_cvt_pk_bf16_f32 v168, v152, v153
	v_cvt_pk_bf16_f32 v169, v154, v155
	v_cvt_pk_bf16_f32 v170, v156, v157
	v_cvt_pk_bf16_f32 v171, v158, v159
	global_store_dwordx4 v185, v[168:171], s[66:67]
	global_load_dwordx4 v[108:111], v179, s[64:65]
	global_load_dwordx4 v[104:107], v187, s[68:69]
	s_waitcnt vmcnt(9)
; __device__ __forceinline__ float sigmoidf_(float x) { return 1.f / (1.f + __expf(-x)); }
	v_lshlrev_b32_e32 v152, 16, v216
	v_and_b32_e32 v153, 0xffff0000, v216
	v_lshlrev_b32_e32 v154, 16, v217
	v_and_b32_e32 v155, 0xffff0000, v217
	v_lshlrev_b32_e32 v156, 16, v218
	v_and_b32_e32 v157, 0xffff0000, v218
	v_lshlrev_b32_e32 v158, 16, v219
	v_and_b32_e32 v159, 0xffff0000, v219
	v_mul_f32_e32 v152, 0xbfb8aa3b, v152
	v_mul_f32_e32 v153, 0xbfb8aa3b, v153
	v_mul_f32_e32 v154, 0xbfb8aa3b, v154
	v_mul_f32_e32 v155, 0xbfb8aa3b, v155
	v_mul_f32_e32 v156, 0xbfb8aa3b, v156
	v_mul_f32_e32 v157, 0xbfb8aa3b, v157
	v_mul_f32_e32 v158, 0xbfb8aa3b, v158
	v_mul_f32_e32 v159, 0xbfb8aa3b, v159
	v_exp_f32_e32 v152, v152
	v_exp_f32_e32 v153, v153
	v_exp_f32_e32 v154, v154
	v_exp_f32_e32 v155, v155
	v_exp_f32_e32 v156, v156
	v_exp_f32_e32 v157, v157
	v_exp_f32_e32 v158, v158
	v_exp_f32_e32 v159, v159
	v_pk_add_f32 v[152:153], v[152:153], 1.0 op_sel_hi:[1,0]
	v_pk_add_f32 v[154:155], v[154:155], 1.0 op_sel_hi:[1,0]
	v_pk_add_f32 v[156:157], v[156:157], 1.0 op_sel_hi:[1,0]
	v_pk_add_f32 v[158:159], v[158:159], 1.0 op_sel_hi:[1,0]
	v_div_scale_f32 v160, s[2:3], v152, v152, 1.0
	v_rcp_f32_e32 v161, v160
	s_nop 0
	v_fma_f32 v162, -v160, v161, 1.0
	v_fmac_f32_e32 v161, v162, v161
	v_div_scale_f32 v163, vcc, 1.0, v152, 1.0
	v_mul_f32_e32 v164, v163, v161
	v_div_scale_f32 v128, s[2:3], v153, v153, 1.0
	v_fma_f32 v162, -v160, v164, v163
	v_rcp_f32_e32 v129, v128
	v_fmac_f32_e32 v164, v162, v161
	s_nop 0
	v_fma_f32 v160, -v160, v164, v163
	v_fma_f32 v130, -v128, v129, 1.0
	v_div_fmas_f32 v160, v160, v161, v164
	v_fmac_f32_e32 v129, v130, v129
	v_div_fixup_f32 v152, v160, v152, 1.0
	v_div_scale_f32 v131, vcc, 1.0, v153, 1.0
	v_mul_f32_e32 v165, v131, v129
	v_div_scale_f32 v160, s[2:3], v154, v154, 1.0
	v_fma_f32 v130, -v128, v165, v131
	v_rcp_f32_e32 v161, v160
	v_fmac_f32_e32 v165, v130, v129
	s_nop 0
	v_fma_f32 v128, -v128, v165, v131
	v_fma_f32 v162, -v160, v161, 1.0
	v_div_fmas_f32 v128, v128, v129, v165
	v_fmac_f32_e32 v161, v162, v161
	v_div_fixup_f32 v153, v128, v153, 1.0
	v_div_scale_f32 v163, vcc, 1.0, v154, 1.0
	v_mul_f32_e32 v164, v163, v161
	v_div_scale_f32 v128, s[2:3], v155, v155, 1.0
	v_fma_f32 v162, -v160, v164, v163
	v_rcp_f32_e32 v129, v128
	v_fmac_f32_e32 v164, v162, v161
	s_nop 0
	v_fma_f32 v160, -v160, v164, v163
	v_fma_f32 v130, -v128, v129, 1.0
	v_div_fmas_f32 v160, v160, v161, v164
	v_fmac_f32_e32 v129, v130, v129
	v_div_fixup_f32 v154, v160, v154, 1.0
	v_div_scale_f32 v131, vcc, 1.0, v155, 1.0
	v_mul_f32_e32 v165, v131, v129
	v_div_scale_f32 v160, s[2:3], v156, v156, 1.0
	v_fma_f32 v130, -v128, v165, v131
	v_rcp_f32_e32 v161, v160
	v_fmac_f32_e32 v165, v130, v129
	s_nop 0
	v_fma_f32 v128, -v128, v165, v131
	v_fma_f32 v162, -v160, v161, 1.0
	v_div_fmas_f32 v128, v128, v129, v165
	v_fmac_f32_e32 v161, v162, v161
	v_div_fixup_f32 v155, v128, v155, 1.0
	v_div_scale_f32 v163, vcc, 1.0, v156, 1.0
	v_mul_f32_e32 v164, v163, v161
	v_div_scale_f32 v128, s[2:3], v157, v157, 1.0
	v_fma_f32 v162, -v160, v164, v163
	v_rcp_f32_e32 v129, v128
	v_fmac_f32_e32 v164, v162, v161
	s_nop 0
	v_fma_f32 v160, -v160, v164, v163
	v_fma_f32 v130, -v128, v129, 1.0
	v_div_fmas_f32 v160, v160, v161, v164
	v_fmac_f32_e32 v129, v130, v129
	v_div_fixup_f32 v156, v160, v156, 1.0
	v_div_scale_f32 v131, vcc, 1.0, v157, 1.0
	v_mul_f32_e32 v165, v131, v129
	v_div_scale_f32 v160, s[2:3], v158, v158, 1.0
	v_fma_f32 v130, -v128, v165, v131
	v_rcp_f32_e32 v161, v160
	v_fmac_f32_e32 v165, v130, v129
	s_nop 0
	v_fma_f32 v128, -v128, v165, v131
	v_fma_f32 v162, -v160, v161, 1.0
	v_div_fmas_f32 v128, v128, v129, v165
	v_fmac_f32_e32 v161, v162, v161
	v_div_fixup_f32 v157, v128, v157, 1.0
	v_div_scale_f32 v163, vcc, 1.0, v158, 1.0
	v_mul_f32_e32 v164, v163, v161
	v_div_scale_f32 v128, s[2:3], v159, v159, 1.0
	v_fma_f32 v162, -v160, v164, v163
	v_rcp_f32_e32 v129, v128
	v_fmac_f32_e32 v164, v162, v161
	s_nop 0
	v_fma_f32 v160, -v160, v164, v163
	v_fma_f32 v130, -v128, v129, 1.0
	v_div_fmas_f32 v160, v160, v161, v164
	v_fmac_f32_e32 v129, v130, v129
	v_div_fixup_f32 v158, v160, v158, 1.0
	v_div_scale_f32 v131, vcc, 1.0, v159, 1.0
	v_mul_f32_e32 v165, v131, v129
	v_fma_f32 v130, -v128, v165, v131
	v_fmac_f32_e32 v165, v130, v129
	v_fma_f32 v128, -v128, v165, v131
	v_div_fmas_f32 v128, v128, v129, v165
	v_div_fixup_f32 v159, v128, v159, 1.0
	v_lshlrev_b32_e32 v166, 16, v220
	v_and_b32_e32 v167, 0xffff0000, v220
	v_pk_fma_f32 v[152:153], v[100:101], v[152:153], v[166:167]
	v_lshlrev_b32_e32 v166, 16, v221
	v_and_b32_e32 v167, 0xffff0000, v221
	v_pk_fma_f32 v[154:155], v[102:103], v[154:155], v[166:167]
	v_lshlrev_b32_e32 v166, 16, v222
	v_and_b32_e32 v167, 0xffff0000, v222
	v_pk_fma_f32 v[156:157], v[96:97], v[156:157], v[166:167]
	v_lshlrev_b32_e32 v166, 16, v223
	v_and_b32_e32 v167, 0xffff0000, v223
	v_pk_fma_f32 v[158:159], v[98:99], v[158:159], v[166:167]
	v_cvt_pk_bf16_f32 v168, v152, v153
	v_cvt_pk_bf16_f32 v169, v154, v155
	v_cvt_pk_bf16_f32 v170, v156, v157
	v_cvt_pk_bf16_f32 v171, v158, v159
	global_store_dwordx4 v185, v[168:171], s[66:67] offset:256
	global_load_dwordx4 v[100:103], v179, s[64:65] offset:256
	global_load_dwordx4 v[96:99], v187, s[68:69] offset:256
	s_waitcnt vmcnt(9)
; __device__ __forceinline__ float sigmoidf_(float x) { return 1.f / (1.f + __expf(-x)); }
	v_lshlrev_b32_e32 v152, 16, v124
	v_and_b32_e32 v153, 0xffff0000, v124
	v_lshlrev_b32_e32 v154, 16, v125
	v_and_b32_e32 v155, 0xffff0000, v125
	v_lshlrev_b32_e32 v156, 16, v126
	v_and_b32_e32 v157, 0xffff0000, v126
	v_lshlrev_b32_e32 v158, 16, v127
	v_and_b32_e32 v159, 0xffff0000, v127
	v_mul_f32_e32 v152, 0xbfb8aa3b, v152
	v_mul_f32_e32 v153, 0xbfb8aa3b, v153
	v_mul_f32_e32 v154, 0xbfb8aa3b, v154
	v_mul_f32_e32 v155, 0xbfb8aa3b, v155
	v_mul_f32_e32 v156, 0xbfb8aa3b, v156
	v_mul_f32_e32 v157, 0xbfb8aa3b, v157
	v_mul_f32_e32 v158, 0xbfb8aa3b, v158
	v_mul_f32_e32 v159, 0xbfb8aa3b, v159
	v_exp_f32_e32 v152, v152
	v_exp_f32_e32 v153, v153
	v_exp_f32_e32 v154, v154
	v_exp_f32_e32 v155, v155
	v_exp_f32_e32 v156, v156
	v_exp_f32_e32 v157, v157
	v_exp_f32_e32 v158, v158
	v_exp_f32_e32 v159, v159
	v_pk_add_f32 v[152:153], v[152:153], 1.0 op_sel_hi:[1,0]
	v_pk_add_f32 v[154:155], v[154:155], 1.0 op_sel_hi:[1,0]
	v_pk_add_f32 v[156:157], v[156:157], 1.0 op_sel_hi:[1,0]
	v_pk_add_f32 v[158:159], v[158:159], 1.0 op_sel_hi:[1,0]
	v_div_scale_f32 v160, s[2:3], v152, v152, 1.0
	v_rcp_f32_e32 v161, v160
	s_nop 0
	v_fma_f32 v162, -v160, v161, 1.0
	v_fmac_f32_e32 v161, v162, v161
	v_div_scale_f32 v163, vcc, 1.0, v152, 1.0
	v_mul_f32_e32 v164, v163, v161
	v_div_scale_f32 v128, s[2:3], v153, v153, 1.0
	v_fma_f32 v162, -v160, v164, v163
	v_rcp_f32_e32 v129, v128
	v_fmac_f32_e32 v164, v162, v161
	s_nop 0
	v_fma_f32 v160, -v160, v164, v163
	v_fma_f32 v130, -v128, v129, 1.0
	v_div_fmas_f32 v160, v160, v161, v164
	v_fmac_f32_e32 v129, v130, v129
	v_div_fixup_f32 v152, v160, v152, 1.0
	v_div_scale_f32 v131, vcc, 1.0, v153, 1.0
	v_mul_f32_e32 v165, v131, v129
	v_div_scale_f32 v160, s[2:3], v154, v154, 1.0
	v_fma_f32 v130, -v128, v165, v131
	v_rcp_f32_e32 v161, v160
	v_fmac_f32_e32 v165, v130, v129
	s_nop 0
	v_fma_f32 v128, -v128, v165, v131
	v_fma_f32 v162, -v160, v161, 1.0
	v_div_fmas_f32 v128, v128, v129, v165
	v_fmac_f32_e32 v161, v162, v161
	v_div_fixup_f32 v153, v128, v153, 1.0
	v_div_scale_f32 v163, vcc, 1.0, v154, 1.0
	v_mul_f32_e32 v164, v163, v161
	v_div_scale_f32 v128, s[2:3], v155, v155, 1.0
	v_fma_f32 v162, -v160, v164, v163
	v_rcp_f32_e32 v129, v128
	v_fmac_f32_e32 v164, v162, v161
	s_nop 0
	v_fma_f32 v160, -v160, v164, v163
	v_fma_f32 v130, -v128, v129, 1.0
	v_div_fmas_f32 v160, v160, v161, v164
	v_fmac_f32_e32 v129, v130, v129
	v_div_fixup_f32 v154, v160, v154, 1.0
	v_div_scale_f32 v131, vcc, 1.0, v155, 1.0
	v_mul_f32_e32 v165, v131, v129
	v_div_scale_f32 v160, s[2:3], v156, v156, 1.0
	v_fma_f32 v130, -v128, v165, v131
	v_rcp_f32_e32 v161, v160
	v_fmac_f32_e32 v165, v130, v129
	s_nop 0
	v_fma_f32 v128, -v128, v165, v131
	v_fma_f32 v162, -v160, v161, 1.0
	v_div_fmas_f32 v128, v128, v129, v165
	v_fmac_f32_e32 v161, v162, v161
	v_div_fixup_f32 v155, v128, v155, 1.0
	v_div_scale_f32 v163, vcc, 1.0, v156, 1.0
	v_mul_f32_e32 v164, v163, v161
	v_div_scale_f32 v128, s[2:3], v157, v157, 1.0
	v_fma_f32 v162, -v160, v164, v163
	v_rcp_f32_e32 v129, v128
	v_fmac_f32_e32 v164, v162, v161
	s_nop 0
	v_fma_f32 v160, -v160, v164, v163
	v_fma_f32 v130, -v128, v129, 1.0
	v_div_fmas_f32 v160, v160, v161, v164
	v_fmac_f32_e32 v129, v130, v129
	v_div_fixup_f32 v156, v160, v156, 1.0
	v_div_scale_f32 v131, vcc, 1.0, v157, 1.0
	v_mul_f32_e32 v165, v131, v129
	v_div_scale_f32 v160, s[2:3], v158, v158, 1.0
	v_fma_f32 v130, -v128, v165, v131
	v_rcp_f32_e32 v161, v160
	v_fmac_f32_e32 v165, v130, v129
	s_nop 0
	v_fma_f32 v128, -v128, v165, v131
	v_fma_f32 v162, -v160, v161, 1.0
	v_div_fmas_f32 v128, v128, v129, v165
	v_fmac_f32_e32 v161, v162, v161
	v_div_fixup_f32 v157, v128, v157, 1.0
	v_div_scale_f32 v163, vcc, 1.0, v158, 1.0
	v_mul_f32_e32 v164, v163, v161
	v_div_scale_f32 v128, s[2:3], v159, v159, 1.0
	v_fma_f32 v162, -v160, v164, v163
	v_rcp_f32_e32 v129, v128
	v_fmac_f32_e32 v164, v162, v161
	s_nop 0
	v_fma_f32 v160, -v160, v164, v163
	v_fma_f32 v130, -v128, v129, 1.0
	v_div_fmas_f32 v160, v160, v161, v164
	v_fmac_f32_e32 v129, v130, v129
	v_div_fixup_f32 v158, v160, v158, 1.0
	v_div_scale_f32 v131, vcc, 1.0, v159, 1.0
	v_mul_f32_e32 v165, v131, v129
	v_fma_f32 v130, -v128, v165, v131
	v_fmac_f32_e32 v165, v130, v129
	v_fma_f32 v128, -v128, v165, v131
	v_div_fmas_f32 v128, v128, v129, v165
	v_div_fixup_f32 v159, v128, v159, 1.0
	v_lshlrev_b32_e32 v166, 16, v120
	v_and_b32_e32 v167, 0xffff0000, v120
	v_pk_fma_f32 v[152:153], v[92:93], v[152:153], v[166:167]
	v_lshlrev_b32_e32 v166, 16, v121
	v_and_b32_e32 v167, 0xffff0000, v121
	v_pk_fma_f32 v[154:155], v[94:95], v[154:155], v[166:167]
	v_lshlrev_b32_e32 v166, 16, v122
	v_and_b32_e32 v167, 0xffff0000, v122
	v_pk_fma_f32 v[156:157], v[88:89], v[156:157], v[166:167]
	v_lshlrev_b32_e32 v166, 16, v123
	v_and_b32_e32 v167, 0xffff0000, v123
	v_pk_fma_f32 v[158:159], v[90:91], v[158:159], v[166:167]
	v_cvt_pk_bf16_f32 v168, v152, v153
	v_cvt_pk_bf16_f32 v169, v154, v155
	v_cvt_pk_bf16_f32 v170, v156, v157
	v_cvt_pk_bf16_f32 v171, v158, v159
	global_store_dwordx4 v186, v[168:171], s[66:67]
	global_load_dwordx4 v[92:95], v180, s[64:65]
	global_load_dwordx4 v[88:91], v188, s[68:69]
	s_waitcnt vmcnt(9)
; __device__ __forceinline__ float sigmoidf_(float x) { return 1.f / (1.f + __expf(-x)); }
	v_lshlrev_b32_e32 v152, 16, v116
	v_and_b32_e32 v153, 0xffff0000, v116
	v_lshlrev_b32_e32 v154, 16, v117
	v_and_b32_e32 v155, 0xffff0000, v117
	v_lshlrev_b32_e32 v156, 16, v118
	v_and_b32_e32 v157, 0xffff0000, v118
	v_lshlrev_b32_e32 v158, 16, v119
	v_and_b32_e32 v159, 0xffff0000, v119
	v_mul_f32_e32 v152, 0xbfb8aa3b, v152
	v_mul_f32_e32 v153, 0xbfb8aa3b, v153
	v_mul_f32_e32 v154, 0xbfb8aa3b, v154
	v_mul_f32_e32 v155, 0xbfb8aa3b, v155
	v_mul_f32_e32 v156, 0xbfb8aa3b, v156
	v_mul_f32_e32 v157, 0xbfb8aa3b, v157
	v_mul_f32_e32 v158, 0xbfb8aa3b, v158
	v_mul_f32_e32 v159, 0xbfb8aa3b, v159
	v_exp_f32_e32 v152, v152
	v_exp_f32_e32 v153, v153
	v_exp_f32_e32 v154, v154
	v_exp_f32_e32 v155, v155
	v_exp_f32_e32 v156, v156
	v_exp_f32_e32 v157, v157
	v_exp_f32_e32 v158, v158
	v_exp_f32_e32 v159, v159
	v_pk_add_f32 v[152:153], v[152:153], 1.0 op_sel_hi:[1,0]
	v_pk_add_f32 v[154:155], v[154:155], 1.0 op_sel_hi:[1,0]
	v_pk_add_f32 v[156:157], v[156:157], 1.0 op_sel_hi:[1,0]
	v_pk_add_f32 v[158:159], v[158:159], 1.0 op_sel_hi:[1,0]
	v_div_scale_f32 v160, s[2:3], v152, v152, 1.0
	v_rcp_f32_e32 v161, v160
	s_nop 0
	v_fma_f32 v162, -v160, v161, 1.0
	v_fmac_f32_e32 v161, v162, v161
	v_div_scale_f32 v163, vcc, 1.0, v152, 1.0
	v_mul_f32_e32 v164, v163, v161
	v_div_scale_f32 v128, s[2:3], v153, v153, 1.0
	v_fma_f32 v162, -v160, v164, v163
	v_rcp_f32_e32 v129, v128
	v_fmac_f32_e32 v164, v162, v161
	s_nop 0
	v_fma_f32 v160, -v160, v164, v163
	v_fma_f32 v130, -v128, v129, 1.0
	v_div_fmas_f32 v160, v160, v161, v164
	v_fmac_f32_e32 v129, v130, v129
	v_div_fixup_f32 v152, v160, v152, 1.0
	v_div_scale_f32 v131, vcc, 1.0, v153, 1.0
	v_mul_f32_e32 v165, v131, v129
	v_div_scale_f32 v160, s[2:3], v154, v154, 1.0
	v_fma_f32 v130, -v128, v165, v131
	v_rcp_f32_e32 v161, v160
	v_fmac_f32_e32 v165, v130, v129
	s_nop 0
	v_fma_f32 v128, -v128, v165, v131
	v_fma_f32 v162, -v160, v161, 1.0
	v_div_fmas_f32 v128, v128, v129, v165
	v_fmac_f32_e32 v161, v162, v161
	v_div_fixup_f32 v153, v128, v153, 1.0
	v_div_scale_f32 v163, vcc, 1.0, v154, 1.0
	v_mul_f32_e32 v164, v163, v161
	v_div_scale_f32 v128, s[2:3], v155, v155, 1.0
	v_fma_f32 v162, -v160, v164, v163
	v_rcp_f32_e32 v129, v128
	v_fmac_f32_e32 v164, v162, v161
	s_nop 0
	v_fma_f32 v160, -v160, v164, v163
	v_fma_f32 v130, -v128, v129, 1.0
	v_div_fmas_f32 v160, v160, v161, v164
	v_fmac_f32_e32 v129, v130, v129
	v_div_fixup_f32 v154, v160, v154, 1.0
	v_div_scale_f32 v131, vcc, 1.0, v155, 1.0
	v_mul_f32_e32 v165, v131, v129
	v_div_scale_f32 v160, s[2:3], v156, v156, 1.0
	v_fma_f32 v130, -v128, v165, v131
	v_rcp_f32_e32 v161, v160
	v_fmac_f32_e32 v165, v130, v129
	s_nop 0
	v_fma_f32 v128, -v128, v165, v131
	v_fma_f32 v162, -v160, v161, 1.0
	v_div_fmas_f32 v128, v128, v129, v165
	v_fmac_f32_e32 v161, v162, v161
	v_div_fixup_f32 v155, v128, v155, 1.0
	v_div_scale_f32 v163, vcc, 1.0, v156, 1.0
	v_mul_f32_e32 v164, v163, v161
	v_div_scale_f32 v128, s[2:3], v157, v157, 1.0
	v_fma_f32 v162, -v160, v164, v163
	v_rcp_f32_e32 v129, v128
	v_fmac_f32_e32 v164, v162, v161
	s_nop 0
	v_fma_f32 v160, -v160, v164, v163
	v_fma_f32 v130, -v128, v129, 1.0
	v_div_fmas_f32 v160, v160, v161, v164
	v_fmac_f32_e32 v129, v130, v129
	v_div_fixup_f32 v156, v160, v156, 1.0
	v_div_scale_f32 v131, vcc, 1.0, v157, 1.0
	v_mul_f32_e32 v165, v131, v129
	v_div_scale_f32 v160, s[2:3], v158, v158, 1.0
	v_fma_f32 v130, -v128, v165, v131
	v_rcp_f32_e32 v161, v160
	v_fmac_f32_e32 v165, v130, v129
	s_nop 0
	v_fma_f32 v128, -v128, v165, v131
	v_fma_f32 v162, -v160, v161, 1.0
	v_div_fmas_f32 v128, v128, v129, v165
	v_fmac_f32_e32 v161, v162, v161
	v_div_fixup_f32 v157, v128, v157, 1.0
	v_div_scale_f32 v163, vcc, 1.0, v158, 1.0
	v_mul_f32_e32 v164, v163, v161
	v_div_scale_f32 v128, s[2:3], v159, v159, 1.0
	v_fma_f32 v162, -v160, v164, v163
	v_rcp_f32_e32 v129, v128
	v_fmac_f32_e32 v164, v162, v161
	s_nop 0
	v_fma_f32 v160, -v160, v164, v163
	v_fma_f32 v130, -v128, v129, 1.0
	v_div_fmas_f32 v160, v160, v161, v164
	v_fmac_f32_e32 v129, v130, v129
	v_div_fixup_f32 v158, v160, v158, 1.0
	v_div_scale_f32 v131, vcc, 1.0, v159, 1.0
	v_mul_f32_e32 v165, v131, v129
	v_fma_f32 v130, -v128, v165, v131
	v_fmac_f32_e32 v165, v130, v129
	v_fma_f32 v128, -v128, v165, v131
	v_div_fmas_f32 v128, v128, v129, v165
	v_div_fixup_f32 v159, v128, v159, 1.0
	v_lshlrev_b32_e32 v166, 16, v112
	v_and_b32_e32 v167, 0xffff0000, v112
	v_pk_fma_f32 v[152:153], v[84:85], v[152:153], v[166:167]
	v_lshlrev_b32_e32 v166, 16, v113
	v_and_b32_e32 v167, 0xffff0000, v113
	v_pk_fma_f32 v[154:155], v[86:87], v[154:155], v[166:167]
	v_lshlrev_b32_e32 v166, 16, v114
	v_and_b32_e32 v167, 0xffff0000, v114
	v_pk_fma_f32 v[156:157], v[80:81], v[156:157], v[166:167]
	v_lshlrev_b32_e32 v166, 16, v115
	v_and_b32_e32 v167, 0xffff0000, v115
	v_pk_fma_f32 v[158:159], v[82:83], v[158:159], v[166:167]
	v_cvt_pk_bf16_f32 v168, v152, v153
	v_cvt_pk_bf16_f32 v169, v154, v155
	v_cvt_pk_bf16_f32 v170, v156, v157
	v_cvt_pk_bf16_f32 v171, v158, v159
	global_store_dwordx4 v186, v[168:171], s[66:67] offset:256
	global_load_dwordx4 v[84:87], v180, s[64:65] offset:256
	global_load_dwordx4 v[80:83], v188, s[68:69] offset:256
	s_waitcnt vmcnt(9)
; __device__ __forceinline__ float sigmoidf_(float x) { return 1.f / (1.f + __expf(-x)); }
	v_lshlrev_b32_e32 v152, 16, v108
	v_and_b32_e32 v153, 0xffff0000, v108
	v_lshlrev_b32_e32 v154, 16, v109
	v_and_b32_e32 v155, 0xffff0000, v109
	v_lshlrev_b32_e32 v156, 16, v110
	v_and_b32_e32 v157, 0xffff0000, v110
	v_lshlrev_b32_e32 v158, 16, v111
	v_and_b32_e32 v159, 0xffff0000, v111
	v_mul_f32_e32 v152, 0xbfb8aa3b, v152
	v_mul_f32_e32 v153, 0xbfb8aa3b, v153
	v_mul_f32_e32 v154, 0xbfb8aa3b, v154
	v_mul_f32_e32 v155, 0xbfb8aa3b, v155
	v_mul_f32_e32 v156, 0xbfb8aa3b, v156
	v_mul_f32_e32 v157, 0xbfb8aa3b, v157
	v_mul_f32_e32 v158, 0xbfb8aa3b, v158
	v_mul_f32_e32 v159, 0xbfb8aa3b, v159
	v_exp_f32_e32 v152, v152
	v_exp_f32_e32 v153, v153
	v_exp_f32_e32 v154, v154
	v_exp_f32_e32 v155, v155
	v_exp_f32_e32 v156, v156
	v_exp_f32_e32 v157, v157
	v_exp_f32_e32 v158, v158
	v_exp_f32_e32 v159, v159
	v_pk_add_f32 v[152:153], v[152:153], 1.0 op_sel_hi:[1,0]
	v_pk_add_f32 v[154:155], v[154:155], 1.0 op_sel_hi:[1,0]
	v_pk_add_f32 v[156:157], v[156:157], 1.0 op_sel_hi:[1,0]
	v_pk_add_f32 v[158:159], v[158:159], 1.0 op_sel_hi:[1,0]
	v_div_scale_f32 v160, s[2:3], v152, v152, 1.0
	v_rcp_f32_e32 v161, v160
	s_nop 0
	v_fma_f32 v162, -v160, v161, 1.0
	v_fmac_f32_e32 v161, v162, v161
	v_div_scale_f32 v163, vcc, 1.0, v152, 1.0
	v_mul_f32_e32 v164, v163, v161
	v_div_scale_f32 v128, s[2:3], v153, v153, 1.0
	v_fma_f32 v162, -v160, v164, v163
	v_rcp_f32_e32 v129, v128
	v_fmac_f32_e32 v164, v162, v161
	s_nop 0
	v_fma_f32 v160, -v160, v164, v163
	v_fma_f32 v130, -v128, v129, 1.0
	v_div_fmas_f32 v160, v160, v161, v164
	v_fmac_f32_e32 v129, v130, v129
	v_div_fixup_f32 v152, v160, v152, 1.0
	v_div_scale_f32 v131, vcc, 1.0, v153, 1.0
	v_mul_f32_e32 v165, v131, v129
	v_div_scale_f32 v160, s[2:3], v154, v154, 1.0
	v_fma_f32 v130, -v128, v165, v131
	v_rcp_f32_e32 v161, v160
	v_fmac_f32_e32 v165, v130, v129
	s_nop 0
	v_fma_f32 v128, -v128, v165, v131
	v_fma_f32 v162, -v160, v161, 1.0
	v_div_fmas_f32 v128, v128, v129, v165
	v_fmac_f32_e32 v161, v162, v161
	v_div_fixup_f32 v153, v128, v153, 1.0
	v_div_scale_f32 v163, vcc, 1.0, v154, 1.0
	v_mul_f32_e32 v164, v163, v161
	v_div_scale_f32 v128, s[2:3], v155, v155, 1.0
	v_fma_f32 v162, -v160, v164, v163
	v_rcp_f32_e32 v129, v128
	v_fmac_f32_e32 v164, v162, v161
	s_nop 0
	v_fma_f32 v160, -v160, v164, v163
	v_fma_f32 v130, -v128, v129, 1.0
	v_div_fmas_f32 v160, v160, v161, v164
	v_fmac_f32_e32 v129, v130, v129
	v_div_fixup_f32 v154, v160, v154, 1.0
	v_div_scale_f32 v131, vcc, 1.0, v155, 1.0
	v_mul_f32_e32 v165, v131, v129
	v_div_scale_f32 v160, s[2:3], v156, v156, 1.0
	v_fma_f32 v130, -v128, v165, v131
	v_rcp_f32_e32 v161, v160
	v_fmac_f32_e32 v165, v130, v129
	s_nop 0
	v_fma_f32 v128, -v128, v165, v131
	v_fma_f32 v162, -v160, v161, 1.0
	v_div_fmas_f32 v128, v128, v129, v165
	v_fmac_f32_e32 v161, v162, v161
	v_div_fixup_f32 v155, v128, v155, 1.0
	v_div_scale_f32 v163, vcc, 1.0, v156, 1.0
	v_mul_f32_e32 v164, v163, v161
	v_div_scale_f32 v128, s[2:3], v157, v157, 1.0
	v_fma_f32 v162, -v160, v164, v163
	v_rcp_f32_e32 v129, v128
	v_fmac_f32_e32 v164, v162, v161
	s_nop 0
	v_fma_f32 v160, -v160, v164, v163
	v_fma_f32 v130, -v128, v129, 1.0
	v_div_fmas_f32 v160, v160, v161, v164
	v_fmac_f32_e32 v129, v130, v129
	v_div_fixup_f32 v156, v160, v156, 1.0
	v_div_scale_f32 v131, vcc, 1.0, v157, 1.0
	v_mul_f32_e32 v165, v131, v129
	v_div_scale_f32 v160, s[2:3], v158, v158, 1.0
	v_fma_f32 v130, -v128, v165, v131
	v_rcp_f32_e32 v161, v160
	v_fmac_f32_e32 v165, v130, v129
	s_nop 0
	v_fma_f32 v128, -v128, v165, v131
	v_fma_f32 v162, -v160, v161, 1.0
	v_div_fmas_f32 v128, v128, v129, v165
	v_fmac_f32_e32 v161, v162, v161
	v_div_fixup_f32 v157, v128, v157, 1.0
	v_div_scale_f32 v163, vcc, 1.0, v158, 1.0
	v_mul_f32_e32 v164, v163, v161
	v_div_scale_f32 v128, s[2:3], v159, v159, 1.0
	v_fma_f32 v162, -v160, v164, v163
	v_rcp_f32_e32 v129, v128
	v_fmac_f32_e32 v164, v162, v161
	s_nop 0
	v_fma_f32 v160, -v160, v164, v163
	v_fma_f32 v130, -v128, v129, 1.0
	v_div_fmas_f32 v160, v160, v161, v164
	v_fmac_f32_e32 v129, v130, v129
	v_div_fixup_f32 v158, v160, v158, 1.0
	v_div_scale_f32 v131, vcc, 1.0, v159, 1.0
	v_mul_f32_e32 v165, v131, v129
	v_fma_f32 v130, -v128, v165, v131
	v_fmac_f32_e32 v165, v130, v129
	v_fma_f32 v128, -v128, v165, v131
	v_div_fmas_f32 v128, v128, v129, v165
	v_div_fixup_f32 v159, v128, v159, 1.0
	v_lshlrev_b32_e32 v166, 16, v104
	v_and_b32_e32 v167, 0xffff0000, v104
	v_pk_fma_f32 v[152:153], v[76:77], v[152:153], v[166:167]
	v_lshlrev_b32_e32 v166, 16, v105
	v_and_b32_e32 v167, 0xffff0000, v105
	v_pk_fma_f32 v[154:155], v[78:79], v[154:155], v[166:167]
	v_lshlrev_b32_e32 v166, 16, v106
	v_and_b32_e32 v167, 0xffff0000, v106
	v_pk_fma_f32 v[156:157], v[72:73], v[156:157], v[166:167]
	v_lshlrev_b32_e32 v166, 16, v107
	v_and_b32_e32 v167, 0xffff0000, v107
	v_pk_fma_f32 v[158:159], v[74:75], v[158:159], v[166:167]
	v_cvt_pk_bf16_f32 v168, v152, v153
	v_cvt_pk_bf16_f32 v169, v154, v155
	v_cvt_pk_bf16_f32 v170, v156, v157
	v_cvt_pk_bf16_f32 v171, v158, v159
	global_store_dwordx4 v187, v[168:171], s[66:67]
	global_load_dwordx4 v[76:79], v181, s[64:65]
	global_load_dwordx4 v[72:75], v189, s[68:69]
	s_waitcnt vmcnt(9)
; __device__ __forceinline__ float sigmoidf_(float x) { return 1.f / (1.f + __expf(-x)); }
	v_lshlrev_b32_e32 v152, 16, v100
	v_and_b32_e32 v153, 0xffff0000, v100
	v_lshlrev_b32_e32 v154, 16, v101
	v_and_b32_e32 v155, 0xffff0000, v101
	v_lshlrev_b32_e32 v156, 16, v102
	v_and_b32_e32 v157, 0xffff0000, v102
	v_lshlrev_b32_e32 v158, 16, v103
	v_and_b32_e32 v159, 0xffff0000, v103
	v_mul_f32_e32 v152, 0xbfb8aa3b, v152
	v_mul_f32_e32 v153, 0xbfb8aa3b, v153
	v_mul_f32_e32 v154, 0xbfb8aa3b, v154
	v_mul_f32_e32 v155, 0xbfb8aa3b, v155
	v_mul_f32_e32 v156, 0xbfb8aa3b, v156
	v_mul_f32_e32 v157, 0xbfb8aa3b, v157
	v_mul_f32_e32 v158, 0xbfb8aa3b, v158
	v_mul_f32_e32 v159, 0xbfb8aa3b, v159
	v_exp_f32_e32 v152, v152
	v_exp_f32_e32 v153, v153
	v_exp_f32_e32 v154, v154
	v_exp_f32_e32 v155, v155
	v_exp_f32_e32 v156, v156
	v_exp_f32_e32 v157, v157
	v_exp_f32_e32 v158, v158
	v_exp_f32_e32 v159, v159
	v_pk_add_f32 v[152:153], v[152:153], 1.0 op_sel_hi:[1,0]
	v_pk_add_f32 v[154:155], v[154:155], 1.0 op_sel_hi:[1,0]
	v_pk_add_f32 v[156:157], v[156:157], 1.0 op_sel_hi:[1,0]
	v_pk_add_f32 v[158:159], v[158:159], 1.0 op_sel_hi:[1,0]
	v_div_scale_f32 v160, s[2:3], v152, v152, 1.0
	v_rcp_f32_e32 v161, v160
	s_nop 0
	v_fma_f32 v162, -v160, v161, 1.0
	v_fmac_f32_e32 v161, v162, v161
	v_div_scale_f32 v163, vcc, 1.0, v152, 1.0
	v_mul_f32_e32 v164, v163, v161
	v_div_scale_f32 v128, s[2:3], v153, v153, 1.0
	v_fma_f32 v162, -v160, v164, v163
	v_rcp_f32_e32 v129, v128
	v_fmac_f32_e32 v164, v162, v161
	s_nop 0
	v_fma_f32 v160, -v160, v164, v163
	v_fma_f32 v130, -v128, v129, 1.0
	v_div_fmas_f32 v160, v160, v161, v164
	v_fmac_f32_e32 v129, v130, v129
	v_div_fixup_f32 v152, v160, v152, 1.0
	v_div_scale_f32 v131, vcc, 1.0, v153, 1.0
	v_mul_f32_e32 v165, v131, v129
	v_div_scale_f32 v160, s[2:3], v154, v154, 1.0
	v_fma_f32 v130, -v128, v165, v131
	v_rcp_f32_e32 v161, v160
	v_fmac_f32_e32 v165, v130, v129
	s_nop 0
	v_fma_f32 v128, -v128, v165, v131
	v_fma_f32 v162, -v160, v161, 1.0
	v_div_fmas_f32 v128, v128, v129, v165
	v_fmac_f32_e32 v161, v162, v161
	v_div_fixup_f32 v153, v128, v153, 1.0
	v_div_scale_f32 v163, vcc, 1.0, v154, 1.0
	v_mul_f32_e32 v164, v163, v161
	v_div_scale_f32 v128, s[2:3], v155, v155, 1.0
	v_fma_f32 v162, -v160, v164, v163
	v_rcp_f32_e32 v129, v128
	v_fmac_f32_e32 v164, v162, v161
	s_nop 0
	v_fma_f32 v160, -v160, v164, v163
	v_fma_f32 v130, -v128, v129, 1.0
	v_div_fmas_f32 v160, v160, v161, v164
	v_fmac_f32_e32 v129, v130, v129
	v_div_fixup_f32 v154, v160, v154, 1.0
	v_div_scale_f32 v131, vcc, 1.0, v155, 1.0
	v_mul_f32_e32 v165, v131, v129
	v_div_scale_f32 v160, s[2:3], v156, v156, 1.0
	v_fma_f32 v130, -v128, v165, v131
	v_rcp_f32_e32 v161, v160
	v_fmac_f32_e32 v165, v130, v129
	s_nop 0
	v_fma_f32 v128, -v128, v165, v131
	v_fma_f32 v162, -v160, v161, 1.0
	v_div_fmas_f32 v128, v128, v129, v165
	v_fmac_f32_e32 v161, v162, v161
	v_div_fixup_f32 v155, v128, v155, 1.0
	v_div_scale_f32 v163, vcc, 1.0, v156, 1.0
	v_mul_f32_e32 v164, v163, v161
	v_div_scale_f32 v128, s[2:3], v157, v157, 1.0
	v_fma_f32 v162, -v160, v164, v163
	v_rcp_f32_e32 v129, v128
	v_fmac_f32_e32 v164, v162, v161
	s_nop 0
	v_fma_f32 v160, -v160, v164, v163
	v_fma_f32 v130, -v128, v129, 1.0
	v_div_fmas_f32 v160, v160, v161, v164
	v_fmac_f32_e32 v129, v130, v129
	v_div_fixup_f32 v156, v160, v156, 1.0
	v_div_scale_f32 v131, vcc, 1.0, v157, 1.0
	v_mul_f32_e32 v165, v131, v129
	v_div_scale_f32 v160, s[2:3], v158, v158, 1.0
	v_fma_f32 v130, -v128, v165, v131
	v_rcp_f32_e32 v161, v160
	v_fmac_f32_e32 v165, v130, v129
	s_nop 0
	v_fma_f32 v128, -v128, v165, v131
	v_fma_f32 v162, -v160, v161, 1.0
	v_div_fmas_f32 v128, v128, v129, v165
	v_fmac_f32_e32 v161, v162, v161
	v_div_fixup_f32 v157, v128, v157, 1.0
	v_div_scale_f32 v163, vcc, 1.0, v158, 1.0
	v_mul_f32_e32 v164, v163, v161
	v_div_scale_f32 v128, s[2:3], v159, v159, 1.0
	v_fma_f32 v162, -v160, v164, v163
	v_rcp_f32_e32 v129, v128
	v_fmac_f32_e32 v164, v162, v161
	s_nop 0
	v_fma_f32 v160, -v160, v164, v163
	v_fma_f32 v130, -v128, v129, 1.0
	v_div_fmas_f32 v160, v160, v161, v164
	v_fmac_f32_e32 v129, v130, v129
	v_div_fixup_f32 v158, v160, v158, 1.0
	v_div_scale_f32 v131, vcc, 1.0, v159, 1.0
	v_mul_f32_e32 v165, v131, v129
	v_fma_f32 v130, -v128, v165, v131
	v_fmac_f32_e32 v165, v130, v129
	v_fma_f32 v128, -v128, v165, v131
	v_div_fmas_f32 v128, v128, v129, v165
	v_div_fixup_f32 v159, v128, v159, 1.0
	v_lshlrev_b32_e32 v166, 16, v96
	v_and_b32_e32 v167, 0xffff0000, v96
	v_pk_fma_f32 v[152:153], v[68:69], v[152:153], v[166:167]
	v_lshlrev_b32_e32 v166, 16, v97
	v_and_b32_e32 v167, 0xffff0000, v97
	v_pk_fma_f32 v[154:155], v[70:71], v[154:155], v[166:167]
	v_lshlrev_b32_e32 v166, 16, v98
	v_and_b32_e32 v167, 0xffff0000, v98
	v_pk_fma_f32 v[156:157], v[64:65], v[156:157], v[166:167]
	v_lshlrev_b32_e32 v166, 16, v99
	v_and_b32_e32 v167, 0xffff0000, v99
	v_pk_fma_f32 v[158:159], v[66:67], v[158:159], v[166:167]
	v_cvt_pk_bf16_f32 v168, v152, v153
	v_cvt_pk_bf16_f32 v169, v154, v155
	v_cvt_pk_bf16_f32 v170, v156, v157
	v_cvt_pk_bf16_f32 v171, v158, v159
	global_store_dwordx4 v187, v[168:171], s[66:67] offset:256
	global_load_dwordx4 v[68:71], v181, s[64:65] offset:256
	global_load_dwordx4 v[64:67], v189, s[68:69] offset:256
	s_waitcnt vmcnt(9)
; __device__ __forceinline__ float sigmoidf_(float x) { return 1.f / (1.f + __expf(-x)); }
	v_lshlrev_b32_e32 v152, 16, v92
	v_and_b32_e32 v153, 0xffff0000, v92
	v_lshlrev_b32_e32 v154, 16, v93
	v_and_b32_e32 v155, 0xffff0000, v93
	v_lshlrev_b32_e32 v156, 16, v94
	v_and_b32_e32 v157, 0xffff0000, v94
	v_lshlrev_b32_e32 v158, 16, v95
	v_and_b32_e32 v159, 0xffff0000, v95
	v_mul_f32_e32 v152, 0xbfb8aa3b, v152
	v_mul_f32_e32 v153, 0xbfb8aa3b, v153
	v_mul_f32_e32 v154, 0xbfb8aa3b, v154
	v_mul_f32_e32 v155, 0xbfb8aa3b, v155
	v_mul_f32_e32 v156, 0xbfb8aa3b, v156
	v_mul_f32_e32 v157, 0xbfb8aa3b, v157
	v_mul_f32_e32 v158, 0xbfb8aa3b, v158
	v_mul_f32_e32 v159, 0xbfb8aa3b, v159
	v_exp_f32_e32 v152, v152
	v_exp_f32_e32 v153, v153
	v_exp_f32_e32 v154, v154
	v_exp_f32_e32 v155, v155
	v_exp_f32_e32 v156, v156
	v_exp_f32_e32 v157, v157
	v_exp_f32_e32 v158, v158
	v_exp_f32_e32 v159, v159
	v_pk_add_f32 v[152:153], v[152:153], 1.0 op_sel_hi:[1,0]
	v_pk_add_f32 v[154:155], v[154:155], 1.0 op_sel_hi:[1,0]
	v_pk_add_f32 v[156:157], v[156:157], 1.0 op_sel_hi:[1,0]
	v_pk_add_f32 v[158:159], v[158:159], 1.0 op_sel_hi:[1,0]
	v_div_scale_f32 v160, s[2:3], v152, v152, 1.0
	v_rcp_f32_e32 v161, v160
	s_nop 0
	v_fma_f32 v162, -v160, v161, 1.0
	v_fmac_f32_e32 v161, v162, v161
	v_div_scale_f32 v163, vcc, 1.0, v152, 1.0
	v_mul_f32_e32 v164, v163, v161
	v_div_scale_f32 v128, s[2:3], v153, v153, 1.0
	v_fma_f32 v162, -v160, v164, v163
	v_rcp_f32_e32 v129, v128
	v_fmac_f32_e32 v164, v162, v161
	s_nop 0
	v_fma_f32 v160, -v160, v164, v163
	v_fma_f32 v130, -v128, v129, 1.0
	v_div_fmas_f32 v160, v160, v161, v164
	v_fmac_f32_e32 v129, v130, v129
	v_div_fixup_f32 v152, v160, v152, 1.0
	v_div_scale_f32 v131, vcc, 1.0, v153, 1.0
	v_mul_f32_e32 v165, v131, v129
	v_div_scale_f32 v160, s[2:3], v154, v154, 1.0
	v_fma_f32 v130, -v128, v165, v131
	v_rcp_f32_e32 v161, v160
	v_fmac_f32_e32 v165, v130, v129
	s_nop 0
	v_fma_f32 v128, -v128, v165, v131
	v_fma_f32 v162, -v160, v161, 1.0
	v_div_fmas_f32 v128, v128, v129, v165
	v_fmac_f32_e32 v161, v162, v161
	v_div_fixup_f32 v153, v128, v153, 1.0
	v_div_scale_f32 v163, vcc, 1.0, v154, 1.0
	v_mul_f32_e32 v164, v163, v161
	v_div_scale_f32 v128, s[2:3], v155, v155, 1.0
	v_fma_f32 v162, -v160, v164, v163
	v_rcp_f32_e32 v129, v128
	v_fmac_f32_e32 v164, v162, v161
	s_nop 0
	v_fma_f32 v160, -v160, v164, v163
	v_fma_f32 v130, -v128, v129, 1.0
	v_div_fmas_f32 v160, v160, v161, v164
	v_fmac_f32_e32 v129, v130, v129
	v_div_fixup_f32 v154, v160, v154, 1.0
	v_div_scale_f32 v131, vcc, 1.0, v155, 1.0
	v_mul_f32_e32 v165, v131, v129
	v_div_scale_f32 v160, s[2:3], v156, v156, 1.0
	v_fma_f32 v130, -v128, v165, v131
	v_rcp_f32_e32 v161, v160
	v_fmac_f32_e32 v165, v130, v129
	s_nop 0
	v_fma_f32 v128, -v128, v165, v131
	v_fma_f32 v162, -v160, v161, 1.0
	v_div_fmas_f32 v128, v128, v129, v165
	v_fmac_f32_e32 v161, v162, v161
	v_div_fixup_f32 v155, v128, v155, 1.0
	v_div_scale_f32 v163, vcc, 1.0, v156, 1.0
	v_mul_f32_e32 v164, v163, v161
	v_div_scale_f32 v128, s[2:3], v157, v157, 1.0
	v_fma_f32 v162, -v160, v164, v163
	v_rcp_f32_e32 v129, v128
	v_fmac_f32_e32 v164, v162, v161
	s_nop 0
	v_fma_f32 v160, -v160, v164, v163
	v_fma_f32 v130, -v128, v129, 1.0
	v_div_fmas_f32 v160, v160, v161, v164
	v_fmac_f32_e32 v129, v130, v129
	v_div_fixup_f32 v156, v160, v156, 1.0
	v_div_scale_f32 v131, vcc, 1.0, v157, 1.0
	v_mul_f32_e32 v165, v131, v129
	v_div_scale_f32 v160, s[2:3], v158, v158, 1.0
	v_fma_f32 v130, -v128, v165, v131
	v_rcp_f32_e32 v161, v160
	v_fmac_f32_e32 v165, v130, v129
	s_nop 0
	v_fma_f32 v128, -v128, v165, v131
	v_fma_f32 v162, -v160, v161, 1.0
	v_div_fmas_f32 v128, v128, v129, v165
	v_fmac_f32_e32 v161, v162, v161
	v_div_fixup_f32 v157, v128, v157, 1.0
	v_div_scale_f32 v163, vcc, 1.0, v158, 1.0
	v_mul_f32_e32 v164, v163, v161
	v_div_scale_f32 v128, s[2:3], v159, v159, 1.0
	v_fma_f32 v162, -v160, v164, v163
	v_rcp_f32_e32 v129, v128
	v_fmac_f32_e32 v164, v162, v161
	s_nop 0
	v_fma_f32 v160, -v160, v164, v163
	v_fma_f32 v130, -v128, v129, 1.0
	v_div_fmas_f32 v160, v160, v161, v164
	v_fmac_f32_e32 v129, v130, v129
	v_div_fixup_f32 v158, v160, v158, 1.0
	v_div_scale_f32 v131, vcc, 1.0, v159, 1.0
	v_mul_f32_e32 v165, v131, v129
	v_fma_f32 v130, -v128, v165, v131
	v_fmac_f32_e32 v165, v130, v129
	v_fma_f32 v128, -v128, v165, v131
	v_div_fmas_f32 v128, v128, v129, v165
	v_div_fixup_f32 v159, v128, v159, 1.0
	v_lshlrev_b32_e32 v166, 16, v88
	v_and_b32_e32 v167, 0xffff0000, v88
	v_pk_fma_f32 v[152:153], v[60:61], v[152:153], v[166:167]
	v_lshlrev_b32_e32 v166, 16, v89
	v_and_b32_e32 v167, 0xffff0000, v89
	v_pk_fma_f32 v[154:155], v[62:63], v[154:155], v[166:167]
	v_lshlrev_b32_e32 v166, 16, v90
	v_and_b32_e32 v167, 0xffff0000, v90
	v_pk_fma_f32 v[156:157], v[56:57], v[156:157], v[166:167]
	v_lshlrev_b32_e32 v166, 16, v91
	v_and_b32_e32 v167, 0xffff0000, v91
	v_pk_fma_f32 v[158:159], v[58:59], v[158:159], v[166:167]
	v_cvt_pk_bf16_f32 v168, v152, v153
	v_cvt_pk_bf16_f32 v169, v154, v155
	v_cvt_pk_bf16_f32 v170, v156, v157
	v_cvt_pk_bf16_f32 v171, v158, v159
	global_store_dwordx4 v188, v[168:171], s[66:67]
	global_load_dwordx4 v[60:63], v182, s[64:65]
	global_load_dwordx4 v[56:59], v190, s[68:69]
	s_waitcnt vmcnt(9)
; __device__ __forceinline__ float sigmoidf_(float x) { return 1.f / (1.f + __expf(-x)); }
	v_lshlrev_b32_e32 v152, 16, v84
	v_and_b32_e32 v153, 0xffff0000, v84
	v_lshlrev_b32_e32 v154, 16, v85
	v_and_b32_e32 v155, 0xffff0000, v85
	v_lshlrev_b32_e32 v156, 16, v86
	v_and_b32_e32 v157, 0xffff0000, v86
	v_lshlrev_b32_e32 v158, 16, v87
	v_and_b32_e32 v159, 0xffff0000, v87
	v_mul_f32_e32 v152, 0xbfb8aa3b, v152
	v_mul_f32_e32 v153, 0xbfb8aa3b, v153
	v_mul_f32_e32 v154, 0xbfb8aa3b, v154
	v_mul_f32_e32 v155, 0xbfb8aa3b, v155
	v_mul_f32_e32 v156, 0xbfb8aa3b, v156
	v_mul_f32_e32 v157, 0xbfb8aa3b, v157
	v_mul_f32_e32 v158, 0xbfb8aa3b, v158
	v_mul_f32_e32 v159, 0xbfb8aa3b, v159
	v_exp_f32_e32 v152, v152
	v_exp_f32_e32 v153, v153
	v_exp_f32_e32 v154, v154
	v_exp_f32_e32 v155, v155
	v_exp_f32_e32 v156, v156
	v_exp_f32_e32 v157, v157
	v_exp_f32_e32 v158, v158
	v_exp_f32_e32 v159, v159
	v_pk_add_f32 v[152:153], v[152:153], 1.0 op_sel_hi:[1,0]
	v_pk_add_f32 v[154:155], v[154:155], 1.0 op_sel_hi:[1,0]
	v_pk_add_f32 v[156:157], v[156:157], 1.0 op_sel_hi:[1,0]
	v_pk_add_f32 v[158:159], v[158:159], 1.0 op_sel_hi:[1,0]
	v_div_scale_f32 v160, s[2:3], v152, v152, 1.0
	v_rcp_f32_e32 v161, v160
	s_nop 0
	v_fma_f32 v162, -v160, v161, 1.0
	v_fmac_f32_e32 v161, v162, v161
	v_div_scale_f32 v163, vcc, 1.0, v152, 1.0
	v_mul_f32_e32 v164, v163, v161
	v_div_scale_f32 v128, s[2:3], v153, v153, 1.0
	v_fma_f32 v162, -v160, v164, v163
	v_rcp_f32_e32 v129, v128
	v_fmac_f32_e32 v164, v162, v161
	s_nop 0
	v_fma_f32 v160, -v160, v164, v163
	v_fma_f32 v130, -v128, v129, 1.0
	v_div_fmas_f32 v160, v160, v161, v164
	v_fmac_f32_e32 v129, v130, v129
	v_div_fixup_f32 v152, v160, v152, 1.0
	v_div_scale_f32 v131, vcc, 1.0, v153, 1.0
	v_mul_f32_e32 v165, v131, v129
	v_div_scale_f32 v160, s[2:3], v154, v154, 1.0
	v_fma_f32 v130, -v128, v165, v131
	v_rcp_f32_e32 v161, v160
	v_fmac_f32_e32 v165, v130, v129
	s_nop 0
	v_fma_f32 v128, -v128, v165, v131
	v_fma_f32 v162, -v160, v161, 1.0
	v_div_fmas_f32 v128, v128, v129, v165
	v_fmac_f32_e32 v161, v162, v161
	v_div_fixup_f32 v153, v128, v153, 1.0
	v_div_scale_f32 v163, vcc, 1.0, v154, 1.0
	v_mul_f32_e32 v164, v163, v161
	v_div_scale_f32 v128, s[2:3], v155, v155, 1.0
	v_fma_f32 v162, -v160, v164, v163
	v_rcp_f32_e32 v129, v128
	v_fmac_f32_e32 v164, v162, v161
	s_nop 0
	v_fma_f32 v160, -v160, v164, v163
	v_fma_f32 v130, -v128, v129, 1.0
	v_div_fmas_f32 v160, v160, v161, v164
	v_fmac_f32_e32 v129, v130, v129
	v_div_fixup_f32 v154, v160, v154, 1.0
	v_div_scale_f32 v131, vcc, 1.0, v155, 1.0
	v_mul_f32_e32 v165, v131, v129
	v_div_scale_f32 v160, s[2:3], v156, v156, 1.0
	v_fma_f32 v130, -v128, v165, v131
	v_rcp_f32_e32 v161, v160
	v_fmac_f32_e32 v165, v130, v129
	s_nop 0
	v_fma_f32 v128, -v128, v165, v131
	v_fma_f32 v162, -v160, v161, 1.0
	v_div_fmas_f32 v128, v128, v129, v165
	v_fmac_f32_e32 v161, v162, v161
	v_div_fixup_f32 v155, v128, v155, 1.0
	v_div_scale_f32 v163, vcc, 1.0, v156, 1.0
	v_mul_f32_e32 v164, v163, v161
	v_div_scale_f32 v128, s[2:3], v157, v157, 1.0
	v_fma_f32 v162, -v160, v164, v163
	v_rcp_f32_e32 v129, v128
	v_fmac_f32_e32 v164, v162, v161
	s_nop 0
	v_fma_f32 v160, -v160, v164, v163
	v_fma_f32 v130, -v128, v129, 1.0
	v_div_fmas_f32 v160, v160, v161, v164
	v_fmac_f32_e32 v129, v130, v129
	v_div_fixup_f32 v156, v160, v156, 1.0
	v_div_scale_f32 v131, vcc, 1.0, v157, 1.0
	v_mul_f32_e32 v165, v131, v129
	v_div_scale_f32 v160, s[2:3], v158, v158, 1.0
	v_fma_f32 v130, -v128, v165, v131
	v_rcp_f32_e32 v161, v160
	v_fmac_f32_e32 v165, v130, v129
	s_nop 0
	v_fma_f32 v128, -v128, v165, v131
	v_fma_f32 v162, -v160, v161, 1.0
	v_div_fmas_f32 v128, v128, v129, v165
	v_fmac_f32_e32 v161, v162, v161
	v_div_fixup_f32 v157, v128, v157, 1.0
	v_div_scale_f32 v163, vcc, 1.0, v158, 1.0
	v_mul_f32_e32 v164, v163, v161
	v_div_scale_f32 v128, s[2:3], v159, v159, 1.0
	v_fma_f32 v162, -v160, v164, v163
	v_rcp_f32_e32 v129, v128
	v_fmac_f32_e32 v164, v162, v161
	s_nop 0
	v_fma_f32 v160, -v160, v164, v163
	v_fma_f32 v130, -v128, v129, 1.0
	v_div_fmas_f32 v160, v160, v161, v164
	v_fmac_f32_e32 v129, v130, v129
	v_div_fixup_f32 v158, v160, v158, 1.0
	v_div_scale_f32 v131, vcc, 1.0, v159, 1.0
	v_mul_f32_e32 v165, v131, v129
	v_fma_f32 v130, -v128, v165, v131
	v_fmac_f32_e32 v165, v130, v129
	v_fma_f32 v128, -v128, v165, v131
	v_div_fmas_f32 v128, v128, v129, v165
	v_div_fixup_f32 v159, v128, v159, 1.0
	v_lshlrev_b32_e32 v166, 16, v80
	v_and_b32_e32 v167, 0xffff0000, v80
	v_pk_fma_f32 v[152:153], v[52:53], v[152:153], v[166:167]
	v_lshlrev_b32_e32 v166, 16, v81
	v_and_b32_e32 v167, 0xffff0000, v81
	v_pk_fma_f32 v[154:155], v[54:55], v[154:155], v[166:167]
	v_lshlrev_b32_e32 v166, 16, v82
	v_and_b32_e32 v167, 0xffff0000, v82
	v_pk_fma_f32 v[156:157], v[48:49], v[156:157], v[166:167]
	v_lshlrev_b32_e32 v166, 16, v83
	v_and_b32_e32 v167, 0xffff0000, v83
	v_pk_fma_f32 v[158:159], v[50:51], v[158:159], v[166:167]
	v_cvt_pk_bf16_f32 v168, v152, v153
	v_cvt_pk_bf16_f32 v169, v154, v155
	v_cvt_pk_bf16_f32 v170, v156, v157
	v_cvt_pk_bf16_f32 v171, v158, v159
	global_store_dwordx4 v188, v[168:171], s[66:67] offset:256
	global_load_dwordx4 v[52:55], v182, s[64:65] offset:256
	global_load_dwordx4 v[48:51], v190, s[68:69] offset:256
	s_waitcnt vmcnt(9)
; __device__ __forceinline__ float sigmoidf_(float x) { return 1.f / (1.f + __expf(-x)); }
	v_lshlrev_b32_e32 v152, 16, v76
	v_and_b32_e32 v153, 0xffff0000, v76
	v_lshlrev_b32_e32 v154, 16, v77
	v_and_b32_e32 v155, 0xffff0000, v77
	v_lshlrev_b32_e32 v156, 16, v78
	v_and_b32_e32 v157, 0xffff0000, v78
	v_lshlrev_b32_e32 v158, 16, v79
	v_and_b32_e32 v159, 0xffff0000, v79
	v_mul_f32_e32 v152, 0xbfb8aa3b, v152
	v_mul_f32_e32 v153, 0xbfb8aa3b, v153
	v_mul_f32_e32 v154, 0xbfb8aa3b, v154
	v_mul_f32_e32 v155, 0xbfb8aa3b, v155
	v_mul_f32_e32 v156, 0xbfb8aa3b, v156
	v_mul_f32_e32 v157, 0xbfb8aa3b, v157
	v_mul_f32_e32 v158, 0xbfb8aa3b, v158
	v_mul_f32_e32 v159, 0xbfb8aa3b, v159
	v_exp_f32_e32 v152, v152
	v_exp_f32_e32 v153, v153
	v_exp_f32_e32 v154, v154
	v_exp_f32_e32 v155, v155
	v_exp_f32_e32 v156, v156
	v_exp_f32_e32 v157, v157
	v_exp_f32_e32 v158, v158
	v_exp_f32_e32 v159, v159
	v_pk_add_f32 v[152:153], v[152:153], 1.0 op_sel_hi:[1,0]
	v_pk_add_f32 v[154:155], v[154:155], 1.0 op_sel_hi:[1,0]
	v_pk_add_f32 v[156:157], v[156:157], 1.0 op_sel_hi:[1,0]
	v_pk_add_f32 v[158:159], v[158:159], 1.0 op_sel_hi:[1,0]
	v_div_scale_f32 v160, s[2:3], v152, v152, 1.0
	v_rcp_f32_e32 v161, v160
	s_nop 0
	v_fma_f32 v162, -v160, v161, 1.0
	v_fmac_f32_e32 v161, v162, v161
	v_div_scale_f32 v163, vcc, 1.0, v152, 1.0
	v_mul_f32_e32 v164, v163, v161
	v_div_scale_f32 v128, s[2:3], v153, v153, 1.0
	v_fma_f32 v162, -v160, v164, v163
	v_rcp_f32_e32 v129, v128
	v_fmac_f32_e32 v164, v162, v161
	s_nop 0
	v_fma_f32 v160, -v160, v164, v163
	v_fma_f32 v130, -v128, v129, 1.0
	v_div_fmas_f32 v160, v160, v161, v164
	v_fmac_f32_e32 v129, v130, v129
	v_div_fixup_f32 v152, v160, v152, 1.0
	v_div_scale_f32 v131, vcc, 1.0, v153, 1.0
	v_mul_f32_e32 v165, v131, v129
	v_div_scale_f32 v160, s[2:3], v154, v154, 1.0
	v_fma_f32 v130, -v128, v165, v131
	v_rcp_f32_e32 v161, v160
	v_fmac_f32_e32 v165, v130, v129
	s_nop 0
	v_fma_f32 v128, -v128, v165, v131
	v_fma_f32 v162, -v160, v161, 1.0
	v_div_fmas_f32 v128, v128, v129, v165
	v_fmac_f32_e32 v161, v162, v161
	v_div_fixup_f32 v153, v128, v153, 1.0
	v_div_scale_f32 v163, vcc, 1.0, v154, 1.0
	v_mul_f32_e32 v164, v163, v161
	v_div_scale_f32 v128, s[2:3], v155, v155, 1.0
	v_fma_f32 v162, -v160, v164, v163
	v_rcp_f32_e32 v129, v128
	v_fmac_f32_e32 v164, v162, v161
	s_nop 0
	v_fma_f32 v160, -v160, v164, v163
	v_fma_f32 v130, -v128, v129, 1.0
	v_div_fmas_f32 v160, v160, v161, v164
	v_fmac_f32_e32 v129, v130, v129
	v_div_fixup_f32 v154, v160, v154, 1.0
	v_div_scale_f32 v131, vcc, 1.0, v155, 1.0
	v_mul_f32_e32 v165, v131, v129
	v_div_scale_f32 v160, s[2:3], v156, v156, 1.0
	v_fma_f32 v130, -v128, v165, v131
	v_rcp_f32_e32 v161, v160
	v_fmac_f32_e32 v165, v130, v129
	s_nop 0
	v_fma_f32 v128, -v128, v165, v131
	v_fma_f32 v162, -v160, v161, 1.0
	v_div_fmas_f32 v128, v128, v129, v165
	v_fmac_f32_e32 v161, v162, v161
	v_div_fixup_f32 v155, v128, v155, 1.0
	v_div_scale_f32 v163, vcc, 1.0, v156, 1.0
	v_mul_f32_e32 v164, v163, v161
	v_div_scale_f32 v128, s[2:3], v157, v157, 1.0
	v_fma_f32 v162, -v160, v164, v163
	v_rcp_f32_e32 v129, v128
	v_fmac_f32_e32 v164, v162, v161
	s_nop 0
	v_fma_f32 v160, -v160, v164, v163
	v_fma_f32 v130, -v128, v129, 1.0
	v_div_fmas_f32 v160, v160, v161, v164
	v_fmac_f32_e32 v129, v130, v129
	v_div_fixup_f32 v156, v160, v156, 1.0
	v_div_scale_f32 v131, vcc, 1.0, v157, 1.0
	v_mul_f32_e32 v165, v131, v129
	v_div_scale_f32 v160, s[2:3], v158, v158, 1.0
	v_fma_f32 v130, -v128, v165, v131
	v_rcp_f32_e32 v161, v160
	v_fmac_f32_e32 v165, v130, v129
	s_nop 0
	v_fma_f32 v128, -v128, v165, v131
	v_fma_f32 v162, -v160, v161, 1.0
	v_div_fmas_f32 v128, v128, v129, v165
	v_fmac_f32_e32 v161, v162, v161
	v_div_fixup_f32 v157, v128, v157, 1.0
	v_div_scale_f32 v163, vcc, 1.0, v158, 1.0
	v_mul_f32_e32 v164, v163, v161
	v_div_scale_f32 v128, s[2:3], v159, v159, 1.0
	v_fma_f32 v162, -v160, v164, v163
	v_rcp_f32_e32 v129, v128
	v_fmac_f32_e32 v164, v162, v161
	s_nop 0
	v_fma_f32 v160, -v160, v164, v163
	v_fma_f32 v130, -v128, v129, 1.0
	v_div_fmas_f32 v160, v160, v161, v164
	v_fmac_f32_e32 v129, v130, v129
	v_div_fixup_f32 v158, v160, v158, 1.0
	v_div_scale_f32 v131, vcc, 1.0, v159, 1.0
	v_mul_f32_e32 v165, v131, v129
	v_fma_f32 v130, -v128, v165, v131
	v_fmac_f32_e32 v165, v130, v129
	v_fma_f32 v128, -v128, v165, v131
	v_div_fmas_f32 v128, v128, v129, v165
	v_div_fixup_f32 v159, v128, v159, 1.0
	v_lshlrev_b32_e32 v166, 16, v72
	v_and_b32_e32 v167, 0xffff0000, v72
	v_pk_fma_f32 v[152:153], v[44:45], v[152:153], v[166:167]
	v_lshlrev_b32_e32 v166, 16, v73
	v_and_b32_e32 v167, 0xffff0000, v73
	v_pk_fma_f32 v[154:155], v[46:47], v[154:155], v[166:167]
	v_lshlrev_b32_e32 v166, 16, v74
	v_and_b32_e32 v167, 0xffff0000, v74
	v_pk_fma_f32 v[156:157], v[40:41], v[156:157], v[166:167]
	v_lshlrev_b32_e32 v166, 16, v75
	v_and_b32_e32 v167, 0xffff0000, v75
	v_pk_fma_f32 v[158:159], v[42:43], v[158:159], v[166:167]
	v_cvt_pk_bf16_f32 v168, v152, v153
	v_cvt_pk_bf16_f32 v169, v154, v155
	v_cvt_pk_bf16_f32 v170, v156, v157
	v_cvt_pk_bf16_f32 v171, v158, v159
	global_store_dwordx4 v189, v[168:171], s[66:67]
	global_load_dwordx4 v[44:47], v183, s[64:65]
	global_load_dwordx4 v[40:43], v191, s[68:69]
	s_waitcnt vmcnt(9)
; __device__ __forceinline__ float sigmoidf_(float x) { return 1.f / (1.f + __expf(-x)); }
	v_lshlrev_b32_e32 v152, 16, v68
	v_and_b32_e32 v153, 0xffff0000, v68
	v_lshlrev_b32_e32 v154, 16, v69
	v_and_b32_e32 v155, 0xffff0000, v69
	v_lshlrev_b32_e32 v156, 16, v70
	v_and_b32_e32 v157, 0xffff0000, v70
	v_lshlrev_b32_e32 v158, 16, v71
	v_and_b32_e32 v159, 0xffff0000, v71
	v_mul_f32_e32 v152, 0xbfb8aa3b, v152
	v_mul_f32_e32 v153, 0xbfb8aa3b, v153
	v_mul_f32_e32 v154, 0xbfb8aa3b, v154
	v_mul_f32_e32 v155, 0xbfb8aa3b, v155
	v_mul_f32_e32 v156, 0xbfb8aa3b, v156
	v_mul_f32_e32 v157, 0xbfb8aa3b, v157
	v_mul_f32_e32 v158, 0xbfb8aa3b, v158
	v_mul_f32_e32 v159, 0xbfb8aa3b, v159
	v_exp_f32_e32 v152, v152
	v_exp_f32_e32 v153, v153
	v_exp_f32_e32 v154, v154
	v_exp_f32_e32 v155, v155
	v_exp_f32_e32 v156, v156
	v_exp_f32_e32 v157, v157
	v_exp_f32_e32 v158, v158
	v_exp_f32_e32 v159, v159
	v_pk_add_f32 v[152:153], v[152:153], 1.0 op_sel_hi:[1,0]
	v_pk_add_f32 v[154:155], v[154:155], 1.0 op_sel_hi:[1,0]
	v_pk_add_f32 v[156:157], v[156:157], 1.0 op_sel_hi:[1,0]
	v_pk_add_f32 v[158:159], v[158:159], 1.0 op_sel_hi:[1,0]
	v_div_scale_f32 v160, s[2:3], v152, v152, 1.0
	v_rcp_f32_e32 v161, v160
	s_nop 0
	v_fma_f32 v162, -v160, v161, 1.0
	v_fmac_f32_e32 v161, v162, v161
	v_div_scale_f32 v163, vcc, 1.0, v152, 1.0
	v_mul_f32_e32 v164, v163, v161
	v_div_scale_f32 v128, s[2:3], v153, v153, 1.0
	v_fma_f32 v162, -v160, v164, v163
	v_rcp_f32_e32 v129, v128
	v_fmac_f32_e32 v164, v162, v161
	s_nop 0
	v_fma_f32 v160, -v160, v164, v163
	v_fma_f32 v130, -v128, v129, 1.0
	v_div_fmas_f32 v160, v160, v161, v164
	v_fmac_f32_e32 v129, v130, v129
	v_div_fixup_f32 v152, v160, v152, 1.0
	v_div_scale_f32 v131, vcc, 1.0, v153, 1.0
	v_mul_f32_e32 v165, v131, v129
	v_div_scale_f32 v160, s[2:3], v154, v154, 1.0
	v_fma_f32 v130, -v128, v165, v131
	v_rcp_f32_e32 v161, v160
	v_fmac_f32_e32 v165, v130, v129
	s_nop 0
	v_fma_f32 v128, -v128, v165, v131
	v_fma_f32 v162, -v160, v161, 1.0
	v_div_fmas_f32 v128, v128, v129, v165
	v_fmac_f32_e32 v161, v162, v161
	v_div_fixup_f32 v153, v128, v153, 1.0
	v_div_scale_f32 v163, vcc, 1.0, v154, 1.0
	v_mul_f32_e32 v164, v163, v161
	v_div_scale_f32 v128, s[2:3], v155, v155, 1.0
	v_fma_f32 v162, -v160, v164, v163
	v_rcp_f32_e32 v129, v128
	v_fmac_f32_e32 v164, v162, v161
	s_nop 0
	v_fma_f32 v160, -v160, v164, v163
	v_fma_f32 v130, -v128, v129, 1.0
	v_div_fmas_f32 v160, v160, v161, v164
	v_fmac_f32_e32 v129, v130, v129
	v_div_fixup_f32 v154, v160, v154, 1.0
	v_div_scale_f32 v131, vcc, 1.0, v155, 1.0
	v_mul_f32_e32 v165, v131, v129
	v_div_scale_f32 v160, s[2:3], v156, v156, 1.0
	v_fma_f32 v130, -v128, v165, v131
	v_rcp_f32_e32 v161, v160
	v_fmac_f32_e32 v165, v130, v129
	s_nop 0
	v_fma_f32 v128, -v128, v165, v131
	v_fma_f32 v162, -v160, v161, 1.0
	v_div_fmas_f32 v128, v128, v129, v165
	v_fmac_f32_e32 v161, v162, v161
	v_div_fixup_f32 v155, v128, v155, 1.0
	v_div_scale_f32 v163, vcc, 1.0, v156, 1.0
	v_mul_f32_e32 v164, v163, v161
	v_div_scale_f32 v128, s[2:3], v157, v157, 1.0
	v_fma_f32 v162, -v160, v164, v163
	v_rcp_f32_e32 v129, v128
	v_fmac_f32_e32 v164, v162, v161
	s_nop 0
	v_fma_f32 v160, -v160, v164, v163
	v_fma_f32 v130, -v128, v129, 1.0
	v_div_fmas_f32 v160, v160, v161, v164
	v_fmac_f32_e32 v129, v130, v129
	v_div_fixup_f32 v156, v160, v156, 1.0
	v_div_scale_f32 v131, vcc, 1.0, v157, 1.0
	v_mul_f32_e32 v165, v131, v129
	v_div_scale_f32 v160, s[2:3], v158, v158, 1.0
	v_fma_f32 v130, -v128, v165, v131
	v_rcp_f32_e32 v161, v160
	v_fmac_f32_e32 v165, v130, v129
	s_nop 0
	v_fma_f32 v128, -v128, v165, v131
	v_fma_f32 v162, -v160, v161, 1.0
	v_div_fmas_f32 v128, v128, v129, v165
	v_fmac_f32_e32 v161, v162, v161
	v_div_fixup_f32 v157, v128, v157, 1.0
	v_div_scale_f32 v163, vcc, 1.0, v158, 1.0
	v_mul_f32_e32 v164, v163, v161
	v_div_scale_f32 v128, s[2:3], v159, v159, 1.0
	v_fma_f32 v162, -v160, v164, v163
	v_rcp_f32_e32 v129, v128
	v_fmac_f32_e32 v164, v162, v161
	s_nop 0
	v_fma_f32 v160, -v160, v164, v163
	v_fma_f32 v130, -v128, v129, 1.0
	v_div_fmas_f32 v160, v160, v161, v164
	v_fmac_f32_e32 v129, v130, v129
	v_div_fixup_f32 v158, v160, v158, 1.0
	v_div_scale_f32 v131, vcc, 1.0, v159, 1.0
	v_mul_f32_e32 v165, v131, v129
	v_fma_f32 v130, -v128, v165, v131
	v_fmac_f32_e32 v165, v130, v129
	v_fma_f32 v128, -v128, v165, v131
	v_div_fmas_f32 v128, v128, v129, v165
	v_div_fixup_f32 v159, v128, v159, 1.0
	v_lshlrev_b32_e32 v166, 16, v64
	v_and_b32_e32 v167, 0xffff0000, v64
	v_pk_fma_f32 v[152:153], v[36:37], v[152:153], v[166:167]
	v_lshlrev_b32_e32 v166, 16, v65
	v_and_b32_e32 v167, 0xffff0000, v65
	v_pk_fma_f32 v[154:155], v[38:39], v[154:155], v[166:167]
	v_lshlrev_b32_e32 v166, 16, v66
	v_and_b32_e32 v167, 0xffff0000, v66
	v_pk_fma_f32 v[156:157], v[32:33], v[156:157], v[166:167]
	v_lshlrev_b32_e32 v166, 16, v67
	v_and_b32_e32 v167, 0xffff0000, v67
	v_pk_fma_f32 v[158:159], v[34:35], v[158:159], v[166:167]
	v_cvt_pk_bf16_f32 v168, v152, v153
	v_cvt_pk_bf16_f32 v169, v154, v155
	v_cvt_pk_bf16_f32 v170, v156, v157
	v_cvt_pk_bf16_f32 v171, v158, v159
	global_store_dwordx4 v189, v[168:171], s[66:67] offset:256
	global_load_dwordx4 v[36:39], v183, s[64:65] offset:256
	global_load_dwordx4 v[32:35], v191, s[68:69] offset:256
	s_waitcnt vmcnt(9)
; __device__ __forceinline__ float sigmoidf_(float x) { return 1.f / (1.f + __expf(-x)); }
	v_lshlrev_b32_e32 v152, 16, v60
	v_and_b32_e32 v153, 0xffff0000, v60
	v_lshlrev_b32_e32 v154, 16, v61
	v_and_b32_e32 v155, 0xffff0000, v61
	v_lshlrev_b32_e32 v156, 16, v62
	v_and_b32_e32 v157, 0xffff0000, v62
	v_lshlrev_b32_e32 v158, 16, v63
	v_and_b32_e32 v159, 0xffff0000, v63
	v_mul_f32_e32 v152, 0xbfb8aa3b, v152
	v_mul_f32_e32 v153, 0xbfb8aa3b, v153
	v_mul_f32_e32 v154, 0xbfb8aa3b, v154
	v_mul_f32_e32 v155, 0xbfb8aa3b, v155
	v_mul_f32_e32 v156, 0xbfb8aa3b, v156
	v_mul_f32_e32 v157, 0xbfb8aa3b, v157
	v_mul_f32_e32 v158, 0xbfb8aa3b, v158
	v_mul_f32_e32 v159, 0xbfb8aa3b, v159
	v_exp_f32_e32 v152, v152
	v_exp_f32_e32 v153, v153
	v_exp_f32_e32 v154, v154
	v_exp_f32_e32 v155, v155
	v_exp_f32_e32 v156, v156
	v_exp_f32_e32 v157, v157
	v_exp_f32_e32 v158, v158
	v_exp_f32_e32 v159, v159
	v_pk_add_f32 v[152:153], v[152:153], 1.0 op_sel_hi:[1,0]
	v_pk_add_f32 v[154:155], v[154:155], 1.0 op_sel_hi:[1,0]
	v_pk_add_f32 v[156:157], v[156:157], 1.0 op_sel_hi:[1,0]
	v_pk_add_f32 v[158:159], v[158:159], 1.0 op_sel_hi:[1,0]
	v_div_scale_f32 v160, s[2:3], v152, v152, 1.0
	v_rcp_f32_e32 v161, v160
	s_nop 0
	v_fma_f32 v162, -v160, v161, 1.0
	v_fmac_f32_e32 v161, v162, v161
	v_div_scale_f32 v163, vcc, 1.0, v152, 1.0
	v_mul_f32_e32 v164, v163, v161
	v_div_scale_f32 v128, s[2:3], v153, v153, 1.0
	v_fma_f32 v162, -v160, v164, v163
	v_rcp_f32_e32 v129, v128
	v_fmac_f32_e32 v164, v162, v161
	s_nop 0
	v_fma_f32 v160, -v160, v164, v163
	v_fma_f32 v130, -v128, v129, 1.0
	v_div_fmas_f32 v160, v160, v161, v164
	v_fmac_f32_e32 v129, v130, v129
	v_div_fixup_f32 v152, v160, v152, 1.0
	v_div_scale_f32 v131, vcc, 1.0, v153, 1.0
	v_mul_f32_e32 v165, v131, v129
	v_div_scale_f32 v160, s[2:3], v154, v154, 1.0
	v_fma_f32 v130, -v128, v165, v131
	v_rcp_f32_e32 v161, v160
	v_fmac_f32_e32 v165, v130, v129
	s_nop 0
	v_fma_f32 v128, -v128, v165, v131
	v_fma_f32 v162, -v160, v161, 1.0
	v_div_fmas_f32 v128, v128, v129, v165
	v_fmac_f32_e32 v161, v162, v161
	v_div_fixup_f32 v153, v128, v153, 1.0
	v_div_scale_f32 v163, vcc, 1.0, v154, 1.0
	v_mul_f32_e32 v164, v163, v161
	v_div_scale_f32 v128, s[2:3], v155, v155, 1.0
	v_fma_f32 v162, -v160, v164, v163
	v_rcp_f32_e32 v129, v128
	v_fmac_f32_e32 v164, v162, v161
	s_nop 0
	v_fma_f32 v160, -v160, v164, v163
	v_fma_f32 v130, -v128, v129, 1.0
	v_div_fmas_f32 v160, v160, v161, v164
	v_fmac_f32_e32 v129, v130, v129
	v_div_fixup_f32 v154, v160, v154, 1.0
	v_div_scale_f32 v131, vcc, 1.0, v155, 1.0
	v_mul_f32_e32 v165, v131, v129
	v_div_scale_f32 v160, s[2:3], v156, v156, 1.0
	v_fma_f32 v130, -v128, v165, v131
	v_rcp_f32_e32 v161, v160
	v_fmac_f32_e32 v165, v130, v129
	s_nop 0
	v_fma_f32 v128, -v128, v165, v131
	v_fma_f32 v162, -v160, v161, 1.0
	v_div_fmas_f32 v128, v128, v129, v165
	v_fmac_f32_e32 v161, v162, v161
	v_div_fixup_f32 v155, v128, v155, 1.0
	v_div_scale_f32 v163, vcc, 1.0, v156, 1.0
	v_mul_f32_e32 v164, v163, v161
	v_div_scale_f32 v128, s[2:3], v157, v157, 1.0
	v_fma_f32 v162, -v160, v164, v163
	v_rcp_f32_e32 v129, v128
	v_fmac_f32_e32 v164, v162, v161
	s_nop 0
	v_fma_f32 v160, -v160, v164, v163
	v_fma_f32 v130, -v128, v129, 1.0
	v_div_fmas_f32 v160, v160, v161, v164
	v_fmac_f32_e32 v129, v130, v129
	v_div_fixup_f32 v156, v160, v156, 1.0
	v_div_scale_f32 v131, vcc, 1.0, v157, 1.0
	v_mul_f32_e32 v165, v131, v129
	v_div_scale_f32 v160, s[2:3], v158, v158, 1.0
	v_fma_f32 v130, -v128, v165, v131
	v_rcp_f32_e32 v161, v160
	v_fmac_f32_e32 v165, v130, v129
	s_nop 0
	v_fma_f32 v128, -v128, v165, v131
	v_fma_f32 v162, -v160, v161, 1.0
	v_div_fmas_f32 v128, v128, v129, v165
	v_fmac_f32_e32 v161, v162, v161
	v_div_fixup_f32 v157, v128, v157, 1.0
	v_div_scale_f32 v163, vcc, 1.0, v158, 1.0
	v_mul_f32_e32 v164, v163, v161
	v_div_scale_f32 v128, s[2:3], v159, v159, 1.0
	v_fma_f32 v162, -v160, v164, v163
	v_rcp_f32_e32 v129, v128
	v_fmac_f32_e32 v164, v162, v161
	s_nop 0
	v_fma_f32 v160, -v160, v164, v163
	v_fma_f32 v130, -v128, v129, 1.0
	v_div_fmas_f32 v160, v160, v161, v164
	v_fmac_f32_e32 v129, v130, v129
	v_div_fixup_f32 v158, v160, v158, 1.0
	v_div_scale_f32 v131, vcc, 1.0, v159, 1.0
	v_mul_f32_e32 v165, v131, v129
	v_fma_f32 v130, -v128, v165, v131
	v_fmac_f32_e32 v165, v130, v129
	v_fma_f32 v128, -v128, v165, v131
	v_div_fmas_f32 v128, v128, v129, v165
	v_div_fixup_f32 v159, v128, v159, 1.0
	v_lshlrev_b32_e32 v166, 16, v56
	v_and_b32_e32 v167, 0xffff0000, v56
	v_pk_fma_f32 v[152:153], v[28:29], v[152:153], v[166:167]
	v_lshlrev_b32_e32 v166, 16, v57
	v_and_b32_e32 v167, 0xffff0000, v57
	v_pk_fma_f32 v[154:155], v[30:31], v[154:155], v[166:167]
	v_lshlrev_b32_e32 v166, 16, v58
	v_and_b32_e32 v167, 0xffff0000, v58
	v_pk_fma_f32 v[156:157], v[24:25], v[156:157], v[166:167]
	v_lshlrev_b32_e32 v166, 16, v59
	v_and_b32_e32 v167, 0xffff0000, v59
	v_pk_fma_f32 v[158:159], v[26:27], v[158:159], v[166:167]
	v_cvt_pk_bf16_f32 v168, v152, v153
	v_cvt_pk_bf16_f32 v169, v154, v155
	v_cvt_pk_bf16_f32 v170, v156, v157
	v_cvt_pk_bf16_f32 v171, v158, v159
	global_store_dwordx4 v190, v[168:171], s[66:67]
	s_waitcnt vmcnt(7)
; __device__ __forceinline__ float sigmoidf_(float x) { return 1.f / (1.f + __expf(-x)); }
	v_lshlrev_b32_e32 v152, 16, v52
	v_and_b32_e32 v153, 0xffff0000, v52
	v_lshlrev_b32_e32 v154, 16, v53
	v_and_b32_e32 v155, 0xffff0000, v53
	v_lshlrev_b32_e32 v156, 16, v54
	v_and_b32_e32 v157, 0xffff0000, v54
	v_lshlrev_b32_e32 v158, 16, v55
	v_and_b32_e32 v159, 0xffff0000, v55
	v_mul_f32_e32 v152, 0xbfb8aa3b, v152
	v_mul_f32_e32 v153, 0xbfb8aa3b, v153
	v_mul_f32_e32 v154, 0xbfb8aa3b, v154
	v_mul_f32_e32 v155, 0xbfb8aa3b, v155
	v_mul_f32_e32 v156, 0xbfb8aa3b, v156
	v_mul_f32_e32 v157, 0xbfb8aa3b, v157
	v_mul_f32_e32 v158, 0xbfb8aa3b, v158
	v_mul_f32_e32 v159, 0xbfb8aa3b, v159
	v_exp_f32_e32 v152, v152
	v_exp_f32_e32 v153, v153
	v_exp_f32_e32 v154, v154
	v_exp_f32_e32 v155, v155
	v_exp_f32_e32 v156, v156
	v_exp_f32_e32 v157, v157
	v_exp_f32_e32 v158, v158
	v_exp_f32_e32 v159, v159
	v_pk_add_f32 v[152:153], v[152:153], 1.0 op_sel_hi:[1,0]
	v_pk_add_f32 v[154:155], v[154:155], 1.0 op_sel_hi:[1,0]
	v_pk_add_f32 v[156:157], v[156:157], 1.0 op_sel_hi:[1,0]
	v_pk_add_f32 v[158:159], v[158:159], 1.0 op_sel_hi:[1,0]
	v_div_scale_f32 v160, s[2:3], v152, v152, 1.0
	v_rcp_f32_e32 v161, v160
	s_nop 0
	v_fma_f32 v162, -v160, v161, 1.0
	v_fmac_f32_e32 v161, v162, v161
	v_div_scale_f32 v163, vcc, 1.0, v152, 1.0
	v_mul_f32_e32 v164, v163, v161
	v_div_scale_f32 v128, s[2:3], v153, v153, 1.0
	v_fma_f32 v162, -v160, v164, v163
	v_rcp_f32_e32 v129, v128
	v_fmac_f32_e32 v164, v162, v161
	s_nop 0
	v_fma_f32 v160, -v160, v164, v163
	v_fma_f32 v130, -v128, v129, 1.0
	v_div_fmas_f32 v160, v160, v161, v164
	v_fmac_f32_e32 v129, v130, v129
	v_div_fixup_f32 v152, v160, v152, 1.0
	v_div_scale_f32 v131, vcc, 1.0, v153, 1.0
	v_mul_f32_e32 v165, v131, v129
	v_div_scale_f32 v160, s[2:3], v154, v154, 1.0
	v_fma_f32 v130, -v128, v165, v131
	v_rcp_f32_e32 v161, v160
	v_fmac_f32_e32 v165, v130, v129
	s_nop 0
	v_fma_f32 v128, -v128, v165, v131
	v_fma_f32 v162, -v160, v161, 1.0
	v_div_fmas_f32 v128, v128, v129, v165
	v_fmac_f32_e32 v161, v162, v161
	v_div_fixup_f32 v153, v128, v153, 1.0
	v_div_scale_f32 v163, vcc, 1.0, v154, 1.0
	v_mul_f32_e32 v164, v163, v161
	v_div_scale_f32 v128, s[2:3], v155, v155, 1.0
	v_fma_f32 v162, -v160, v164, v163
	v_rcp_f32_e32 v129, v128
	v_fmac_f32_e32 v164, v162, v161
	s_nop 0
	v_fma_f32 v160, -v160, v164, v163
	v_fma_f32 v130, -v128, v129, 1.0
	v_div_fmas_f32 v160, v160, v161, v164
	v_fmac_f32_e32 v129, v130, v129
	v_div_fixup_f32 v154, v160, v154, 1.0
	v_div_scale_f32 v131, vcc, 1.0, v155, 1.0
	v_mul_f32_e32 v165, v131, v129
	v_div_scale_f32 v160, s[2:3], v156, v156, 1.0
	v_fma_f32 v130, -v128, v165, v131
	v_rcp_f32_e32 v161, v160
	v_fmac_f32_e32 v165, v130, v129
	s_nop 0
	v_fma_f32 v128, -v128, v165, v131
	v_fma_f32 v162, -v160, v161, 1.0
	v_div_fmas_f32 v128, v128, v129, v165
	v_fmac_f32_e32 v161, v162, v161
	v_div_fixup_f32 v155, v128, v155, 1.0
	v_div_scale_f32 v163, vcc, 1.0, v156, 1.0
	v_mul_f32_e32 v164, v163, v161
	v_div_scale_f32 v128, s[2:3], v157, v157, 1.0
	v_fma_f32 v162, -v160, v164, v163
	v_rcp_f32_e32 v129, v128
	v_fmac_f32_e32 v164, v162, v161
	s_nop 0
	v_fma_f32 v160, -v160, v164, v163
	v_fma_f32 v130, -v128, v129, 1.0
	v_div_fmas_f32 v160, v160, v161, v164
	v_fmac_f32_e32 v129, v130, v129
	v_div_fixup_f32 v156, v160, v156, 1.0
	v_div_scale_f32 v131, vcc, 1.0, v157, 1.0
	v_mul_f32_e32 v165, v131, v129
	v_div_scale_f32 v160, s[2:3], v158, v158, 1.0
	v_fma_f32 v130, -v128, v165, v131
	v_rcp_f32_e32 v161, v160
	v_fmac_f32_e32 v165, v130, v129
	s_nop 0
	v_fma_f32 v128, -v128, v165, v131
	v_fma_f32 v162, -v160, v161, 1.0
	v_div_fmas_f32 v128, v128, v129, v165
	v_fmac_f32_e32 v161, v162, v161
	v_div_fixup_f32 v157, v128, v157, 1.0
	v_div_scale_f32 v163, vcc, 1.0, v158, 1.0
	v_mul_f32_e32 v164, v163, v161
	v_div_scale_f32 v128, s[2:3], v159, v159, 1.0
	v_fma_f32 v162, -v160, v164, v163
	v_rcp_f32_e32 v129, v128
	v_fmac_f32_e32 v164, v162, v161
	s_nop 0
	v_fma_f32 v160, -v160, v164, v163
	v_fma_f32 v130, -v128, v129, 1.0
	v_div_fmas_f32 v160, v160, v161, v164
	v_fmac_f32_e32 v129, v130, v129
	v_div_fixup_f32 v158, v160, v158, 1.0
	v_div_scale_f32 v131, vcc, 1.0, v159, 1.0
	v_mul_f32_e32 v165, v131, v129
	v_fma_f32 v130, -v128, v165, v131
	v_fmac_f32_e32 v165, v130, v129
	v_fma_f32 v128, -v128, v165, v131
	v_div_fmas_f32 v128, v128, v129, v165
	v_div_fixup_f32 v159, v128, v159, 1.0
	v_lshlrev_b32_e32 v166, 16, v48
	v_and_b32_e32 v167, 0xffff0000, v48
	v_pk_fma_f32 v[152:153], v[20:21], v[152:153], v[166:167]
	v_lshlrev_b32_e32 v166, 16, v49
	v_and_b32_e32 v167, 0xffff0000, v49
	v_pk_fma_f32 v[154:155], v[22:23], v[154:155], v[166:167]
	v_lshlrev_b32_e32 v166, 16, v50
	v_and_b32_e32 v167, 0xffff0000, v50
	v_pk_fma_f32 v[156:157], v[16:17], v[156:157], v[166:167]
	v_lshlrev_b32_e32 v166, 16, v51
	v_and_b32_e32 v167, 0xffff0000, v51
	v_pk_fma_f32 v[158:159], v[18:19], v[158:159], v[166:167]
	v_cvt_pk_bf16_f32 v168, v152, v153
	v_cvt_pk_bf16_f32 v169, v154, v155
	v_cvt_pk_bf16_f32 v170, v156, v157
	v_cvt_pk_bf16_f32 v171, v158, v159
	global_store_dwordx4 v190, v[168:171], s[66:67] offset:256
	s_waitcnt vmcnt(5)
; __device__ __forceinline__ float sigmoidf_(float x) { return 1.f / (1.f + __expf(-x)); }
	v_lshlrev_b32_e32 v152, 16, v44
	v_and_b32_e32 v153, 0xffff0000, v44
	v_lshlrev_b32_e32 v154, 16, v45
	v_and_b32_e32 v155, 0xffff0000, v45
	v_lshlrev_b32_e32 v156, 16, v46
	v_and_b32_e32 v157, 0xffff0000, v46
	v_lshlrev_b32_e32 v158, 16, v47
	v_and_b32_e32 v159, 0xffff0000, v47
	v_mul_f32_e32 v152, 0xbfb8aa3b, v152
	v_mul_f32_e32 v153, 0xbfb8aa3b, v153
	v_mul_f32_e32 v154, 0xbfb8aa3b, v154
	v_mul_f32_e32 v155, 0xbfb8aa3b, v155
	v_mul_f32_e32 v156, 0xbfb8aa3b, v156
	v_mul_f32_e32 v157, 0xbfb8aa3b, v157
	v_mul_f32_e32 v158, 0xbfb8aa3b, v158
	v_mul_f32_e32 v159, 0xbfb8aa3b, v159
	v_exp_f32_e32 v152, v152
	v_exp_f32_e32 v153, v153
	v_exp_f32_e32 v154, v154
	v_exp_f32_e32 v155, v155
	v_exp_f32_e32 v156, v156
	v_exp_f32_e32 v157, v157
	v_exp_f32_e32 v158, v158
	v_exp_f32_e32 v159, v159
	v_pk_add_f32 v[152:153], v[152:153], 1.0 op_sel_hi:[1,0]
	v_pk_add_f32 v[154:155], v[154:155], 1.0 op_sel_hi:[1,0]
	v_pk_add_f32 v[156:157], v[156:157], 1.0 op_sel_hi:[1,0]
	v_pk_add_f32 v[158:159], v[158:159], 1.0 op_sel_hi:[1,0]
	v_div_scale_f32 v160, s[2:3], v152, v152, 1.0
	v_rcp_f32_e32 v161, v160
	s_nop 0
	v_fma_f32 v162, -v160, v161, 1.0
	v_fmac_f32_e32 v161, v162, v161
	v_div_scale_f32 v163, vcc, 1.0, v152, 1.0
	v_mul_f32_e32 v164, v163, v161
	v_div_scale_f32 v128, s[2:3], v153, v153, 1.0
	v_fma_f32 v162, -v160, v164, v163
	v_rcp_f32_e32 v129, v128
	v_fmac_f32_e32 v164, v162, v161
	s_nop 0
	v_fma_f32 v160, -v160, v164, v163
	v_fma_f32 v130, -v128, v129, 1.0
	v_div_fmas_f32 v160, v160, v161, v164
	v_fmac_f32_e32 v129, v130, v129
	v_div_fixup_f32 v152, v160, v152, 1.0
	v_div_scale_f32 v131, vcc, 1.0, v153, 1.0
	v_mul_f32_e32 v165, v131, v129
	v_div_scale_f32 v160, s[2:3], v154, v154, 1.0
	v_fma_f32 v130, -v128, v165, v131
	v_rcp_f32_e32 v161, v160
	v_fmac_f32_e32 v165, v130, v129
	s_nop 0
	v_fma_f32 v128, -v128, v165, v131
	v_fma_f32 v162, -v160, v161, 1.0
	v_div_fmas_f32 v128, v128, v129, v165
	v_fmac_f32_e32 v161, v162, v161
	v_div_fixup_f32 v153, v128, v153, 1.0
	v_div_scale_f32 v163, vcc, 1.0, v154, 1.0
	v_mul_f32_e32 v164, v163, v161
	v_div_scale_f32 v128, s[2:3], v155, v155, 1.0
	v_fma_f32 v162, -v160, v164, v163
	v_rcp_f32_e32 v129, v128
	v_fmac_f32_e32 v164, v162, v161
	s_nop 0
	v_fma_f32 v160, -v160, v164, v163
	v_fma_f32 v130, -v128, v129, 1.0
	v_div_fmas_f32 v160, v160, v161, v164
	v_fmac_f32_e32 v129, v130, v129
	v_div_fixup_f32 v154, v160, v154, 1.0
	v_div_scale_f32 v131, vcc, 1.0, v155, 1.0
	v_mul_f32_e32 v165, v131, v129
	v_div_scale_f32 v160, s[2:3], v156, v156, 1.0
	v_fma_f32 v130, -v128, v165, v131
	v_rcp_f32_e32 v161, v160
	v_fmac_f32_e32 v165, v130, v129
	s_nop 0
	v_fma_f32 v128, -v128, v165, v131
	v_fma_f32 v162, -v160, v161, 1.0
	v_div_fmas_f32 v128, v128, v129, v165
	v_fmac_f32_e32 v161, v162, v161
	v_div_fixup_f32 v155, v128, v155, 1.0
	v_div_scale_f32 v163, vcc, 1.0, v156, 1.0
	v_mul_f32_e32 v164, v163, v161
	v_div_scale_f32 v128, s[2:3], v157, v157, 1.0
	v_fma_f32 v162, -v160, v164, v163
	v_rcp_f32_e32 v129, v128
	v_fmac_f32_e32 v164, v162, v161
	s_nop 0
	v_fma_f32 v160, -v160, v164, v163
	v_fma_f32 v130, -v128, v129, 1.0
	v_div_fmas_f32 v160, v160, v161, v164
	v_fmac_f32_e32 v129, v130, v129
	v_div_fixup_f32 v156, v160, v156, 1.0
	v_div_scale_f32 v131, vcc, 1.0, v157, 1.0
	v_mul_f32_e32 v165, v131, v129
	v_div_scale_f32 v160, s[2:3], v158, v158, 1.0
	v_fma_f32 v130, -v128, v165, v131
	v_rcp_f32_e32 v161, v160
	v_fmac_f32_e32 v165, v130, v129
	s_nop 0
	v_fma_f32 v128, -v128, v165, v131
	v_fma_f32 v162, -v160, v161, 1.0
	v_div_fmas_f32 v128, v128, v129, v165
	v_fmac_f32_e32 v161, v162, v161
	v_div_fixup_f32 v157, v128, v157, 1.0
	v_div_scale_f32 v163, vcc, 1.0, v158, 1.0
	v_mul_f32_e32 v164, v163, v161
	v_div_scale_f32 v128, s[2:3], v159, v159, 1.0
	v_fma_f32 v162, -v160, v164, v163
	v_rcp_f32_e32 v129, v128
	v_fmac_f32_e32 v164, v162, v161
	s_nop 0
	v_fma_f32 v160, -v160, v164, v163
	v_fma_f32 v130, -v128, v129, 1.0
	v_div_fmas_f32 v160, v160, v161, v164
	v_fmac_f32_e32 v129, v130, v129
	v_div_fixup_f32 v158, v160, v158, 1.0
	v_div_scale_f32 v131, vcc, 1.0, v159, 1.0
	v_mul_f32_e32 v165, v131, v129
	v_fma_f32 v130, -v128, v165, v131
	v_fmac_f32_e32 v165, v130, v129
	v_fma_f32 v128, -v128, v165, v131
	v_div_fmas_f32 v128, v128, v129, v165
	v_div_fixup_f32 v159, v128, v159, 1.0
	v_lshlrev_b32_e32 v166, 16, v40
	v_and_b32_e32 v167, 0xffff0000, v40
	v_pk_fma_f32 v[152:153], v[12:13], v[152:153], v[166:167]
	v_lshlrev_b32_e32 v166, 16, v41
	v_and_b32_e32 v167, 0xffff0000, v41
	v_pk_fma_f32 v[154:155], v[14:15], v[154:155], v[166:167]
	v_lshlrev_b32_e32 v166, 16, v42
	v_and_b32_e32 v167, 0xffff0000, v42
	v_pk_fma_f32 v[156:157], v[8:9], v[156:157], v[166:167]
	v_lshlrev_b32_e32 v166, 16, v43
	v_and_b32_e32 v167, 0xffff0000, v43
	v_pk_fma_f32 v[158:159], v[10:11], v[158:159], v[166:167]
	v_cvt_pk_bf16_f32 v168, v152, v153
	v_cvt_pk_bf16_f32 v169, v154, v155
	v_cvt_pk_bf16_f32 v170, v156, v157
	v_cvt_pk_bf16_f32 v171, v158, v159
	global_store_dwordx4 v191, v[168:171], s[66:67]
	s_waitcnt vmcnt(3)
; __device__ __forceinline__ float sigmoidf_(float x) { return 1.f / (1.f + __expf(-x)); }
	v_lshlrev_b32_e32 v152, 16, v36
	v_and_b32_e32 v153, 0xffff0000, v36
	v_lshlrev_b32_e32 v154, 16, v37
	v_and_b32_e32 v155, 0xffff0000, v37
	v_lshlrev_b32_e32 v156, 16, v38
	v_and_b32_e32 v157, 0xffff0000, v38
	v_lshlrev_b32_e32 v158, 16, v39
	v_and_b32_e32 v159, 0xffff0000, v39
	v_mul_f32_e32 v152, 0xbfb8aa3b, v152
	v_mul_f32_e32 v153, 0xbfb8aa3b, v153
	v_mul_f32_e32 v154, 0xbfb8aa3b, v154
	v_mul_f32_e32 v155, 0xbfb8aa3b, v155
	v_mul_f32_e32 v156, 0xbfb8aa3b, v156
	v_mul_f32_e32 v157, 0xbfb8aa3b, v157
	v_mul_f32_e32 v158, 0xbfb8aa3b, v158
	v_mul_f32_e32 v159, 0xbfb8aa3b, v159
	v_exp_f32_e32 v152, v152
	v_exp_f32_e32 v153, v153
	v_exp_f32_e32 v154, v154
	v_exp_f32_e32 v155, v155
	v_exp_f32_e32 v156, v156
	v_exp_f32_e32 v157, v157
	v_exp_f32_e32 v158, v158
	v_exp_f32_e32 v159, v159
	v_pk_add_f32 v[152:153], v[152:153], 1.0 op_sel_hi:[1,0]
	v_pk_add_f32 v[154:155], v[154:155], 1.0 op_sel_hi:[1,0]
	v_pk_add_f32 v[156:157], v[156:157], 1.0 op_sel_hi:[1,0]
	v_pk_add_f32 v[158:159], v[158:159], 1.0 op_sel_hi:[1,0]
	v_div_scale_f32 v160, s[2:3], v152, v152, 1.0
	v_rcp_f32_e32 v161, v160
	s_nop 0
	v_fma_f32 v162, -v160, v161, 1.0
	v_fmac_f32_e32 v161, v162, v161
	v_div_scale_f32 v163, vcc, 1.0, v152, 1.0
	v_mul_f32_e32 v164, v163, v161
	v_div_scale_f32 v128, s[2:3], v153, v153, 1.0
	v_fma_f32 v162, -v160, v164, v163
	v_rcp_f32_e32 v129, v128
	v_fmac_f32_e32 v164, v162, v161
	s_nop 0
	v_fma_f32 v160, -v160, v164, v163
	v_fma_f32 v130, -v128, v129, 1.0
	v_div_fmas_f32 v160, v160, v161, v164
	v_fmac_f32_e32 v129, v130, v129
	v_div_fixup_f32 v152, v160, v152, 1.0
	v_div_scale_f32 v131, vcc, 1.0, v153, 1.0
	v_mul_f32_e32 v165, v131, v129
	v_div_scale_f32 v160, s[2:3], v154, v154, 1.0
	v_fma_f32 v130, -v128, v165, v131
	v_rcp_f32_e32 v161, v160
	v_fmac_f32_e32 v165, v130, v129
	s_nop 0
	v_fma_f32 v128, -v128, v165, v131
	v_fma_f32 v162, -v160, v161, 1.0
	v_div_fmas_f32 v128, v128, v129, v165
	v_fmac_f32_e32 v161, v162, v161
	v_div_fixup_f32 v153, v128, v153, 1.0
	v_div_scale_f32 v163, vcc, 1.0, v154, 1.0
	v_mul_f32_e32 v164, v163, v161
	v_div_scale_f32 v128, s[2:3], v155, v155, 1.0
	v_fma_f32 v162, -v160, v164, v163
	v_rcp_f32_e32 v129, v128
	v_fmac_f32_e32 v164, v162, v161
	s_nop 0
	v_fma_f32 v160, -v160, v164, v163
	v_fma_f32 v130, -v128, v129, 1.0
	v_div_fmas_f32 v160, v160, v161, v164
	v_fmac_f32_e32 v129, v130, v129
	v_div_fixup_f32 v154, v160, v154, 1.0
	v_div_scale_f32 v131, vcc, 1.0, v155, 1.0
	v_mul_f32_e32 v165, v131, v129
	v_div_scale_f32 v160, s[2:3], v156, v156, 1.0
	v_fma_f32 v130, -v128, v165, v131
	v_rcp_f32_e32 v161, v160
	v_fmac_f32_e32 v165, v130, v129
	s_nop 0
	v_fma_f32 v128, -v128, v165, v131
	v_fma_f32 v162, -v160, v161, 1.0
	v_div_fmas_f32 v128, v128, v129, v165
	v_fmac_f32_e32 v161, v162, v161
	v_div_fixup_f32 v155, v128, v155, 1.0
	v_div_scale_f32 v163, vcc, 1.0, v156, 1.0
	v_mul_f32_e32 v164, v163, v161
	v_div_scale_f32 v128, s[2:3], v157, v157, 1.0
	v_fma_f32 v162, -v160, v164, v163
	v_rcp_f32_e32 v129, v128
	v_fmac_f32_e32 v164, v162, v161
	s_nop 0
	v_fma_f32 v160, -v160, v164, v163
	v_fma_f32 v130, -v128, v129, 1.0
	v_div_fmas_f32 v160, v160, v161, v164
	v_fmac_f32_e32 v129, v130, v129
	v_div_fixup_f32 v156, v160, v156, 1.0
	v_div_scale_f32 v131, vcc, 1.0, v157, 1.0
	v_mul_f32_e32 v165, v131, v129
	v_div_scale_f32 v160, s[2:3], v158, v158, 1.0
	v_fma_f32 v130, -v128, v165, v131
	v_rcp_f32_e32 v161, v160
	v_fmac_f32_e32 v165, v130, v129
	s_nop 0
	v_fma_f32 v128, -v128, v165, v131
	v_fma_f32 v162, -v160, v161, 1.0
	v_div_fmas_f32 v128, v128, v129, v165
	v_fmac_f32_e32 v161, v162, v161
	v_div_fixup_f32 v157, v128, v157, 1.0
	v_div_scale_f32 v163, vcc, 1.0, v158, 1.0
	v_mul_f32_e32 v164, v163, v161
	v_div_scale_f32 v128, s[2:3], v159, v159, 1.0
	v_fma_f32 v162, -v160, v164, v163
	v_rcp_f32_e32 v129, v128
	v_fmac_f32_e32 v164, v162, v161
	s_nop 0
	v_fma_f32 v160, -v160, v164, v163
	v_fma_f32 v130, -v128, v129, 1.0
	v_div_fmas_f32 v160, v160, v161, v164
	v_fmac_f32_e32 v129, v130, v129
	v_div_fixup_f32 v158, v160, v158, 1.0
	v_div_scale_f32 v131, vcc, 1.0, v159, 1.0
	v_mul_f32_e32 v165, v131, v129
	v_fma_f32 v130, -v128, v165, v131
	v_fmac_f32_e32 v165, v130, v129
	v_fma_f32 v128, -v128, v165, v131
	v_div_fmas_f32 v128, v128, v129, v165
	v_div_fixup_f32 v159, v128, v159, 1.0
	v_lshlrev_b32_e32 v166, 16, v32
	v_and_b32_e32 v167, 0xffff0000, v32
	v_pk_fma_f32 v[152:153], v[4:5], v[152:153], v[166:167]
	v_lshlrev_b32_e32 v166, 16, v33
	v_and_b32_e32 v167, 0xffff0000, v33
	v_pk_fma_f32 v[154:155], v[6:7], v[154:155], v[166:167]
	v_lshlrev_b32_e32 v166, 16, v34
	v_and_b32_e32 v167, 0xffff0000, v34
	v_pk_fma_f32 v[156:157], v[0:1], v[156:157], v[166:167]
	v_lshlrev_b32_e32 v166, 16, v35
	v_and_b32_e32 v167, 0xffff0000, v35
	v_pk_fma_f32 v[158:159], v[2:3], v[158:159], v[166:167]
	v_cvt_pk_bf16_f32 v168, v152, v153
	v_cvt_pk_bf16_f32 v169, v154, v155
	v_cvt_pk_bf16_f32 v170, v156, v157
	v_cvt_pk_bf16_f32 v171, v158, v159
	global_store_dwordx4 v191, v[168:171], s[66:67] offset:256
	s_mov_b32 s32, 1
	s_branch .LBB0_567
.Lepi5:
	v_lshlrev_b32_e32 v176, 12, v150
	v_lshl_add_u32 v176, v148, 2, v176
	v_add_u32_e32 v177, 0x10000, v176
	v_add_u32_e32 v178, 0x20000, v176
	v_add_u32_e32 v179, 0x30000, v176
	v_add_u32_e32 v180, 0x80000, v176
	v_add_u32_e32 v181, 0x90000, v176
	v_add_u32_e32 v182, 0xa0000, v176
	v_add_u32_e32 v183, 0xb0000, v176
	global_load_dwordx4 v[184:187], v176, s[24:25] nt
	global_load_dwordx4 v[188:191], v176, s[24:25] offset:16 nt
	global_load_dwordx4 v[192:195], v176, s[24:25] offset:512 nt
	global_load_dwordx4 v[196:199], v176, s[24:25] offset:528 nt
	global_load_dwordx4 v[200:203], v177, s[24:25] nt
	global_load_dwordx4 v[204:207], v177, s[24:25] offset:16 nt
	global_load_dwordx4 v[208:211], v177, s[24:25] offset:512 nt
	global_load_dwordx4 v[212:215], v177, s[24:25] offset:528 nt
	global_load_dwordx4 v[216:219], v178, s[24:25] nt
	global_load_dwordx4 v[220:223], v178, s[24:25] offset:16 nt
	global_load_dwordx4 v[152:155], v178, s[24:25] offset:512 nt
	global_load_dwordx4 v[156:159], v178, s[24:25] offset:528 nt
	global_load_dwordx4 v[160:163], v179, s[24:25] nt
	global_load_dwordx4 v[164:167], v179, s[24:25] offset:16 nt
	global_load_dwordx4 v[168:171], v179, s[24:25] offset:512 nt
	global_load_dwordx4 v[128:131], v179, s[24:25] offset:528 nt
	s_waitcnt vmcnt(14)
	v_pk_add_f32 v[186:187], v[126:127], v[186:187]
	v_pk_add_f32 v[184:185], v[124:125], v[184:185]
	v_pk_add_f32 v[190:191], v[122:123], v[190:191]
	v_pk_add_f32 v[188:189], v[120:121], v[188:189]
	global_store_dwordx4 v176, v[184:187], s[58:59]
	global_store_dwordx4 v176, v[188:191], s[58:59] offset:16
	global_load_dwordx4 v[124:127], v180, s[24:25] nt
	global_load_dwordx4 v[120:123], v180, s[24:25] offset:16 nt
	s_waitcnt vmcnt(16)
	v_pk_add_f32 v[194:195], v[118:119], v[194:195]
	v_pk_add_f32 v[192:193], v[116:117], v[192:193]
	v_pk_add_f32 v[198:199], v[114:115], v[198:199]
	v_pk_add_f32 v[196:197], v[112:113], v[196:197]
	global_store_dwordx4 v176, v[192:195], s[58:59] offset:512
	global_store_dwordx4 v176, v[196:199], s[58:59] offset:528
	global_load_dwordx4 v[116:119], v180, s[24:25] offset:512 nt
	global_load_dwordx4 v[112:115], v180, s[24:25] offset:528 nt
	s_waitcnt vmcnt(18)
	v_pk_add_f32 v[202:203], v[110:111], v[202:203]
	v_pk_add_f32 v[200:201], v[108:109], v[200:201]
	v_pk_add_f32 v[206:207], v[106:107], v[206:207]
	v_pk_add_f32 v[204:205], v[104:105], v[204:205]
	global_store_dwordx4 v177, v[200:203], s[58:59]
	global_store_dwordx4 v177, v[204:207], s[58:59] offset:16
	global_load_dwordx4 v[108:111], v181, s[24:25] nt
	global_load_dwordx4 v[104:107], v181, s[24:25] offset:16 nt
	s_waitcnt vmcnt(20)
	v_pk_add_f32 v[210:211], v[102:103], v[210:211]
	v_pk_add_f32 v[208:209], v[100:101], v[208:209]
	v_pk_add_f32 v[214:215], v[98:99], v[214:215]
	v_pk_add_f32 v[212:213], v[96:97], v[212:213]
	global_store_dwordx4 v177, v[208:211], s[58:59] offset:512
	global_store_dwordx4 v177, v[212:215], s[58:59] offset:528
	global_load_dwordx4 v[100:103], v181, s[24:25] offset:512 nt
	global_load_dwordx4 v[96:99], v181, s[24:25] offset:528 nt
	s_waitcnt vmcnt(22)
	v_pk_add_f32 v[218:219], v[94:95], v[218:219]
	v_pk_add_f32 v[216:217], v[92:93], v[216:217]
	v_pk_add_f32 v[222:223], v[90:91], v[222:223]
	v_pk_add_f32 v[220:221], v[88:89], v[220:221]
	global_store_dwordx4 v178, v[216:219], s[58:59]
	global_store_dwordx4 v178, v[220:223], s[58:59] offset:16
	global_load_dwordx4 v[92:95], v182, s[24:25] nt
	global_load_dwordx4 v[88:91], v182, s[24:25] offset:16 nt
	s_waitcnt vmcnt(24)
	v_pk_add_f32 v[154:155], v[86:87], v[154:155]
	v_pk_add_f32 v[152:153], v[84:85], v[152:153]
	v_pk_add_f32 v[158:159], v[82:83], v[158:159]
	v_pk_add_f32 v[156:157], v[80:81], v[156:157]
	global_store_dwordx4 v178, v[152:155], s[58:59] offset:512
	global_store_dwordx4 v178, v[156:159], s[58:59] offset:528
	global_load_dwordx4 v[84:87], v182, s[24:25] offset:512 nt
	global_load_dwordx4 v[80:83], v182, s[24:25] offset:528 nt
	s_waitcnt vmcnt(26)
	v_pk_add_f32 v[162:163], v[78:79], v[162:163]
	v_pk_add_f32 v[160:161], v[76:77], v[160:161]
	v_pk_add_f32 v[166:167], v[74:75], v[166:167]
	v_pk_add_f32 v[164:165], v[72:73], v[164:165]
	global_store_dwordx4 v179, v[160:163], s[58:59]
	global_store_dwordx4 v179, v[164:167], s[58:59] offset:16
	global_load_dwordx4 v[76:79], v183, s[24:25] nt
	global_load_dwordx4 v[72:75], v183, s[24:25] offset:16 nt
	s_waitcnt vmcnt(28)
	v_pk_add_f32 v[170:171], v[70:71], v[170:171]
	v_pk_add_f32 v[168:169], v[68:69], v[168:169]
	v_pk_add_f32 v[130:131], v[66:67], v[130:131]
	v_pk_add_f32 v[128:129], v[64:65], v[128:129]
	global_store_dwordx4 v179, v[168:171], s[58:59] offset:512
	global_store_dwordx4 v179, v[128:131], s[58:59] offset:528
	global_load_dwordx4 v[68:71], v183, s[24:25] offset:512 nt
	global_load_dwordx4 v[64:67], v183, s[24:25] offset:528 nt
	s_waitcnt vmcnt(28)
	v_pk_add_f32 v[126:127], v[62:63], v[126:127]
	v_pk_add_f32 v[124:125], v[60:61], v[124:125]
	v_pk_add_f32 v[122:123], v[58:59], v[122:123]
	v_pk_add_f32 v[120:121], v[56:57], v[120:121]
	global_store_dwordx4 v180, v[124:127], s[58:59]
	global_store_dwordx4 v180, v[120:123], s[58:59] offset:16
	s_waitcnt vmcnt(26)
	v_pk_add_f32 v[118:119], v[54:55], v[118:119]
	v_pk_add_f32 v[116:117], v[52:53], v[116:117]
	v_pk_add_f32 v[114:115], v[50:51], v[114:115]
	v_pk_add_f32 v[112:113], v[48:49], v[112:113]
	global_store_dwordx4 v180, v[116:119], s[58:59] offset:512
	global_store_dwordx4 v180, v[112:115], s[58:59] offset:528
	s_waitcnt vmcnt(24)
	v_pk_add_f32 v[110:111], v[46:47], v[110:111]
	v_pk_add_f32 v[108:109], v[44:45], v[108:109]
	v_pk_add_f32 v[106:107], v[42:43], v[106:107]
	v_pk_add_f32 v[104:105], v[40:41], v[104:105]
	global_store_dwordx4 v181, v[108:111], s[58:59]
	global_store_dwordx4 v181, v[104:107], s[58:59] offset:16
	s_waitcnt vmcnt(22)
	v_pk_add_f32 v[102:103], v[38:39], v[102:103]
	v_pk_add_f32 v[100:101], v[36:37], v[100:101]
	v_pk_add_f32 v[98:99], v[34:35], v[98:99]
	v_pk_add_f32 v[96:97], v[32:33], v[96:97]
	global_store_dwordx4 v181, v[100:103], s[58:59] offset:512
	global_store_dwordx4 v181, v[96:99], s[58:59] offset:528
	s_waitcnt vmcnt(20)
	v_pk_add_f32 v[94:95], v[30:31], v[94:95]
	v_pk_add_f32 v[92:93], v[28:29], v[92:93]
	v_pk_add_f32 v[90:91], v[26:27], v[90:91]
	v_pk_add_f32 v[88:89], v[24:25], v[88:89]
	global_store_dwordx4 v182, v[92:95], s[58:59]
	global_store_dwordx4 v182, v[88:91], s[58:59] offset:16
	s_waitcnt vmcnt(18)
	v_pk_add_f32 v[86:87], v[22:23], v[86:87]
	v_pk_add_f32 v[84:85], v[20:21], v[84:85]
	v_pk_add_f32 v[82:83], v[18:19], v[82:83]
	v_pk_add_f32 v[80:81], v[16:17], v[80:81]
	global_store_dwordx4 v182, v[84:87], s[58:59] offset:512
	global_store_dwordx4 v182, v[80:83], s[58:59] offset:528
	s_waitcnt vmcnt(16)
	v_pk_add_f32 v[78:79], v[14:15], v[78:79]
	v_pk_add_f32 v[76:77], v[12:13], v[76:77]
	v_pk_add_f32 v[74:75], v[10:11], v[74:75]
	v_pk_add_f32 v[72:73], v[8:9], v[72:73]
	global_store_dwordx4 v183, v[76:79], s[58:59]
	global_store_dwordx4 v183, v[72:75], s[58:59] offset:16
	s_waitcnt vmcnt(14)
	v_pk_add_f32 v[70:71], v[6:7], v[70:71]
	v_pk_add_f32 v[68:69], v[4:5], v[68:69]
	v_pk_add_f32 v[66:67], v[2:3], v[66:67]
	v_pk_add_f32 v[64:65], v[0:1], v[64:65]
	global_store_dwordx4 v183, v[68:71], s[58:59] offset:512
	global_store_dwordx4 v183, v[64:67], s[58:59] offset:528
	s_mov_b32 s32, 1
	s_branch .LBB0_567
.Lepi7:
	v_lshlrev_b32_e32 v176, 12, v150
	v_lshl_add_u32 v176, v148, 2, v176
	v_add_u32_e32 v177, 0x10000, v176
	v_add_u32_e32 v178, 0x20000, v176
	v_add_u32_e32 v179, 0x30000, v176
	v_add_u32_e32 v180, 0x80000, v176
	v_add_u32_e32 v181, 0x90000, v176
	v_add_u32_e32 v182, 0xa0000, v176
	v_add_u32_e32 v183, 0xb0000, v176
	global_load_dwordx4 v[184:187], v176, s[58:59] nt
	global_load_dwordx4 v[188:191], v176, s[58:59] offset:16 nt
	global_load_dwordx4 v[192:195], v176, s[58:59] offset:512 nt
	global_load_dwordx4 v[196:199], v176, s[58:59] offset:528 nt
	global_load_dwordx4 v[200:203], v177, s[58:59] nt
	global_load_dwordx4 v[204:207], v177, s[58:59] offset:16 nt
	global_load_dwordx4 v[208:211], v177, s[58:59] offset:512 nt
	global_load_dwordx4 v[212:215], v177, s[58:59] offset:528 nt
	global_load_dwordx4 v[216:219], v178, s[58:59] nt
	global_load_dwordx4 v[220:223], v178, s[58:59] offset:16 nt
	global_load_dwordx4 v[152:155], v178, s[58:59] offset:512 nt
	global_load_dwordx4 v[156:159], v178, s[58:59] offset:528 nt
	global_load_dwordx4 v[160:163], v179, s[58:59] nt
	global_load_dwordx4 v[164:167], v179, s[58:59] offset:16 nt
	global_load_dwordx4 v[168:171], v179, s[58:59] offset:512 nt
	global_load_dwordx4 v[128:131], v179, s[58:59] offset:528 nt
	s_waitcnt vmcnt(14)
	v_pk_add_f32 v[186:187], v[126:127], v[186:187]
	v_pk_add_f32 v[184:185], v[124:125], v[184:185]
	v_pk_add_f32 v[190:191], v[122:123], v[190:191]
	v_pk_add_f32 v[188:189], v[120:121], v[188:189]
	global_store_dwordx4 v176, v[184:187], s[58:59] nt
	global_store_dwordx4 v176, v[188:191], s[58:59] offset:16 nt
	global_load_dwordx4 v[124:127], v180, s[58:59] nt
	global_load_dwordx4 v[120:123], v180, s[58:59] offset:16 nt
	s_waitcnt vmcnt(16)
	v_pk_add_f32 v[194:195], v[118:119], v[194:195]
	v_pk_add_f32 v[192:193], v[116:117], v[192:193]
	v_pk_add_f32 v[198:199], v[114:115], v[198:199]
	v_pk_add_f32 v[196:197], v[112:113], v[196:197]
	global_store_dwordx4 v176, v[192:195], s[58:59] offset:512 nt
	global_store_dwordx4 v176, v[196:199], s[58:59] offset:528 nt
	global_load_dwordx4 v[116:119], v180, s[58:59] offset:512 nt
	global_load_dwordx4 v[112:115], v180, s[58:59] offset:528 nt
	s_waitcnt vmcnt(18)
	v_pk_add_f32 v[202:203], v[110:111], v[202:203]
	v_pk_add_f32 v[200:201], v[108:109], v[200:201]
	v_pk_add_f32 v[206:207], v[106:107], v[206:207]
	v_pk_add_f32 v[204:205], v[104:105], v[204:205]
	global_store_dwordx4 v177, v[200:203], s[58:59] nt
	global_store_dwordx4 v177, v[204:207], s[58:59] offset:16 nt
	global_load_dwordx4 v[108:111], v181, s[58:59] nt
	global_load_dwordx4 v[104:107], v181, s[58:59] offset:16 nt
	s_waitcnt vmcnt(20)
	v_pk_add_f32 v[210:211], v[102:103], v[210:211]
	v_pk_add_f32 v[208:209], v[100:101], v[208:209]
	v_pk_add_f32 v[214:215], v[98:99], v[214:215]
	v_pk_add_f32 v[212:213], v[96:97], v[212:213]
	global_store_dwordx4 v177, v[208:211], s[58:59] offset:512 nt
	global_store_dwordx4 v177, v[212:215], s[58:59] offset:528 nt
	global_load_dwordx4 v[100:103], v181, s[58:59] offset:512 nt
	global_load_dwordx4 v[96:99], v181, s[58:59] offset:528 nt
	s_waitcnt vmcnt(22)
	v_pk_add_f32 v[218:219], v[94:95], v[218:219]
	v_pk_add_f32 v[216:217], v[92:93], v[216:217]
	v_pk_add_f32 v[222:223], v[90:91], v[222:223]
	v_pk_add_f32 v[220:221], v[88:89], v[220:221]
	global_store_dwordx4 v178, v[216:219], s[58:59] nt
	global_store_dwordx4 v178, v[220:223], s[58:59] offset:16 nt
	global_load_dwordx4 v[92:95], v182, s[58:59] nt
	global_load_dwordx4 v[88:91], v182, s[58:59] offset:16 nt
	s_waitcnt vmcnt(24)
	v_pk_add_f32 v[154:155], v[86:87], v[154:155]
	v_pk_add_f32 v[152:153], v[84:85], v[152:153]
	v_pk_add_f32 v[158:159], v[82:83], v[158:159]
	v_pk_add_f32 v[156:157], v[80:81], v[156:157]
	global_store_dwordx4 v178, v[152:155], s[58:59] offset:512 nt
	global_store_dwordx4 v178, v[156:159], s[58:59] offset:528 nt
	global_load_dwordx4 v[84:87], v182, s[58:59] offset:512 nt
	global_load_dwordx4 v[80:83], v182, s[58:59] offset:528 nt
	s_waitcnt vmcnt(26)
; #define PG8_STAGE(bufoff, gbase, voff) do { _Pragma("unroll") for (int _i = 0; _i < 2; ++_i) \
;     __builtin_amdgcn_global_load_lds((const unsigned*)((const char*)(gbase) + (voff)[_i]), (LAS unsigned*)(lds + (bufoff) + ldsw + _i * 8192), 16, 0, 0); } while (0)
; #define PG8_LDA(dst, b, h) do { _Pragma("unroll") for (int m = 0; m < 4; ++m) _Pragma("unroll") for (int k = 0; k < 2; ++k) dst[m][k] = *(const LAS bf16x8*)(lds + PG8_SA(b, h) + aoff + m * 2048 + k * 1024); } while (0)
; #define PG8_LDB(dst, b, h) do { _Pragma("unroll") for (int n = 0; n < 2; ++n) _Pragma("unroll") for (int k = 0; k < 2; ++k) dst[n][k] = *(const LAS bf16x8*)(lds + PG8_SB(b, h) + boff + n * 2048 + k * 1024); } while (0)
; #define PG8_MMA(ai, bj, At, Bt) do { __builtin_amdgcn_s_setprio(1); _Pragma("unroll") for (int m = 0; m < 4; ++m) _Pragma("unroll") for (int n = 0; n < 2; ++n) _Pragma("unroll") for (int k = 0; k < 2; ++k) \
;     acc[ai][bj][m][n] = __builtin_amdgcn_mfma_f32_16x16x32_bf16(Bt[n][k], At[m][k], acc[ai][bj][m][n], 0, 0, 0); __builtin_amdgcn_s_setprio(0); } while (0)
; #define PG8_WAIT_V(n) asm volatile("s_waitcnt vmcnt(" #n ")" ::: "memory")
; #define PG8_WAIT_L(n) asm volatile("s_waitcnt lgkmcnt(" #n ")" ::: "memory")
; #define PG8_BAR __builtin_amdgcn_s_barrier()
; #define PG8_SCHED __builtin_amdgcn_sched_barrier(0)
; template <class Epi>
; __device__ __forceinline__ void gemm_phase(LAS unsigned char* lds, const Gemm g, const Epi& E) {
;     ...
;       PG8_LDB(B0, 0, 0); PG8_SCHED; PG8_LDA(At, 0, 0); PG8_STAGE(PG8_SA(1, 1), a1 + hstepA, voffA);
;       PG8_WAIT_L(8); PG8_BAR; PG8_WAIT_L(0); PG8_MMA(0, 0, At, B0); PG8_BAR; PG8_SCHED;
;       PG8_LDB(B1, 0, 1); PG8_STAGE(PG8_SB(0, 0), b2, voffB);
;       PG8_BAR; PG8_WAIT_L(0); PG8_MMA(0, 1, At, B1); PG8_BAR;
;       PG8_LDA(At, 0, 1); PG8_STAGE(PG8_SA(0, 0), a2, voffA);
;       PG8_BAR; PG8_WAIT_L(0); PG8_MMA(1, 0, At, B0); PG8_BAR; PG8_SCHED;
;       PG8_STAGE(PG8_SB(0, 1), b2 + hstepB, voffB);
;       PG8_WAIT_V(6); PG8_BAR; PG8_MMA(1, 1, At, B1); PG8_BAR;
	v_pk_add_f32 v[162:163], v[78:79], v[162:163]
	v_pk_add_f32 v[160:161], v[76:77], v[160:161]
	v_pk_add_f32 v[166:167], v[74:75], v[166:167]
	v_pk_add_f32 v[164:165], v[72:73], v[164:165]
	global_store_dwordx4 v179, v[160:163], s[58:59] nt
	global_store_dwordx4 v179, v[164:167], s[58:59] offset:16 nt
	global_load_dwordx4 v[76:79], v183, s[58:59] nt
	global_load_dwordx4 v[72:75], v183, s[58:59] offset:16 nt
	s_waitcnt vmcnt(28)
	v_pk_add_f32 v[170:171], v[70:71], v[170:171]
	v_pk_add_f32 v[168:169], v[68:69], v[168:169]
	v_pk_add_f32 v[130:131], v[66:67], v[130:131]
	v_pk_add_f32 v[128:129], v[64:65], v[128:129]
	global_store_dwordx4 v179, v[168:171], s[58:59] offset:512 nt
	global_store_dwordx4 v179, v[128:131], s[58:59] offset:528 nt
	global_load_dwordx4 v[68:71], v183, s[58:59] offset:512 nt
	global_load_dwordx4 v[64:67], v183, s[58:59] offset:528 nt
	s_waitcnt vmcnt(28)
	v_pk_add_f32 v[126:127], v[62:63], v[126:127]
	v_pk_add_f32 v[124:125], v[60:61], v[124:125]
	v_pk_add_f32 v[122:123], v[58:59], v[122:123]
	v_pk_add_f32 v[120:121], v[56:57], v[120:121]
	global_store_dwordx4 v180, v[124:127], s[58:59] nt
	global_store_dwordx4 v180, v[120:123], s[58:59] offset:16 nt
	s_waitcnt vmcnt(26)
	v_pk_add_f32 v[118:119], v[54:55], v[118:119]
	v_pk_add_f32 v[116:117], v[52:53], v[116:117]
	v_pk_add_f32 v[114:115], v[50:51], v[114:115]
	v_pk_add_f32 v[112:113], v[48:49], v[112:113]
	global_store_dwordx4 v180, v[116:119], s[58:59] offset:512 nt
	global_store_dwordx4 v180, v[112:115], s[58:59] offset:528 nt
	s_waitcnt vmcnt(24)
	v_pk_add_f32 v[110:111], v[46:47], v[110:111]
	v_pk_add_f32 v[108:109], v[44:45], v[108:109]
	v_pk_add_f32 v[106:107], v[42:43], v[106:107]
	v_pk_add_f32 v[104:105], v[40:41], v[104:105]
	global_store_dwordx4 v181, v[108:111], s[58:59] nt
	global_store_dwordx4 v181, v[104:107], s[58:59] offset:16 nt
	s_waitcnt vmcnt(22)
	v_pk_add_f32 v[102:103], v[38:39], v[102:103]
	v_pk_add_f32 v[100:101], v[36:37], v[100:101]
	v_pk_add_f32 v[98:99], v[34:35], v[98:99]
	v_pk_add_f32 v[96:97], v[32:33], v[96:97]
	global_store_dwordx4 v181, v[100:103], s[58:59] offset:512 nt
	global_store_dwordx4 v181, v[96:99], s[58:59] offset:528 nt
	s_waitcnt vmcnt(20)
	v_pk_add_f32 v[94:95], v[30:31], v[94:95]
	v_pk_add_f32 v[92:93], v[28:29], v[92:93]
	v_pk_add_f32 v[90:91], v[26:27], v[90:91]
	v_pk_add_f32 v[88:89], v[24:25], v[88:89]
	global_store_dwordx4 v182, v[92:95], s[58:59] nt
	global_store_dwordx4 v182, v[88:91], s[58:59] offset:16 nt
	s_waitcnt vmcnt(18)
	v_pk_add_f32 v[86:87], v[22:23], v[86:87]
	v_pk_add_f32 v[84:85], v[20:21], v[84:85]
	v_pk_add_f32 v[82:83], v[18:19], v[82:83]
	v_pk_add_f32 v[80:81], v[16:17], v[80:81]
	global_store_dwordx4 v182, v[84:87], s[58:59] offset:512 nt
	global_store_dwordx4 v182, v[80:83], s[58:59] offset:528 nt
	s_waitcnt vmcnt(16)
	v_pk_add_f32 v[78:79], v[14:15], v[78:79]
	v_pk_add_f32 v[76:77], v[12:13], v[76:77]
	v_pk_add_f32 v[74:75], v[10:11], v[74:75]
	v_pk_add_f32 v[72:73], v[8:9], v[72:73]
	global_store_dwordx4 v183, v[76:79], s[58:59] nt
	global_store_dwordx4 v183, v[72:75], s[58:59] offset:16 nt
	s_waitcnt vmcnt(14)
	v_pk_add_f32 v[70:71], v[6:7], v[70:71]
	v_pk_add_f32 v[68:69], v[4:5], v[68:69]
	v_pk_add_f32 v[66:67], v[2:3], v[66:67]
	v_pk_add_f32 v[64:65], v[0:1], v[64:65]
	global_store_dwordx4 v183, v[68:71], s[58:59] offset:512 nt
	global_store_dwordx4 v183, v[64:67], s[58:59] offset:528 nt
	s_mov_b32 s32, 1
	s_branch .LBB0_567
.Lpeel:
	s_add_i32 s76, s26, 2
	s_add_u32 s28, s2, 0x80
	s_addc_u32 s27, s3, 0
	s_add_i32 s83, 0, 0x10000
	v_add_u32_e32 v156, s83, v173
	ds_read_b128 v[128:131], v156
	ds_read_b128 v[148:151], v156 offset:1024
	ds_read_b128 v[152:155], v156 offset:2048
	ds_read_b128 v[156:159], v156 offset:3072
	s_cmp_eq_u32 s89, s26
	s_cselect_b32 s26, s0, s28
	s_cselect_b32 s27, s1, s27
	s_cselect_b32 s29, s21, s39
	s_cselect_b32 s28, s20, s38
	v_lshl_add_u64 v[196:197], s[2:3], 0, v[144:145]
	s_add_i32 m0, s84, 0xc000
	ds_read_b128 v[160:163], v175
	ds_read_b128 v[164:167], v175 offset:1024
	ds_read_b128 v[168:171], v175 offset:2048
	ds_read_b128 v[176:179], v175 offset:3072
	ds_read_b128 v[180:183], v175 offset:4096
	ds_read_b128 v[184:187], v175 offset:5120
	ds_read_b128 v[188:191], v175 offset:6144
	ds_read_b128 v[192:195], v175 offset:7168
	global_load_lds_dwordx4 v[196:197], off
	v_lshl_add_u64 v[196:197], s[2:3], 0, v[146:147]
	s_add_i32 m0, s84, 0xe000
	s_nop 0
	global_load_lds_dwordx4 v[196:197], off
	s_waitcnt lgkmcnt(8)
	s_barrier
	s_waitcnt lgkmcnt(0)
	s_setprio 1
	s_waitcnt lgkmcnt(0)
	v_mfma_f32_16x16x32_bf16 v[124:127], v[128:131], v[160:163], 0
	v_mfma_f32_16x16x32_bf16 v[120:123], v[152:155], v[160:163], 0
	v_mfma_f32_16x16x32_bf16 v[108:111], v[128:131], v[168:171], 0
	v_mfma_f32_16x16x32_bf16 v[104:107], v[152:155], v[168:171], 0
	v_mfma_f32_16x16x32_bf16 v[92:95], v[128:131], v[180:183], 0
	v_mfma_f32_16x16x32_bf16 v[88:91], v[152:155], v[180:183], 0
	v_mfma_f32_16x16x32_bf16 v[76:79], v[128:131], v[188:191], 0
	v_mfma_f32_16x16x32_bf16 v[72:75], v[152:155], v[188:191], 0
	v_mfma_f32_16x16x32_bf16 v[124:127], v[148:151], v[164:167], v[124:127]
	v_mfma_f32_16x16x32_bf16 v[120:123], v[156:159], v[164:167], v[120:123]
	v_mfma_f32_16x16x32_bf16 v[108:111], v[148:151], v[176:179], v[108:111]
	v_mfma_f32_16x16x32_bf16 v[104:107], v[156:159], v[176:179], v[104:107]
	v_mfma_f32_16x16x32_bf16 v[92:95], v[148:151], v[184:187], v[92:95]
	v_mfma_f32_16x16x32_bf16 v[88:91], v[156:159], v[184:187], v[88:91]
	v_mfma_f32_16x16x32_bf16 v[76:79], v[148:151], v[192:195], v[76:79]
	v_mfma_f32_16x16x32_bf16 v[72:75], v[156:159], v[192:195], v[72:75]
	s_setprio 0
	s_barrier
; #define PG8_STAGE(bufoff, gbase, voff) do { _Pragma("unroll") for (int _i = 0; _i < 2; ++_i) \
;     __builtin_amdgcn_global_load_lds((const unsigned*)((const char*)(gbase) + (voff)[_i]), (LAS unsigned*)(lds + (bufoff) + ldsw + _i * 8192), 16, 0, 0); } while (0)
; #define PG8_LDA(dst, b, h) do { _Pragma("unroll") for (int m = 0; m < 4; ++m) _Pragma("unroll") for (int k = 0; k < 2; ++k) dst[m][k] = *(const LAS bf16x8*)(lds + PG8_SA(b, h) + aoff + m * 2048 + k * 1024); } while (0)
; #define PG8_LDB(dst, b, h) do { _Pragma("unroll") for (int n = 0; n < 2; ++n) _Pragma("unroll") for (int k = 0; k < 2; ++k) dst[n][k] = *(const LAS bf16x8*)(lds + PG8_SB(b, h) + boff + n * 2048 + k * 1024); } while (0)
; #define PG8_MMA(ai, bj, At, Bt) do { __builtin_amdgcn_s_setprio(1); _Pragma("unroll") for (int m = 0; m < 4; ++m) _Pragma("unroll") for (int n = 0; n < 2; ++n) _Pragma("unroll") for (int k = 0; k < 2; ++k) \
;     acc[ai][bj][m][n] = __builtin_amdgcn_mfma_f32_16x16x32_bf16(Bt[n][k], At[m][k], acc[ai][bj][m][n], 0, 0, 0); __builtin_amdgcn_s_setprio(0); } while (0)
; #define PG8_WAIT_V(n) asm volatile("s_waitcnt vmcnt(" #n ")" ::: "memory")
; #define PG8_WAIT_L(n) asm volatile("s_waitcnt lgkmcnt(" #n ")" ::: "memory")
; #define PG8_BAR __builtin_amdgcn_s_barrier()
; #define PG8_SCHED __builtin_amdgcn_sched_barrier(0)
; template <class Epi>
; __device__ __forceinline__ void gemm_phase(LAS unsigned char* lds, const Gemm g, const Epi& E) {
;     ...
;       PG8_LDB(B1, 0, 1); PG8_STAGE(PG8_SB(0, 0), b2, voffB);
;       PG8_BAR; PG8_WAIT_L(0); PG8_MMA(0, 1, At, B1); PG8_BAR;
;       PG8_LDA(At, 0, 1); PG8_STAGE(PG8_SA(0, 0), a2, voffA);
;       PG8_BAR; PG8_WAIT_L(0); PG8_MMA(1, 0, At, B0); PG8_BAR; PG8_SCHED;
;       PG8_STAGE(PG8_SB(0, 1), b2 + hstepB, voffB);
;       PG8_WAIT_V(6); PG8_BAR; PG8_MMA(1, 1, At, B1); PG8_BAR;
;       PG8_LDB(B0, 1, 0); PG8_SCHED; PG8_LDA(At, 1, 0); PG8_STAGE(PG8_SA(0, 1), a2 + hstepA, voffA);
;       PG8_WAIT_L(8); PG8_BAR; PG8_WAIT_L(0); PG8_MMA(0, 0, At, B0); PG8_BAR; PG8_SCHED;
	s_add_i32 s94, 0, 0x14000
	s_add_i32 s83, s83, s97
	v_add_u32_e32 v208, s94, v173
	v_lshl_add_u64 v[212:213], s[28:29], 0, v[132:133]
	s_mov_b32 m0, s83
	ds_read_b128 v[196:199], v208
	ds_read_b128 v[200:203], v208 offset:1024
	ds_read_b128 v[204:207], v208 offset:2048
	ds_read_b128 v[208:211], v208 offset:3072
	global_load_lds_dwordx4 v[212:213], off
	v_lshl_add_u64 v[214:215], s[28:29], 0, v[142:143]
	s_add_i32 m0, s83, 0x2000
	s_nop 0
	global_load_lds_dwordx4 v[214:215], off
	s_barrier
	s_waitcnt lgkmcnt(0)
	s_setprio 1
	s_waitcnt lgkmcnt(0)
	v_mfma_f32_16x16x32_bf16 v[116:119], v[196:199], v[160:163], 0
	v_mfma_f32_16x16x32_bf16 v[112:115], v[204:207], v[160:163], 0
	v_mfma_f32_16x16x32_bf16 v[100:103], v[196:199], v[168:171], 0
	v_mfma_f32_16x16x32_bf16 v[96:99], v[204:207], v[168:171], 0
	v_mfma_f32_16x16x32_bf16 v[84:87], v[196:199], v[180:183], 0
	v_mfma_f32_16x16x32_bf16 v[80:83], v[204:207], v[180:183], 0
	v_mfma_f32_16x16x32_bf16 v[68:71], v[196:199], v[188:191], 0
	v_mfma_f32_16x16x32_bf16 v[64:67], v[204:207], v[188:191], 0
	v_mfma_f32_16x16x32_bf16 v[116:119], v[200:203], v[164:167], v[116:119]
	v_mfma_f32_16x16x32_bf16 v[112:115], v[208:211], v[164:167], v[112:115]
	v_mfma_f32_16x16x32_bf16 v[100:103], v[200:203], v[176:179], v[100:103]
	v_mfma_f32_16x16x32_bf16 v[96:99], v[208:211], v[176:179], v[96:99]
	v_mfma_f32_16x16x32_bf16 v[84:87], v[200:203], v[184:187], v[84:87]
	v_mfma_f32_16x16x32_bf16 v[80:83], v[208:211], v[184:187], v[80:83]
	v_mfma_f32_16x16x32_bf16 v[68:71], v[200:203], v[192:195], v[68:71]
	v_mfma_f32_16x16x32_bf16 v[64:67], v[208:211], v[192:195], v[64:67]
	s_setprio 0
	s_mov_b32 m0, s84
	v_lshl_add_u64 v[216:217], s[26:27], 0, v[138:139]
	s_barrier
	ds_read_b128 v[160:163], v175 offset:16384
	ds_read_b128 v[164:167], v175 offset:17408
	ds_read_b128 v[168:171], v175 offset:18432
	ds_read_b128 v[176:179], v175 offset:19456
	ds_read_b128 v[180:183], v175 offset:20480
	ds_read_b128 v[184:187], v175 offset:21504
	ds_read_b128 v[188:191], v175 offset:22528
	ds_read_b128 v[192:195], v175 offset:23552
	global_load_lds_dwordx4 v[216:217], off
	v_lshl_add_u64 v[218:219], s[26:27], 0, v[140:141]
	s_mov_b32 m0, s85
	s_nop 0
	global_load_lds_dwordx4 v[218:219], off
	s_barrier
	s_waitcnt lgkmcnt(0)
	s_setprio 1
	s_waitcnt lgkmcnt(0)
	v_mfma_f32_16x16x32_bf16 v[60:63], v[128:131], v[160:163], 0
	v_mfma_f32_16x16x32_bf16 v[56:59], v[152:155], v[160:163], 0
	v_mfma_f32_16x16x32_bf16 v[44:47], v[128:131], v[168:171], 0
	v_mfma_f32_16x16x32_bf16 v[40:43], v[152:155], v[168:171], 0
	v_mfma_f32_16x16x32_bf16 v[28:31], v[128:131], v[180:183], 0
	v_mfma_f32_16x16x32_bf16 v[24:27], v[152:155], v[180:183], 0
	v_mfma_f32_16x16x32_bf16 v[12:15], v[128:131], v[188:191], 0
	v_mfma_f32_16x16x32_bf16 v[8:11], v[152:155], v[188:191], 0
	v_mfma_f32_16x16x32_bf16 v[60:63], v[148:151], v[164:167], v[60:63]
	v_mfma_f32_16x16x32_bf16 v[56:59], v[156:159], v[164:167], v[56:59]
	v_mfma_f32_16x16x32_bf16 v[44:47], v[148:151], v[176:179], v[44:47]
	v_mfma_f32_16x16x32_bf16 v[40:43], v[156:159], v[176:179], v[40:43]
	v_mfma_f32_16x16x32_bf16 v[28:31], v[148:151], v[184:187], v[28:31]
	v_mfma_f32_16x16x32_bf16 v[24:27], v[156:159], v[184:187], v[24:27]
	v_mfma_f32_16x16x32_bf16 v[12:15], v[148:151], v[192:195], v[12:15]
	v_mfma_f32_16x16x32_bf16 v[8:11], v[156:159], v[192:195], v[8:11]
	s_setprio 0
	s_barrier
	s_add_u32 s28, s28, s95
	s_addc_u32 s29, s29, 0
	s_add_i32 s83, s94, s97
	v_lshl_add_u64 v[220:221], s[28:29], 0, v[132:133]
	s_mov_b32 m0, s83
	v_lshl_add_u64 v[222:223], s[28:29], 0, v[142:143]
	global_load_lds_dwordx4 v[220:221], off
	s_add_i32 m0, s83, 0x2000
	s_nop 0
	global_load_lds_dwordx4 v[222:223], off
	s_waitcnt vmcnt(24)
	s_barrier
	s_setprio 1
	v_mfma_f32_16x16x32_bf16 v[52:55], v[196:199], v[160:163], 0
	v_mfma_f32_16x16x32_bf16 v[48:51], v[204:207], v[160:163], 0
	v_mfma_f32_16x16x32_bf16 v[36:39], v[196:199], v[168:171], 0
	v_mfma_f32_16x16x32_bf16 v[32:35], v[204:207], v[168:171], 0
	v_mfma_f32_16x16x32_bf16 v[20:23], v[196:199], v[180:183], 0
	v_mfma_f32_16x16x32_bf16 v[16:19], v[204:207], v[180:183], 0
	v_mfma_f32_16x16x32_bf16 v[4:7], v[196:199], v[188:191], 0
	v_mfma_f32_16x16x32_bf16 v[0:3], v[204:207], v[188:191], 0
	v_mfma_f32_16x16x32_bf16 v[52:55], v[200:203], v[164:167], v[52:55]
	v_mfma_f32_16x16x32_bf16 v[48:51], v[208:211], v[164:167], v[48:51]
	v_mfma_f32_16x16x32_bf16 v[36:39], v[200:203], v[176:179], v[36:39]
	v_mfma_f32_16x16x32_bf16 v[32:35], v[208:211], v[176:179], v[32:35]
	v_mfma_f32_16x16x32_bf16 v[20:23], v[200:203], v[184:187], v[20:23]
	v_mfma_f32_16x16x32_bf16 v[16:19], v[208:211], v[184:187], v[16:19]
	v_mfma_f32_16x16x32_bf16 v[4:7], v[200:203], v[192:195], v[4:7]
	v_mfma_f32_16x16x32_bf16 v[0:3], v[208:211], v[192:195], v[0:3]
	s_setprio 0
	s_add_i32 s28, 0, 0x18000
	v_add_u32_e32 v156, s28, v173
	s_barrier
	ds_read_b128 v[128:131], v156
	ds_read_b128 v[148:151], v156 offset:1024
	ds_read_b128 v[152:155], v156 offset:2048
	ds_read_b128 v[156:159], v156 offset:3072
	s_add_u32 s26, s26, s56
	s_addc_u32 s27, s27, 0
	s_mov_b32 m0, s86
	v_lshl_add_u64 v[196:197], s[26:27], 0, v[138:139]
	ds_read_b128 v[160:163], v175 offset:32768
	ds_read_b128 v[164:167], v175 offset:33792
	ds_read_b128 v[168:171], v175 offset:34816
	ds_read_b128 v[176:179], v175 offset:35840
	ds_read_b128 v[180:183], v175 offset:36864
	ds_read_b128 v[184:187], v175 offset:37888
	ds_read_b128 v[188:191], v175 offset:38912
	ds_read_b128 v[192:195], v175 offset:39936
	global_load_lds_dwordx4 v[196:197], off
	v_lshl_add_u64 v[196:197], s[26:27], 0, v[140:141]
	s_mov_b32 m0, s87
	s_nop 0
	global_load_lds_dwordx4 v[196:197], off
	s_waitcnt lgkmcnt(8)
	s_barrier
; #define PG8_STAGE(bufoff, gbase, voff) do { _Pragma("unroll") for (int _i = 0; _i < 2; ++_i) \
;     __builtin_amdgcn_global_load_lds((const unsigned*)((const char*)(gbase) + (voff)[_i]), (LAS unsigned*)(lds + (bufoff) + ldsw + _i * 8192), 16, 0, 0); } while (0)
; #define PG8_LDA(dst, b, h) do { _Pragma("unroll") for (int m = 0; m < 4; ++m) _Pragma("unroll") for (int k = 0; k < 2; ++k) dst[m][k] = *(const LAS bf16x8*)(lds + PG8_SA(b, h) + aoff + m * 2048 + k * 1024); } while (0)
; #define PG8_LDB(dst, b, h) do { _Pragma("unroll") for (int n = 0; n < 2; ++n) _Pragma("unroll") for (int k = 0; k < 2; ++k) dst[n][k] = *(const LAS bf16x8*)(lds + PG8_SB(b, h) + boff + n * 2048 + k * 1024); } while (0)
; #define PG8_MMA(ai, bj, At, Bt) do { __builtin_amdgcn_s_setprio(1); _Pragma("unroll") for (int m = 0; m < 4; ++m) _Pragma("unroll") for (int n = 0; n < 2; ++n) _Pragma("unroll") for (int k = 0; k < 2; ++k) \
;     acc[ai][bj][m][n] = __builtin_amdgcn_mfma_f32_16x16x32_bf16(Bt[n][k], At[m][k], acc[ai][bj][m][n], 0, 0, 0); __builtin_amdgcn_s_setprio(0); } while (0)
; #define PG8_WAIT_V(n) asm volatile("s_waitcnt vmcnt(" #n ")" ::: "memory")
; #define PG8_WAIT_L(n) asm volatile("s_waitcnt lgkmcnt(" #n ")" ::: "memory")
; #define PG8_BAR __builtin_amdgcn_s_barrier()
; #define PG8_SCHED __builtin_amdgcn_sched_barrier(0)
; template <class Epi>
; __device__ __forceinline__ void gemm_phase(LAS unsigned char* lds, const Gemm g, const Epi& E) {
;     ...
;       PG8_WAIT_L(8); PG8_BAR; PG8_WAIT_L(0); PG8_MMA(0, 0, At, B0); PG8_BAR; PG8_SCHED;
;       PG8_LDB(B1, 1, 1); PG8_STAGE(PG8_SB(1, 0), b3, voffB);
;       PG8_BAR; PG8_WAIT_L(0); PG8_MMA(0, 1, At, B1); PG8_BAR;
;       PG8_LDA(At, 1, 1); PG8_STAGE(PG8_SA(1, 0), a3, voffA);
;       PG8_BAR; PG8_WAIT_L(0); PG8_MMA(1, 0, At, B0); PG8_BAR; PG8_SCHED;
;       PG8_STAGE(PG8_SB(1, 1), b3 + hstepB, voffB);
;       PG8_WAIT_V(6); PG8_BAR; PG8_MMA(1, 1, At, B1); PG8_BAR;
	s_waitcnt lgkmcnt(0)
	s_setprio 1
	s_waitcnt lgkmcnt(0)
	v_mfma_f32_16x16x32_bf16 v[124:127], v[128:131], v[160:163], v[124:127]
	v_mfma_f32_16x16x32_bf16 v[120:123], v[152:155], v[160:163], v[120:123]
	v_mfma_f32_16x16x32_bf16 v[108:111], v[128:131], v[168:171], v[108:111]
	v_mfma_f32_16x16x32_bf16 v[104:107], v[152:155], v[168:171], v[104:107]
	v_mfma_f32_16x16x32_bf16 v[92:95], v[128:131], v[180:183], v[92:95]
	v_mfma_f32_16x16x32_bf16 v[88:91], v[152:155], v[180:183], v[88:91]
	v_mfma_f32_16x16x32_bf16 v[76:79], v[128:131], v[188:191], v[76:79]
	v_mfma_f32_16x16x32_bf16 v[72:75], v[152:155], v[188:191], v[72:75]
	v_mfma_f32_16x16x32_bf16 v[124:127], v[148:151], v[164:167], v[124:127]
	v_mfma_f32_16x16x32_bf16 v[120:123], v[156:159], v[164:167], v[120:123]
	v_mfma_f32_16x16x32_bf16 v[108:111], v[148:151], v[176:179], v[108:111]
	v_mfma_f32_16x16x32_bf16 v[104:107], v[156:159], v[176:179], v[104:107]
	v_mfma_f32_16x16x32_bf16 v[92:95], v[148:151], v[184:187], v[92:95]
	v_mfma_f32_16x16x32_bf16 v[88:91], v[156:159], v[184:187], v[88:91]
	v_mfma_f32_16x16x32_bf16 v[76:79], v[148:151], v[192:195], v[76:79]
	v_mfma_f32_16x16x32_bf16 v[72:75], v[156:159], v[192:195], v[72:75]
	s_setprio 0
	s_barrier
	s_add_i32 s26, 0, 0x1c000
	s_add_i32 s27, s28, s97
	v_add_u32_e32 v208, s26, v173
	v_lshl_add_u64 v[212:213], v[212:213], 0, s[22:23]
	s_mov_b32 m0, s27
	ds_read_b128 v[196:199], v208
	ds_read_b128 v[200:203], v208 offset:1024
	ds_read_b128 v[204:207], v208 offset:2048
	ds_read_b128 v[208:211], v208 offset:3072
	global_load_lds_dwordx4 v[212:213], off
	v_lshl_add_u64 v[212:213], v[214:215], 0, s[22:23]
	s_add_i32 m0, s27, 0x2000
	s_nop 0
	global_load_lds_dwordx4 v[212:213], off
	s_barrier
	s_waitcnt lgkmcnt(0)
	s_setprio 1
	s_waitcnt lgkmcnt(0)
	v_mfma_f32_16x16x32_bf16 v[116:119], v[196:199], v[160:163], v[116:119]
	v_mfma_f32_16x16x32_bf16 v[112:115], v[204:207], v[160:163], v[112:115]
	v_mfma_f32_16x16x32_bf16 v[100:103], v[196:199], v[168:171], v[100:103]
	v_mfma_f32_16x16x32_bf16 v[96:99], v[204:207], v[168:171], v[96:99]
	v_mfma_f32_16x16x32_bf16 v[84:87], v[196:199], v[180:183], v[84:87]
	v_mfma_f32_16x16x32_bf16 v[80:83], v[204:207], v[180:183], v[80:83]
	v_mfma_f32_16x16x32_bf16 v[68:71], v[196:199], v[188:191], v[68:71]
	v_mfma_f32_16x16x32_bf16 v[64:67], v[204:207], v[188:191], v[64:67]
	v_mfma_f32_16x16x32_bf16 v[116:119], v[200:203], v[164:167], v[116:119]
	v_mfma_f32_16x16x32_bf16 v[112:115], v[208:211], v[164:167], v[112:115]
	v_mfma_f32_16x16x32_bf16 v[100:103], v[200:203], v[176:179], v[100:103]
	v_mfma_f32_16x16x32_bf16 v[96:99], v[208:211], v[176:179], v[96:99]
	v_mfma_f32_16x16x32_bf16 v[84:87], v[200:203], v[184:187], v[84:87]
	v_mfma_f32_16x16x32_bf16 v[80:83], v[208:211], v[184:187], v[80:83]
	v_mfma_f32_16x16x32_bf16 v[68:71], v[200:203], v[192:195], v[68:71]
	v_mfma_f32_16x16x32_bf16 v[64:67], v[208:211], v[192:195], v[64:67]
	s_setprio 0
	s_mov_b32 m0, s74
	v_lshl_add_u64 v[212:213], v[216:217], 0, s[22:23]
	s_waitcnt vmcnt(10)
	s_barrier
	ds_read_b128 v[160:163], v175 offset:49152
	ds_read_b128 v[164:167], v175 offset:50176
	ds_read_b128 v[168:171], v175 offset:51200
	ds_read_b128 v[176:179], v175 offset:52224
	ds_read_b128 v[180:183], v175 offset:53248
	ds_read_b128 v[184:187], v175 offset:54272
	ds_read_b128 v[188:191], v175 offset:55296
	ds_read_b128 v[192:195], v175 offset:56320
	global_load_lds_dwordx4 v[212:213], off
	v_lshl_add_u64 v[212:213], v[218:219], 0, s[22:23]
	s_mov_b32 m0, s78
	s_nop 0
	global_load_lds_dwordx4 v[212:213], off
	s_barrier
	s_waitcnt lgkmcnt(0)
	s_setprio 1
	s_waitcnt lgkmcnt(0)
	v_mfma_f32_16x16x32_bf16 v[60:63], v[128:131], v[160:163], v[60:63]
	v_mfma_f32_16x16x32_bf16 v[56:59], v[152:155], v[160:163], v[56:59]
	v_mfma_f32_16x16x32_bf16 v[44:47], v[128:131], v[168:171], v[44:47]
	v_mfma_f32_16x16x32_bf16 v[40:43], v[152:155], v[168:171], v[40:43]
	v_mfma_f32_16x16x32_bf16 v[28:31], v[128:131], v[180:183], v[28:31]
	v_mfma_f32_16x16x32_bf16 v[24:27], v[152:155], v[180:183], v[24:27]
	v_mfma_f32_16x16x32_bf16 v[12:15], v[128:131], v[188:191], v[12:15]
	v_mfma_f32_16x16x32_bf16 v[8:11], v[152:155], v[188:191], v[8:11]
	v_mfma_f32_16x16x32_bf16 v[60:63], v[148:151], v[164:167], v[60:63]
	v_mfma_f32_16x16x32_bf16 v[56:59], v[156:159], v[164:167], v[56:59]
	v_mfma_f32_16x16x32_bf16 v[44:47], v[148:151], v[176:179], v[44:47]
	v_mfma_f32_16x16x32_bf16 v[40:43], v[156:159], v[176:179], v[40:43]
	v_mfma_f32_16x16x32_bf16 v[28:31], v[148:151], v[184:187], v[28:31]
	v_mfma_f32_16x16x32_bf16 v[24:27], v[156:159], v[184:187], v[24:27]
	v_mfma_f32_16x16x32_bf16 v[12:15], v[148:151], v[192:195], v[12:15]
	v_mfma_f32_16x16x32_bf16 v[8:11], v[156:159], v[192:195], v[8:11]
	s_setprio 0
	s_barrier
	s_add_i32 s26, s26, s97
	v_lshl_add_u64 v[128:129], v[220:221], 0, s[22:23]
	s_mov_b32 m0, s26
	s_nop 0
	global_load_lds_dwordx4 v[128:129], off
	v_lshl_add_u64 v[128:129], v[222:223], 0, s[22:23]
	s_add_i32 m0, s26, 0x2000
	s_nop 0
	global_load_lds_dwordx4 v[128:129], off
	s_waitcnt vmcnt(6)
	s_barrier
	s_setprio 1
	v_mfma_f32_16x16x32_bf16 v[52:55], v[196:199], v[160:163], v[52:55]
	v_mfma_f32_16x16x32_bf16 v[48:51], v[204:207], v[160:163], v[48:51]
	v_mfma_f32_16x16x32_bf16 v[36:39], v[196:199], v[168:171], v[36:39]
	v_mfma_f32_16x16x32_bf16 v[32:35], v[204:207], v[168:171], v[32:35]
	v_mfma_f32_16x16x32_bf16 v[20:23], v[196:199], v[180:183], v[20:23]
	v_mfma_f32_16x16x32_bf16 v[16:19], v[204:207], v[180:183], v[16:19]
	v_mfma_f32_16x16x32_bf16 v[4:7], v[196:199], v[188:191], v[4:7]
	v_mfma_f32_16x16x32_bf16 v[0:3], v[204:207], v[188:191], v[0:3]
	v_mfma_f32_16x16x32_bf16 v[52:55], v[200:203], v[164:167], v[52:55]
	v_mfma_f32_16x16x32_bf16 v[48:51], v[208:211], v[164:167], v[48:51]
	v_mfma_f32_16x16x32_bf16 v[36:39], v[200:203], v[176:179], v[36:39]
	v_mfma_f32_16x16x32_bf16 v[32:35], v[208:211], v[176:179], v[32:35]
	v_mfma_f32_16x16x32_bf16 v[20:23], v[200:203], v[184:187], v[20:23]
	v_mfma_f32_16x16x32_bf16 v[16:19], v[208:211], v[184:187], v[16:19]
	v_mfma_f32_16x16x32_bf16 v[4:7], v[200:203], v[192:195], v[4:7]
	v_mfma_f32_16x16x32_bf16 v[0:3], v[208:211], v[192:195], v[0:3]
	s_setprio 0
	s_add_u32 s2, s2, 0x100
	s_addc_u32 s3, s3, 0
	s_add_u32 s38, s38, 0x100
	s_addc_u32 s39, s39, 0
	s_cmp_ge_u32 s76, s72
	s_mov_b32 s26, s76
	s_barrier
	s_cbranch_scc0 .LBB0_579
	s_branch .Lgemm_exit
